# EpiRes init row statistics: first cross-lane exchange per row via v_permlane16_swap instead of ds_bpermute (80 sites)
# speedup vs baseline: 1.0177x; 1.0023x over previous
.LBB0_813:
	s_add_u32 s0, s58, 0x3100000
	s_addc_u32 s1, s59, 0
	v_writelane_b32 v255, s0, 44
	s_nop 1
	v_writelane_b32 v255, s1, 45
	s_add_u32 s0, s58, 0x1f200000
	s_addc_u32 s1, s59, 0
	v_writelane_b32 v255, s0, 46
	s_add_u32 s76, s58, 0x3c00000
	s_addc_u32 s77, s59, 0
	v_writelane_b32 v255, s1, 47
	s_nop 0
	v_readlane_b32 s0, v255, 32
	v_readlane_b32 s1, v255, 33
	s_and_b64 vcc, exec, s[0:1]
	s_cbranch_vccnz .LBB0_853
	v_ashrrev_i32_e32 v2, 31, v0
	v_lshrrev_b32_e32 v2, 26, v2
	v_add_u32_e32 v2, v0, v2
	v_ashrrev_i32_e32 v137, 6, v2
	v_bfe_i32 v2, v0, 27, 1
	v_lshlrev_b32_e32 v1, 4, v0
	v_lshrrev_b32_e32 v2, 22, v2
	v_add_u32_e32 v2, v1, v2
	v_and_b32_e32 v2, 0xfffffc00, v2
	v_sub_u32_e32 v2, v1, v2
	v_lshrrev_b32_e32 v3, 4, v2
	v_bitop3_b32 v2, v3, v2, 32 bitop3:0x6c
	v_ashrrev_i32_e32 v4, 31, v2
	v_lshrrev_b32_e32 v4, 26, v4
	v_lshlrev_b32_e32 v3, 3, v137
	v_add_u32_e32 v4, v2, v4
	v_and_b32_e32 v3, -16, v3
	v_ashrrev_i32_e32 v149, 6, v4
	v_and_b32_e32 v4, 0xc0, v4
	v_add_u32_e32 v3, v149, v3
	v_lshlrev_b32_e32 v5, 5, v137
	v_sub_u32_e32 v2, v2, v4
	v_mov_b32_e32 v4, 1
	v_and_b32_e32 v147, 32, v5
	v_ashrrev_i16_sdwa v2, v4, sext(v2) dst_sel:DWORD dst_unused:UNUSED_PAD src0_sel:DWORD src1_sel:BYTE_0
	v_lshlrev_b32_e32 v5, 1, v3
	v_lshrrev_b32_e32 v6, 2, v3
	v_and_b32_e32 v7, 3, v149
	s_mov_b32 s4, 0xffffe0
	v_bfe_i32 v161, v2, 0, 16
	v_and_b32_e32 v5, 24, v5
	v_and_b32_e32 v6, 4, v6
	v_and_or_b32 v7, v3, s4, v7
	s_movk_i32 s9, 0xb00
	v_add_u32_e32 v2, v147, v161
	v_or3_b32 v5, v7, v6, v5
	v_mul_lo_u32 v3, v3, s9
	v_add_lshl_u32 v128, v2, v3, 1
	v_mul_u32_u24_e32 v3, 0xb00, v5
	v_add_u32_e32 v1, 0x2000, v1
	v_add_lshl_u32 v130, v3, v2, 1
	v_ashrrev_i32_e32 v2, 31, v1
	v_lshrrev_b32_e32 v2, 22, v2
	v_add_u32_e32 v2, v1, v2
	v_ashrrev_i32_e32 v163, 10, v2
	v_mul_i32_i24_e32 v2, 0x400, v163
	v_sub_u32_e32 v1, v1, v2
	v_lshrrev_b32_e32 v2, 4, v1
	v_bitop3_b32 v1, v2, v1, 32 bitop3:0x6c
	v_ashrrev_i32_e32 v3, 31, v1
	v_lshrrev_b32_e32 v3, 26, v3
	v_lshlrev_b32_e32 v2, 3, v163
	v_add_u32_e32 v3, v1, v3
	v_and_b32_e32 v2, -16, v2
	v_ashrrev_i32_e32 v165, 6, v3
	v_and_b32_e32 v3, 0xc0, v3
	v_add_u32_e32 v2, v165, v2
	v_lshlrev_b32_e32 v5, 5, v163
	v_sub_u32_e32 v1, v1, v3
	v_and_b32_e32 v167, 32, v5
	v_ashrrev_i16_sdwa v1, v4, sext(v1) dst_sel:DWORD dst_unused:UNUSED_PAD src0_sel:DWORD src1_sel:BYTE_0
	v_lshlrev_b32_e32 v3, 1, v2
	v_lshrrev_b32_e32 v4, 2, v2
	v_and_b32_e32 v5, 3, v165
	v_bfe_i32 v169, v1, 0, 16
	v_and_b32_e32 v3, 24, v3
	v_and_b32_e32 v4, 4, v4
	v_and_or_b32 v5, v2, s4, v5
	v_add_u32_e32 v1, v167, v169
	v_or3_b32 v3, v5, v4, v3
	v_mul_lo_u32 v2, v2, s9
	v_bfe_u32 v151, v0, 4, 2
	v_add_lshl_u32 v132, v1, v2, 1
	v_mul_u32_u24_e32 v2, 0xb00, v3
	v_and_b32_e32 v153, 15, v0
	v_add_lshl_u32 v134, v2, v1, 1
	v_mov_b32_e32 v1, v151
	v_mov_b32_e32 v0, v153
	s_ashr_i32 s1, s8, 6
	v_lshlrev_b32_e32 v2, 3, v1
	v_mbcnt_lo_u32_b32 v1, -1, 0
	v_mbcnt_hi_u32_b32 v1, -1, v1
	v_and_b32_e32 v5, 64, v1
	v_xor_b32_e32 v4, 16, v1
	v_add_u32_e32 v5, 64, v5
	v_cmp_lt_i32_e32 vcc, v4, v5
	s_ashr_i32 s10, s8, 8
	s_and_b32 s0, s1, 3
	v_cndmask_b32_e32 v4, v1, v4, vcc
	s_lshl_b32 s7, s1, 10
	s_lshl_b32 s13, s10, 6
	s_lshl_b32 s1, s80, 8
	v_lshlrev_b32_e32 v155, 2, v4
	v_xor_b32_e32 v4, 32, v1
	s_add_i32 s1, s1, s13
	v_cmp_lt_i32_e32 vcc, v4, v5
	v_add_u32_e32 v0, s1, v0
	v_ashrrev_i32_e32 v3, 31, v2
	v_cndmask_b32_e32 v1, v1, v4, vcc
	v_lshlrev_b32_e32 v157, 2, v1
	v_ashrrev_i32_e32 v1, 31, v0
	v_lshl_add_u64 v[4:5], v[2:3], 2, s[62:63]
	v_lshlrev_b64 v[6:7], 7, v[0:1]
	v_lshl_add_u64 v[10:11], v[4:5], 0, v[6:7]
	v_mov_b32_e32 v184, v0
	v_ashrrev_i32_e32 v185, 31, v184
	v_lshlrev_b64 v[184:185], 7, v[184:185]
	v_lshl_add_u64 v[184:185], v[4:5], 0, v[184:185]
	global_load_dwordx4 v[188:191], v[184:185], off offset:16
	global_load_dwordx4 v[192:195], v[184:185], off
	v_add_u32_e32 v184, 0x10, v0
	v_ashrrev_i32_e32 v185, 31, v184
	v_lshlrev_b64 v[184:185], 7, v[184:185]
	v_lshl_add_u64 v[184:185], v[4:5], 0, v[184:185]
	global_load_dwordx4 v[196:199], v[184:185], off offset:16
	global_load_dwordx4 v[200:203], v[184:185], off
	v_add_u32_e32 v184, 0x20, v0
	v_ashrrev_i32_e32 v185, 31, v184
	v_lshlrev_b64 v[184:185], 7, v[184:185]
	v_lshl_add_u64 v[184:185], v[4:5], 0, v[184:185]
	global_load_dwordx4 v[204:207], v[184:185], off offset:16
	global_load_dwordx4 v[208:211], v[184:185], off
	v_add_u32_e32 v184, 0x30, v0
	v_ashrrev_i32_e32 v185, 31, v184
	v_lshlrev_b64 v[184:185], 7, v[184:185]
	v_lshl_add_u64 v[184:185], v[4:5], 0, v[184:185]
	global_load_dwordx4 v[212:215], v[184:185], off offset:16
	global_load_dwordx4 v[216:219], v[184:185], off
	v_add_u32_e32 v184, 0x80, v0
	v_ashrrev_i32_e32 v185, 31, v184
	v_lshlrev_b64 v[184:185], 7, v[184:185]
	v_lshl_add_u64 v[184:185], v[4:5], 0, v[184:185]
	global_load_dwordx4 v[220:223], v[184:185], off offset:16
	global_load_dwordx4 v[224:227], v[184:185], off
	v_add_u32_e32 v184, 0x90, v0
	v_ashrrev_i32_e32 v185, 31, v184
	v_lshlrev_b64 v[184:185], 7, v[184:185]
	v_lshl_add_u64 v[184:185], v[4:5], 0, v[184:185]
	global_load_dwordx4 v[228:231], v[184:185], off offset:16
	global_load_dwordx4 v[232:235], v[184:185], off
	v_add_u32_e32 v184, 0xa0, v0
	v_ashrrev_i32_e32 v185, 31, v184
	v_lshlrev_b64 v[184:185], 7, v[184:185]
	v_lshl_add_u64 v[184:185], v[4:5], 0, v[184:185]
	global_load_dwordx4 v[236:239], v[184:185], off offset:16
	global_load_dwordx4 v[240:243], v[184:185], off
	v_add_u32_e32 v184, 0xb0, v0
	v_ashrrev_i32_e32 v185, 31, v184
	v_lshlrev_b64 v[184:185], 7, v[184:185]
	v_lshl_add_u64 v[184:185], v[4:5], 0, v[184:185]
	global_load_dwordx4 v[244:247], v[184:185], off offset:16
	global_load_dwordx4 v[248:251], v[184:185], off
	s_waitcnt vmcnt(0)
	v_mov_b32_e32 v6, v188
	v_mov_b32_e32 v7, v189
	v_mov_b32_e32 v8, v190
	v_mov_b32_e32 v9, v191
	s_nop 0
	v_mov_b32_e32 v10, v192
	v_mov_b32_e32 v11, v193
	v_mov_b32_e32 v12, v194
	v_mov_b32_e32 v13, v195
	v_add_u32_e32 v56, 0x90, v0
	v_ashrrev_i32_e32 v57, 31, v56
	v_add_u32_e32 v58, 0xa0, v0
	v_ashrrev_i32_e32 v59, 31, v58
	v_add_u32_e32 v60, 0xb0, v0
	v_ashrrev_i32_e32 v61, 31, v60
	s_lshl_b32 s66, s0, 5
	s_lshl_b32 s4, s79, 8
	s_or_b32 s4, s4, s66
	v_add_u32_e32 v2, s4, v2
	v_ashrrev_i32_e32 v3, 31, v2
	s_cmp_gt_i32 s80, 63
	v_readlane_b32 s14, v255, 44
	v_readlane_b32 s34, v255, 46
	v_readlane_b32 s15, v255, 45
	v_readlane_b32 s35, v255, 47
	s_cselect_b32 s5, s34, s14
	s_mul_i32 s14, s79, 0x160000
	s_cselect_b32 s4, s35, s15
	s_mul_hi_i32 s12, s79, 0x160000
	s_add_u32 s60, s5, s14
	s_addc_u32 s61, s4, s12
	s_add_i32 s67, s7, 0
	s_add_i32 m0, s67, 0x10000
	s_mul_i32 s11, s80, 0x160000
	s_mul_hi_i32 s6, s80, 0x160000
	v_mov_b32_e32 v136, 0
	v_mov_b32_e32 v131, v136
	v_mov_b32_e32 v135, v136
	v_mov_b32_e32 v129, v136
	v_mov_b32_e32 v133, v136
	s_mov_b32 s1, 0
	v_mov_b32_e32 v15, v6
	v_mov_b32_e32 v14, v10
	v_mov_b32_e32 v16, v12
	v_mov_b32_e32 v17, v8
	v_pk_add_f32 v[14:15], v[14:15], v[16:17]
	v_add_f32_e32 v6, v11, v13
	v_add_f32_e32 v8, v7, v9
	v_mov_b32_e32 v7, v14
	v_mov_b32_e32 v9, v15
	v_pk_add_f32 v[6:7], v[6:7], v[8:9]
	s_nop 0
	v_mov_b32_e32 v8, v6
	v_mov_b32_e32 v9, v7
	s_nop 1
	v_permlane16_swap_b32 v8, v6
	v_permlane16_swap_b32 v9, v7
	s_nop 0
	v_pk_add_f32 v[48:49], v[6:7], v[8:9]
	v_add_u32_e32 v6, 16, v0
	v_ashrrev_i32_e32 v7, 31, v6
	v_lshlrev_b64 v[8:9], 7, v[6:7]
	v_lshl_add_u64 v[12:13], v[4:5], 0, v[8:9]
	v_mov_b32_e32 v8, v196
	v_mov_b32_e32 v9, v197
	v_mov_b32_e32 v10, v198
	v_mov_b32_e32 v11, v199
	s_nop 0
	v_mov_b32_e32 v12, v200
	v_mov_b32_e32 v13, v201
	v_mov_b32_e32 v14, v202
	v_mov_b32_e32 v15, v203
	ds_bpermute_b32 v51, v157, v49
	ds_bpermute_b32 v50, v157, v48
	v_mov_b32_e32 v17, v8
	v_mov_b32_e32 v16, v12
	v_mov_b32_e32 v18, v14
	v_mov_b32_e32 v19, v10
	v_pk_add_f32 v[16:17], v[16:17], v[18:19]
	v_add_f32_e32 v8, v13, v15
	v_add_f32_e32 v10, v9, v11
	v_mov_b32_e32 v9, v16
	v_mov_b32_e32 v11, v17
	v_pk_add_f32 v[8:9], v[8:9], v[10:11]
	s_nop 0
	v_mov_b32_e32 v10, v8
	v_mov_b32_e32 v11, v9
	s_nop 1
	v_permlane16_swap_b32 v10, v8
	v_permlane16_swap_b32 v11, v9
	s_nop 0
	v_pk_add_f32 v[52:53], v[8:9], v[10:11]
	v_add_u32_e32 v8, 32, v0
	v_ashrrev_i32_e32 v9, 31, v8
	v_lshlrev_b64 v[10:11], 7, v[8:9]
	v_lshl_add_u64 v[14:15], v[4:5], 0, v[10:11]
	v_mov_b32_e32 v10, v204
	v_mov_b32_e32 v11, v205
	v_mov_b32_e32 v12, v206
	v_mov_b32_e32 v13, v207
	s_nop 0
	v_mov_b32_e32 v14, v208
	v_mov_b32_e32 v15, v209
	v_mov_b32_e32 v16, v210
	v_mov_b32_e32 v17, v211
	ds_bpermute_b32 v55, v157, v53
	ds_bpermute_b32 v54, v157, v52
	v_mov_b32_e32 v19, v10
	v_mov_b32_e32 v18, v14
	v_mov_b32_e32 v20, v16
	v_mov_b32_e32 v21, v12
	v_pk_add_f32 v[18:19], v[18:19], v[20:21]
	v_add_f32_e32 v10, v15, v17
	v_add_f32_e32 v12, v11, v13
	v_mov_b32_e32 v11, v18
	v_mov_b32_e32 v13, v19
	v_pk_add_f32 v[10:11], v[10:11], v[12:13]
	s_nop 0
	v_mov_b32_e32 v12, v10
	v_mov_b32_e32 v13, v11
	s_nop 1
	v_permlane16_swap_b32 v12, v10
	v_permlane16_swap_b32 v13, v11
	s_nop 0
	v_pk_add_f32 v[64:65], v[10:11], v[12:13]
	v_add_u32_e32 v10, 48, v0
	v_ashrrev_i32_e32 v11, 31, v10
	v_lshlrev_b64 v[12:13], 7, v[10:11]
	v_lshl_add_u64 v[16:17], v[4:5], 0, v[12:13]
	v_mov_b32_e32 v12, v212
	v_mov_b32_e32 v13, v213
	v_mov_b32_e32 v14, v214
	v_mov_b32_e32 v15, v215
	s_nop 0
	v_mov_b32_e32 v16, v216
	v_mov_b32_e32 v17, v217
	v_mov_b32_e32 v18, v218
	v_mov_b32_e32 v19, v219
	ds_bpermute_b32 v67, v157, v65
	ds_bpermute_b32 v66, v157, v64
	v_mov_b32_e32 v21, v12
	v_mov_b32_e32 v20, v16
	v_mov_b32_e32 v22, v18
	v_mov_b32_e32 v23, v14
	v_pk_add_f32 v[20:21], v[20:21], v[22:23]
	v_add_f32_e32 v12, v17, v19
	v_add_f32_e32 v14, v13, v15
	v_mov_b32_e32 v13, v20
	v_mov_b32_e32 v15, v21
	v_pk_add_f32 v[12:13], v[12:13], v[14:15]
	s_nop 0
	v_mov_b32_e32 v14, v12
	v_mov_b32_e32 v15, v13
	s_nop 1
	v_permlane16_swap_b32 v14, v12
	v_permlane16_swap_b32 v15, v13
	s_nop 0
	v_pk_add_f32 v[68:69], v[12:13], v[14:15]
	v_add_u32_e32 v12, 0x80, v0
	v_ashrrev_i32_e32 v13, 31, v12
	v_lshlrev_b64 v[14:15], 7, v[12:13]
	v_lshl_add_u64 v[18:19], v[4:5], 0, v[14:15]
	v_mov_b32_e32 v14, v220
	v_mov_b32_e32 v15, v221
	v_mov_b32_e32 v16, v222
	v_mov_b32_e32 v17, v223
	s_nop 0
	v_mov_b32_e32 v18, v224
	v_mov_b32_e32 v19, v225
	v_mov_b32_e32 v20, v226
	v_mov_b32_e32 v21, v227
	v_lshlrev_b64 v[0:1], 11, v[0:1]
	v_lshl_add_u64 v[0:1], s[44:45], 0, v[0:1]
	ds_bpermute_b32 v71, v157, v69
	ds_bpermute_b32 v70, v157, v68
	v_mov_b32_e32 v23, v14
	v_mov_b32_e32 v22, v18
	v_mov_b32_e32 v24, v20
	v_mov_b32_e32 v25, v16
	v_pk_add_f32 v[22:23], v[22:23], v[24:25]
	v_add_f32_e32 v14, v19, v21
	v_add_f32_e32 v16, v15, v17
	v_mov_b32_e32 v15, v22
	v_mov_b32_e32 v17, v23
	v_pk_add_f32 v[14:15], v[14:15], v[16:17]
	s_nop 0
	v_mov_b32_e32 v16, v14
	v_mov_b32_e32 v17, v15
	s_nop 1
	v_permlane16_swap_b32 v16, v14
	v_permlane16_swap_b32 v17, v15
	s_nop 0
	v_pk_add_f32 v[112:113], v[14:15], v[16:17]
	v_lshlrev_b64 v[14:15], 7, v[56:57]
	v_lshl_add_u64 v[18:19], v[4:5], 0, v[14:15]
	v_mov_b32_e32 v14, v228
	v_mov_b32_e32 v15, v229
	v_mov_b32_e32 v16, v230
	v_mov_b32_e32 v17, v231
	s_nop 0
	v_mov_b32_e32 v18, v232
	v_mov_b32_e32 v19, v233
	v_mov_b32_e32 v20, v234
	v_mov_b32_e32 v21, v235
	ds_bpermute_b32 v115, v157, v113
	ds_bpermute_b32 v114, v157, v112
	v_mov_b32_e32 v23, v14
	v_mov_b32_e32 v22, v18
	v_mov_b32_e32 v24, v20
	v_mov_b32_e32 v25, v16
	v_pk_add_f32 v[22:23], v[22:23], v[24:25]
	v_add_f32_e32 v14, v19, v21
	v_add_f32_e32 v16, v15, v17
	v_mov_b32_e32 v15, v22
	v_mov_b32_e32 v17, v23
	v_pk_add_f32 v[14:15], v[14:15], v[16:17]
	s_nop 0
	v_mov_b32_e32 v16, v14
	v_mov_b32_e32 v17, v15
	s_nop 1
	v_permlane16_swap_b32 v16, v14
	v_permlane16_swap_b32 v17, v15
	s_nop 0
	v_pk_add_f32 v[116:117], v[14:15], v[16:17]
	v_lshlrev_b64 v[14:15], 7, v[58:59]
	v_lshl_add_u64 v[18:19], v[4:5], 0, v[14:15]
	v_mov_b32_e32 v14, v236
	v_mov_b32_e32 v15, v237
	v_mov_b32_e32 v16, v238
	v_mov_b32_e32 v17, v239
	s_nop 0
	v_mov_b32_e32 v18, v240
	v_mov_b32_e32 v19, v241
	v_mov_b32_e32 v20, v242
	v_mov_b32_e32 v21, v243
	ds_bpermute_b32 v119, v157, v117
	ds_bpermute_b32 v118, v157, v116
	v_mov_b32_e32 v23, v14
	v_mov_b32_e32 v22, v18
	v_mov_b32_e32 v24, v20
	v_mov_b32_e32 v25, v16
	v_pk_add_f32 v[22:23], v[22:23], v[24:25]
	v_add_f32_e32 v14, v19, v21
	v_add_f32_e32 v16, v15, v17
	v_mov_b32_e32 v15, v22
	v_mov_b32_e32 v17, v23
	v_pk_add_f32 v[14:15], v[14:15], v[16:17]
	s_nop 0
	v_mov_b32_e32 v16, v14
	v_mov_b32_e32 v17, v15
	s_nop 1
	v_permlane16_swap_b32 v16, v14
	v_permlane16_swap_b32 v17, v15
	s_nop 0
	v_pk_add_f32 v[120:121], v[14:15], v[16:17]
	v_lshlrev_b64 v[14:15], 7, v[60:61]
	v_lshl_add_u64 v[4:5], v[4:5], 0, v[14:15]
	v_mov_b32_e32 v14, v244
	v_mov_b32_e32 v15, v245
	v_mov_b32_e32 v16, v246
	v_mov_b32_e32 v17, v247
	v_mov_b32_e32 v18, v248
	v_mov_b32_e32 v19, v249
	v_mov_b32_e32 v20, v250
	v_mov_b32_e32 v21, v251
	ds_bpermute_b32 v123, v157, v121
	ds_bpermute_b32 v122, v157, v120
	v_mov_b32_e32 v5, v14
	v_mov_b32_e32 v4, v18
	v_mov_b32_e32 v22, v20
	v_mov_b32_e32 v23, v16
	v_pk_add_f32 v[4:5], v[4:5], v[22:23]
	v_add_f32_e32 v14, v19, v21
	v_add_f32_e32 v16, v15, v17
	v_mov_b32_e32 v15, v4
	v_mov_b32_e32 v17, v5
	v_pk_add_f32 v[4:5], v[14:15], v[16:17]
	s_nop 0
	v_mov_b32_e32 v14, v4
	v_mov_b32_e32 v15, v5
	s_nop 1
	v_permlane16_swap_b32 v14, v4
	v_permlane16_swap_b32 v15, v5
	s_nop 0
	v_pk_add_f32 v[124:125], v[4:5], v[14:15]
	v_lshlrev_b64 v[4:5], 2, v[2:3]
	v_lshlrev_b64 v[2:3], 1, v[2:3]
	v_lshl_add_u64 v[74:75], v[0:1], 0, v[2:3]
	v_lshlrev_b64 v[0:1], 11, v[6:7]
	v_lshl_add_u64 v[0:1], s[44:45], 0, v[0:1]
	v_lshl_add_u64 v[76:77], v[0:1], 0, v[2:3]
	v_lshlrev_b64 v[0:1], 11, v[8:9]
	v_lshl_add_u64 v[0:1], s[44:45], 0, v[0:1]
	v_lshl_add_u64 v[78:79], v[0:1], 0, v[2:3]
	v_lshlrev_b64 v[0:1], 11, v[10:11]
	v_lshl_add_u64 v[0:1], s[44:45], 0, v[0:1]
	v_lshl_add_u64 v[80:81], v[0:1], 0, v[2:3]
	v_lshlrev_b64 v[0:1], 11, v[12:13]
	v_lshl_add_u64 v[0:1], s[44:45], 0, v[0:1]
	v_lshl_add_u64 v[138:139], v[0:1], 0, v[2:3]
	v_lshlrev_b64 v[0:1], 11, v[56:57]
	v_lshl_add_u64 v[0:1], s[44:45], 0, v[0:1]
	v_lshl_add_u64 v[56:57], v[0:1], 0, v[2:3]
	v_lshlrev_b64 v[0:1], 11, v[58:59]
	v_lshl_add_u64 v[0:1], s[44:45], 0, v[0:1]
	v_lshl_add_u64 v[58:59], v[0:1], 0, v[2:3]
	v_lshlrev_b64 v[0:1], 11, v[60:61]
	v_lshl_add_u64 v[0:1], s[44:45], 0, v[0:1]
	v_lshl_add_u64 v[62:63], s[18:19], 0, v[4:5]
	v_lshl_add_u64 v[72:73], s[20:21], 0, v[4:5]
	v_lshl_add_u64 v[140:141], v[0:1], 0, v[2:3]
	global_load_dwordx4 v[36:39], v[62:63], off offset:16
	global_load_dwordx4 v[44:47], v[62:63], off
	global_load_dwordx4 v[32:35], v[72:73], off offset:16
	global_load_dwordx4 v[40:43], v[72:73], off
	global_load_dwordx4 v[28:31], v[74:75], off
	global_load_dwordx4 v[24:27], v[76:77], off
	global_load_dwordx4 v[20:23], v[78:79], off
	global_load_dwordx4 v[16:19], v[80:81], off
	global_load_dwordx4 v[12:15], v[138:139], off
	global_load_dwordx4 v[8:11], v[56:57], off
	global_load_dwordx4 v[4:7], v[58:59], off
	global_load_dwordx4 v[0:3], v[140:141], off
	global_load_dwordx4 v[100:103], v[62:63], off offset:528
	global_load_dwordx4 v[108:111], v[62:63], off offset:512
	global_load_dwordx4 v[96:99], v[72:73], off offset:528
	global_load_dwordx4 v[104:107], v[72:73], off offset:512
	global_load_dwordx4 v[92:95], v[74:75], off offset:256
	global_load_dwordx4 v[88:91], v[76:77], off offset:256
	global_load_dwordx4 v[84:87], v[78:79], off offset:256
	s_nop 0
	global_load_dwordx4 v[80:83], v[80:81], off offset:256
	s_nop 0
	global_load_dwordx4 v[76:79], v[138:139], off offset:256
	global_load_dwordx4 v[72:75], v[56:57], off offset:256
	global_load_dwordx4 v[60:63], v[58:59], off offset:256
	s_nop 0
	global_load_dwordx4 v[56:59], v[140:141], off offset:256
	ds_bpermute_b32 v127, v157, v125
	global_load_lds_dwordx4 v130, s[60:61]
	s_add_i32 m0, s67, 0x12000
	s_add_u32 s4, s60, 0xb0000
	global_load_lds_dwordx4 v134, s[60:61]
	s_addc_u32 s5, s61, 0
	s_add_i32 m0, s67, 0x14000
	ds_bpermute_b32 v126, v157, v124
	global_load_lds_dwordx4 v130, s[4:5]
	s_add_i32 m0, s67, 0x16000
	s_add_u32 s40, s42, s11
	s_addc_u32 s41, s43, s6
	s_add_i32 s68, s67, 0x2000
	global_load_lds_dwordx4 v134, s[4:5]
	s_mov_b32 m0, s67
	s_add_u32 s4, s40, 0xb0000
	global_load_lds_dwordx4 v128, s[40:41]
	s_mov_b32 m0, s68
	s_addc_u32 s5, s41, 0
	s_add_i32 s69, s67, 0x4000
	global_load_lds_dwordx4 v132, s[40:41]
	s_mov_b32 m0, s69
	s_add_i32 s82, s67, 0x6000
	global_load_lds_dwordx4 v128, s[4:5]
	s_mov_b32 m0, s82
	s_cmp_eq_u32 s10, 1
	global_load_lds_dwordx4 v132, s[4:5]
	v_lshl_add_u64 v[138:139], s[60:61], 0, v[130:131]
	v_lshl_add_u64 v[140:141], s[60:61], 0, v[134:135]
	v_lshl_add_u64 v[142:143], s[40:41], 0, v[128:129]
	v_lshl_add_u64 v[144:145], s[40:41], 0, v[132:133]
	s_cselect_b64 s[4:5], -1, 0
	s_cmp_lg_u32 s10, 1
	s_cbranch_scc1 .LBB0_816
	s_barrier

.LBB0_849:
	s_or_b64 exec, exec, s[46:47]
	s_and_b64 vcc, exec, s[8:9]
	s_mov_b64 s[8:9], -1
	s_cbranch_vccnz .LBB0_818
	v_mov_b32_e32 v0, v153
	v_mov_b32_e32 v1, v151
	s_lshl_b32 s8, s78, 8
	s_add_i32 s8, s8, s13
	v_add_u32_e32 v0, s8, v0
	s_waitcnt lgkmcnt(0)
	v_lshlrev_b32_e32 v2, 3, v1
	v_ashrrev_i32_e32 v3, 31, v2
	v_ashrrev_i32_e32 v1, 31, v0
	v_lshl_add_u64 v[6:7], v[2:3], 2, s[62:63]
	v_lshlrev_b64 v[4:5], 7, v[0:1]
	v_lshl_add_u64 v[4:5], v[6:7], 0, v[4:5]
	v_mov_b32_e32 v100, v0
	v_ashrrev_i32_e32 v101, 31, v100
	v_lshlrev_b64 v[100:101], 7, v[100:101]
	v_lshl_add_u64 v[100:101], v[6:7], 0, v[100:101]
	global_load_dwordx4 v[104:107], v[100:101], off offset:16
	global_load_dwordx4 v[108:111], v[100:101], off
	v_add_u32_e32 v100, 0x10, v0
	v_ashrrev_i32_e32 v101, 31, v100
	v_lshlrev_b64 v[100:101], 7, v[100:101]
	v_lshl_add_u64 v[100:101], v[6:7], 0, v[100:101]
	global_load_dwordx4 v[124:127], v[100:101], off offset:16
	global_load_dwordx4 v[180:183], v[100:101], off
	v_add_u32_e32 v100, 0x20, v0
	v_ashrrev_i32_e32 v101, 31, v100
	v_lshlrev_b64 v[100:101], 7, v[100:101]
	v_lshl_add_u64 v[100:101], v[6:7], 0, v[100:101]
	global_load_dwordx4 v[184:187], v[100:101], off offset:16
	global_load_dwordx4 v[188:191], v[100:101], off
	v_add_u32_e32 v100, 0x30, v0
	v_ashrrev_i32_e32 v101, 31, v100
	v_lshlrev_b64 v[100:101], 7, v[100:101]
	v_lshl_add_u64 v[100:101], v[6:7], 0, v[100:101]
	global_load_dwordx4 v[192:195], v[100:101], off offset:16
	global_load_dwordx4 v[196:199], v[100:101], off
	v_add_u32_e32 v100, 0x80, v0
	v_ashrrev_i32_e32 v101, 31, v100
	v_lshlrev_b64 v[100:101], 7, v[100:101]
	v_lshl_add_u64 v[100:101], v[6:7], 0, v[100:101]
	global_load_dwordx4 v[200:203], v[100:101], off offset:16
	global_load_dwordx4 v[204:207], v[100:101], off
	v_add_u32_e32 v100, 0x90, v0
	v_ashrrev_i32_e32 v101, 31, v100
	v_lshlrev_b64 v[100:101], 7, v[100:101]
	v_lshl_add_u64 v[100:101], v[6:7], 0, v[100:101]
	global_load_dwordx4 v[208:211], v[100:101], off offset:16
	global_load_dwordx4 v[212:215], v[100:101], off
	v_add_u32_e32 v100, 0xa0, v0
	v_ashrrev_i32_e32 v101, 31, v100
	v_lshlrev_b64 v[100:101], 7, v[100:101]
	v_lshl_add_u64 v[100:101], v[6:7], 0, v[100:101]
	global_load_dwordx4 v[216:219], v[100:101], off offset:16
	global_load_dwordx4 v[220:223], v[100:101], off
	v_add_u32_e32 v100, 0xb0, v0
	v_ashrrev_i32_e32 v101, 31, v100
	v_lshlrev_b64 v[100:101], 7, v[100:101]
	v_lshl_add_u64 v[100:101], v[6:7], 0, v[100:101]
	global_load_dwordx4 v[224:227], v[100:101], off offset:16
	global_load_dwordx4 v[228:231], v[100:101], off
	s_waitcnt vmcnt(0)
	v_mov_b32_e32 v8, v104
	v_mov_b32_e32 v9, v105
	v_mov_b32_e32 v10, v106
	v_mov_b32_e32 v11, v107
	v_mov_b32_e32 v12, v108
	v_mov_b32_e32 v13, v109
	v_mov_b32_e32 v14, v110
	v_mov_b32_e32 v15, v111
	v_add_u32_e32 v56, 0x90, v0
	v_ashrrev_i32_e32 v57, 31, v56
	v_add_u32_e32 v58, 0xa0, v0
	v_ashrrev_i32_e32 v59, 31, v58
	v_add_u32_e32 v60, 0xb0, v0
	v_ashrrev_i32_e32 v61, 31, v60
	s_lshl_b32 s8, s73, 8
	s_or_b32 s8, s8, s66
	v_add_u32_e32 v2, s8, v2
	v_ashrrev_i32_e32 v3, 31, v2
	s_andn2_b64 vcc, exec, s[4:5]
	v_mov_b32_e32 v5, v8
	v_mov_b32_e32 v4, v12
	v_mov_b32_e32 v16, v14
	v_mov_b32_e32 v17, v10
	v_pk_add_f32 v[4:5], v[4:5], v[16:17]
	v_add_f32_e32 v8, v13, v15
	v_add_f32_e32 v10, v9, v11
	v_mov_b32_e32 v9, v4
	v_mov_b32_e32 v11, v5
	v_pk_add_f32 v[4:5], v[8:9], v[10:11]
	s_nop 0
	v_mov_b32_e32 v8, v4
	v_mov_b32_e32 v9, v5
	s_nop 1
	v_permlane16_swap_b32 v8, v4
	v_permlane16_swap_b32 v9, v5
	s_nop 0
	v_pk_add_f32 v[48:49], v[4:5], v[8:9]
	v_add_u32_e32 v4, 16, v0
	v_ashrrev_i32_e32 v5, 31, v4
	v_lshlrev_b64 v[8:9], 7, v[4:5]
	v_lshl_add_u64 v[12:13], v[6:7], 0, v[8:9]
	v_mov_b32_e32 v8, v124
	v_mov_b32_e32 v9, v125
	v_mov_b32_e32 v10, v126
	v_mov_b32_e32 v11, v127
	s_nop 0
	v_mov_b32_e32 v12, v180
	v_mov_b32_e32 v13, v181
	v_mov_b32_e32 v14, v182
	v_mov_b32_e32 v15, v183
	ds_bpermute_b32 v51, v157, v49
	ds_bpermute_b32 v50, v157, v48
	v_mov_b32_e32 v17, v8
	v_mov_b32_e32 v16, v12
	v_mov_b32_e32 v18, v14
	v_mov_b32_e32 v19, v10
	v_pk_add_f32 v[16:17], v[16:17], v[18:19]
	v_add_f32_e32 v8, v13, v15
	v_add_f32_e32 v10, v9, v11
	v_mov_b32_e32 v9, v16
	v_mov_b32_e32 v11, v17
	v_pk_add_f32 v[8:9], v[8:9], v[10:11]
	s_nop 0
	v_mov_b32_e32 v10, v8
	v_mov_b32_e32 v11, v9
	s_nop 1
	v_permlane16_swap_b32 v10, v8
	v_permlane16_swap_b32 v11, v9
	s_nop 0
	v_pk_add_f32 v[52:53], v[8:9], v[10:11]
	v_add_u32_e32 v8, 32, v0
	v_ashrrev_i32_e32 v9, 31, v8
	v_lshlrev_b64 v[10:11], 7, v[8:9]
	v_lshl_add_u64 v[14:15], v[6:7], 0, v[10:11]
	v_mov_b32_e32 v10, v184
	v_mov_b32_e32 v11, v185
	v_mov_b32_e32 v12, v186
	v_mov_b32_e32 v13, v187
	s_nop 0
	v_mov_b32_e32 v14, v188
	v_mov_b32_e32 v15, v189
	v_mov_b32_e32 v16, v190
	v_mov_b32_e32 v17, v191
	ds_bpermute_b32 v55, v157, v53
	ds_bpermute_b32 v54, v157, v52
	v_mov_b32_e32 v19, v10
	v_mov_b32_e32 v18, v14
	v_mov_b32_e32 v20, v16
	v_mov_b32_e32 v21, v12
	v_pk_add_f32 v[18:19], v[18:19], v[20:21]
	v_add_f32_e32 v10, v15, v17
	v_add_f32_e32 v12, v11, v13
	v_mov_b32_e32 v11, v18
	v_mov_b32_e32 v13, v19
	v_pk_add_f32 v[10:11], v[10:11], v[12:13]
	s_nop 0
	v_mov_b32_e32 v12, v10
	v_mov_b32_e32 v13, v11
	s_nop 1
	v_permlane16_swap_b32 v12, v10
	v_permlane16_swap_b32 v13, v11
	s_nop 0
	v_pk_add_f32 v[64:65], v[10:11], v[12:13]
	v_add_u32_e32 v10, 48, v0
	v_ashrrev_i32_e32 v11, 31, v10
	v_lshlrev_b64 v[12:13], 7, v[10:11]
	v_lshl_add_u64 v[16:17], v[6:7], 0, v[12:13]
	v_mov_b32_e32 v12, v192
	v_mov_b32_e32 v13, v193
	v_mov_b32_e32 v14, v194
	v_mov_b32_e32 v15, v195
	s_nop 0
	v_mov_b32_e32 v16, v196
	v_mov_b32_e32 v17, v197
	v_mov_b32_e32 v18, v198
	v_mov_b32_e32 v19, v199
	ds_bpermute_b32 v67, v157, v65
	ds_bpermute_b32 v66, v157, v64
	v_mov_b32_e32 v21, v12
	v_mov_b32_e32 v20, v16
	v_mov_b32_e32 v22, v18
	v_mov_b32_e32 v23, v14
	v_pk_add_f32 v[20:21], v[20:21], v[22:23]
	v_add_f32_e32 v12, v17, v19
	v_add_f32_e32 v14, v13, v15
	v_mov_b32_e32 v13, v20
	v_mov_b32_e32 v15, v21
	v_pk_add_f32 v[12:13], v[12:13], v[14:15]
	s_nop 0
	v_mov_b32_e32 v14, v12
	v_mov_b32_e32 v15, v13
	s_nop 1
	v_permlane16_swap_b32 v14, v12
	v_permlane16_swap_b32 v15, v13
	s_nop 0
	v_pk_add_f32 v[68:69], v[12:13], v[14:15]
	v_add_u32_e32 v12, 0x80, v0
	v_ashrrev_i32_e32 v13, 31, v12
	v_lshlrev_b64 v[14:15], 7, v[12:13]
	v_lshl_add_u64 v[18:19], v[6:7], 0, v[14:15]
	v_mov_b32_e32 v14, v200
	v_mov_b32_e32 v15, v201
	v_mov_b32_e32 v16, v202
	v_mov_b32_e32 v17, v203
	s_nop 0
	v_mov_b32_e32 v18, v204
	v_mov_b32_e32 v19, v205
	v_mov_b32_e32 v20, v206
	v_mov_b32_e32 v21, v207
	v_lshlrev_b64 v[0:1], 11, v[0:1]
	v_lshl_add_u64 v[0:1], s[44:45], 0, v[0:1]
	ds_bpermute_b32 v71, v157, v69
	ds_bpermute_b32 v70, v157, v68
	v_mov_b32_e32 v23, v14
	v_mov_b32_e32 v22, v18
	v_mov_b32_e32 v24, v20
	v_mov_b32_e32 v25, v16
	v_pk_add_f32 v[22:23], v[22:23], v[24:25]
	v_add_f32_e32 v14, v19, v21
	v_add_f32_e32 v16, v15, v17
	v_mov_b32_e32 v15, v22
	v_mov_b32_e32 v17, v23
	v_pk_add_f32 v[14:15], v[14:15], v[16:17]
	s_nop 0
	v_mov_b32_e32 v16, v14
	v_mov_b32_e32 v17, v15
	s_nop 1
	v_permlane16_swap_b32 v16, v14
	v_permlane16_swap_b32 v17, v15
	s_nop 0
	v_pk_add_f32 v[112:113], v[14:15], v[16:17]
	v_lshlrev_b64 v[14:15], 7, v[56:57]
	v_lshl_add_u64 v[18:19], v[6:7], 0, v[14:15]
	v_mov_b32_e32 v14, v208
	v_mov_b32_e32 v15, v209
	v_mov_b32_e32 v16, v210
	v_mov_b32_e32 v17, v211
	s_nop 0
	v_mov_b32_e32 v18, v212
	v_mov_b32_e32 v19, v213
	v_mov_b32_e32 v20, v214
	v_mov_b32_e32 v21, v215
	ds_bpermute_b32 v115, v157, v113
	ds_bpermute_b32 v114, v157, v112
	v_mov_b32_e32 v23, v14
	v_mov_b32_e32 v22, v18
	v_mov_b32_e32 v24, v20
	v_mov_b32_e32 v25, v16
	v_pk_add_f32 v[22:23], v[22:23], v[24:25]
	v_add_f32_e32 v14, v19, v21
	v_add_f32_e32 v16, v15, v17
	v_mov_b32_e32 v15, v22
	v_mov_b32_e32 v17, v23
	v_pk_add_f32 v[14:15], v[14:15], v[16:17]
	s_nop 0
	v_mov_b32_e32 v16, v14
	v_mov_b32_e32 v17, v15
	s_nop 1
	v_permlane16_swap_b32 v16, v14
	v_permlane16_swap_b32 v17, v15
	s_nop 0
	v_pk_add_f32 v[116:117], v[14:15], v[16:17]
	v_lshlrev_b64 v[14:15], 7, v[58:59]
	v_lshl_add_u64 v[18:19], v[6:7], 0, v[14:15]
	v_mov_b32_e32 v14, v216
	v_mov_b32_e32 v15, v217
	v_mov_b32_e32 v16, v218
	v_mov_b32_e32 v17, v219
	s_nop 0
	v_mov_b32_e32 v18, v220
	v_mov_b32_e32 v19, v221
	v_mov_b32_e32 v20, v222
	v_mov_b32_e32 v21, v223
	ds_bpermute_b32 v119, v157, v117
	ds_bpermute_b32 v118, v157, v116
	v_mov_b32_e32 v23, v14
	v_mov_b32_e32 v22, v18
	v_mov_b32_e32 v24, v20
	v_mov_b32_e32 v25, v16
	v_pk_add_f32 v[22:23], v[22:23], v[24:25]
	v_add_f32_e32 v14, v19, v21
	v_add_f32_e32 v16, v15, v17
	v_mov_b32_e32 v15, v22
	v_mov_b32_e32 v17, v23
	v_pk_add_f32 v[14:15], v[14:15], v[16:17]
	s_nop 0
	v_mov_b32_e32 v16, v14
	v_mov_b32_e32 v17, v15
	s_nop 1
	v_permlane16_swap_b32 v16, v14
	v_permlane16_swap_b32 v17, v15
	s_nop 0
	v_pk_add_f32 v[120:121], v[14:15], v[16:17]
	v_lshlrev_b64 v[14:15], 7, v[60:61]
	v_lshl_add_u64 v[6:7], v[6:7], 0, v[14:15]
	v_mov_b32_e32 v14, v224
	v_mov_b32_e32 v15, v225
	v_mov_b32_e32 v16, v226
	v_mov_b32_e32 v17, v227
	v_mov_b32_e32 v18, v228
	v_mov_b32_e32 v19, v229
	v_mov_b32_e32 v20, v230
	v_mov_b32_e32 v21, v231
	ds_bpermute_b32 v123, v157, v121
	ds_bpermute_b32 v122, v157, v120
	v_mov_b32_e32 v7, v14
	v_mov_b32_e32 v6, v18
	v_mov_b32_e32 v22, v20
	v_mov_b32_e32 v23, v16
	v_pk_add_f32 v[6:7], v[6:7], v[22:23]
	v_add_f32_e32 v14, v19, v21
	v_add_f32_e32 v16, v15, v17
	v_mov_b32_e32 v15, v6
	v_mov_b32_e32 v17, v7
	v_pk_add_f32 v[6:7], v[14:15], v[16:17]
	s_nop 0
	v_mov_b32_e32 v14, v6
	v_mov_b32_e32 v15, v7
	s_nop 1
	v_permlane16_swap_b32 v14, v6
	v_permlane16_swap_b32 v15, v7
	s_nop 0
	v_pk_add_f32 v[124:125], v[6:7], v[14:15]
	v_lshlrev_b64 v[6:7], 2, v[2:3]
	v_lshlrev_b64 v[2:3], 1, v[2:3]
	v_lshl_add_u64 v[74:75], v[0:1], 0, v[2:3]
	v_lshlrev_b64 v[0:1], 11, v[4:5]
	v_lshl_add_u64 v[0:1], s[44:45], 0, v[0:1]
	v_lshl_add_u64 v[76:77], v[0:1], 0, v[2:3]
	v_lshlrev_b64 v[0:1], 11, v[8:9]
	v_lshl_add_u64 v[0:1], s[44:45], 0, v[0:1]
	v_lshl_add_u64 v[78:79], v[0:1], 0, v[2:3]
	v_lshlrev_b64 v[0:1], 11, v[10:11]
	v_lshl_add_u64 v[0:1], s[44:45], 0, v[0:1]
	v_lshl_add_u64 v[80:81], v[0:1], 0, v[2:3]
	v_lshlrev_b64 v[0:1], 11, v[12:13]
	v_lshl_add_u64 v[0:1], s[44:45], 0, v[0:1]
	v_lshl_add_u64 v[146:147], v[0:1], 0, v[2:3]
	v_lshlrev_b64 v[0:1], 11, v[56:57]
	v_lshl_add_u64 v[0:1], s[44:45], 0, v[0:1]
	v_lshl_add_u64 v[56:57], v[0:1], 0, v[2:3]
	v_lshlrev_b64 v[0:1], 11, v[58:59]
	v_lshl_add_u64 v[0:1], s[44:45], 0, v[0:1]
	v_lshl_add_u64 v[58:59], v[0:1], 0, v[2:3]
	v_lshlrev_b64 v[0:1], 11, v[60:61]
	v_lshl_add_u64 v[0:1], s[44:45], 0, v[0:1]
	v_lshl_add_u64 v[62:63], s[18:19], 0, v[6:7]
	v_lshl_add_u64 v[72:73], s[20:21], 0, v[6:7]
	v_lshl_add_u64 v[148:149], v[0:1], 0, v[2:3]
	global_load_dwordx4 v[36:39], v[62:63], off offset:16
	global_load_dwordx4 v[44:47], v[62:63], off
	global_load_dwordx4 v[32:35], v[72:73], off offset:16
	global_load_dwordx4 v[40:43], v[72:73], off
	global_load_dwordx4 v[28:31], v[74:75], off
	global_load_dwordx4 v[24:27], v[76:77], off
	global_load_dwordx4 v[20:23], v[78:79], off
	global_load_dwordx4 v[16:19], v[80:81], off
	global_load_dwordx4 v[12:15], v[146:147], off
	global_load_dwordx4 v[8:11], v[56:57], off
	global_load_dwordx4 v[4:7], v[58:59], off
	global_load_dwordx4 v[0:3], v[148:149], off
	global_load_dwordx4 v[104:107], v[62:63], off offset:528
	global_load_dwordx4 v[108:111], v[62:63], off offset:512
	global_load_dwordx4 v[96:99], v[72:73], off offset:528
	global_load_dwordx4 v[100:103], v[72:73], off offset:512
	global_load_dwordx4 v[92:95], v[74:75], off offset:256
	global_load_dwordx4 v[88:91], v[76:77], off offset:256
	global_load_dwordx4 v[84:87], v[78:79], off offset:256
	s_nop 0
	global_load_dwordx4 v[80:83], v[80:81], off offset:256
	s_nop 0
	global_load_dwordx4 v[76:79], v[146:147], off offset:256
	global_load_dwordx4 v[72:75], v[56:57], off offset:256
	global_load_dwordx4 v[60:63], v[58:59], off offset:256
	s_nop 0
	global_load_dwordx4 v[56:59], v[148:149], off offset:256
	ds_bpermute_b32 v127, v157, v125
	ds_bpermute_b32 v126, v157, v124
	s_cbranch_vccnz .LBB0_817
	s_barrier
	s_branch .LBB0_817

.LBB0_1500:
	v_readlane_b32 s0, v255, 32
	v_readlane_b32 s1, v255, 33
	s_and_b64 vcc, exec, s[0:1]
	s_cbranch_vccnz .LBB0_1536
	v_ashrrev_i32_e32 v2, 31, v0
	v_lshrrev_b32_e32 v2, 26, v2
	v_add_u32_e32 v2, v0, v2
	v_ashrrev_i32_e32 v137, 6, v2
	v_bfe_i32 v2, v0, 27, 1
	v_lshlrev_b32_e32 v1, 4, v0
	v_lshrrev_b32_e32 v2, 22, v2
	v_add_u32_e32 v2, v1, v2
	v_and_b32_e32 v2, 0xfffffc00, v2
	v_sub_u32_e32 v2, v1, v2
	v_lshrrev_b32_e32 v3, 4, v2
	v_bitop3_b32 v2, v3, v2, 32 bitop3:0x6c
	v_ashrrev_i32_e32 v4, 31, v2
	v_lshrrev_b32_e32 v4, 26, v4
	v_add_u32_e32 v4, v2, v4
	v_lshlrev_b32_e32 v3, 3, v137
	v_ashrrev_i32_e32 v147, 6, v4
	v_and_b32_e32 v4, 0xc0, v4
	v_and_b32_e32 v3, -16, v3
	v_sub_u32_e32 v2, v2, v4
	v_mov_b32_e32 v4, 1
	v_add_u32_e32 v3, v147, v3
	v_ashrrev_i16_sdwa v2, v4, sext(v2) dst_sel:DWORD dst_unused:UNUSED_PAD src0_sel:DWORD src1_sel:BYTE_0
	v_lshlrev_b32_e32 v5, 5, v137
	v_bfe_i32 v149, v2, 0, 16
	v_lshlrev_b32_e32 v2, 1, v3
	v_lshrrev_b32_e32 v6, 2, v3
	v_and_b32_e32 v7, 3, v147
	s_mov_b32 s4, 0x1fffe0
	v_and_b32_e32 v5, 32, v5
	v_and_b32_e32 v2, 24, v2
	v_and_b32_e32 v6, 4, v6
	v_and_or_b32 v7, v3, s4, v7
	v_or3_b32 v2, v7, v6, v2
	v_add_lshl_u32 v5, v5, v149, 1
	v_add_u32_e32 v1, 0x2000, v1
	v_lshl_add_u32 v130, v2, 11, v5
	v_ashrrev_i32_e32 v2, 31, v1
	v_lshrrev_b32_e32 v2, 22, v2
	v_add_u32_e32 v2, v1, v2
	v_ashrrev_i32_e32 v161, 10, v2
	v_mul_i32_i24_e32 v2, 0x400, v161
	v_sub_u32_e32 v1, v1, v2
	v_lshrrev_b32_e32 v2, 4, v1
	v_bitop3_b32 v1, v2, v1, 32 bitop3:0x6c
	v_lshl_add_u32 v128, v3, 11, v5
	v_ashrrev_i32_e32 v3, 31, v1
	v_lshrrev_b32_e32 v3, 26, v3
	v_add_u32_e32 v3, v1, v3
	v_lshlrev_b32_e32 v2, 3, v161
	v_ashrrev_i32_e32 v163, 6, v3
	v_and_b32_e32 v3, 0xc0, v3
	v_and_b32_e32 v2, -16, v2
	v_sub_u32_e32 v1, v1, v3
	v_add_u32_e32 v2, v163, v2
	v_ashrrev_i16_sdwa v1, v4, sext(v1) dst_sel:DWORD dst_unused:UNUSED_PAD src0_sel:DWORD src1_sel:BYTE_0
	v_lshlrev_b32_e32 v5, 5, v161
	v_bfe_i32 v165, v1, 0, 16
	v_lshlrev_b32_e32 v1, 1, v2
	v_lshrrev_b32_e32 v3, 2, v2
	v_and_b32_e32 v4, 3, v163
	v_and_b32_e32 v5, 32, v5
	v_and_b32_e32 v1, 24, v1
	v_and_b32_e32 v3, 4, v3
	v_and_or_b32 v4, v2, s4, v4
	v_bfe_u32 v151, v0, 4, 2
	v_or3_b32 v1, v4, v3, v1
	v_add_lshl_u32 v3, v5, v165, 1
	v_and_b32_e32 v153, 15, v0
	v_lshl_add_u32 v134, v1, 11, v3
	v_mov_b32_e32 v0, v153
	v_mov_b32_e32 v1, v151
	v_lshl_add_u32 v132, v2, 11, v3
	v_lshlrev_b32_e32 v2, 3, v1
	v_mbcnt_lo_u32_b32 v1, -1, 0
	v_mbcnt_hi_u32_b32 v1, -1, v1
	v_and_b32_e32 v5, 64, v1
	v_xor_b32_e32 v4, 16, v1
	v_add_u32_e32 v5, 64, v5
	v_cmp_lt_i32_e32 vcc, v4, v5
	s_ashr_i32 s1, s8, 6
	s_ashr_i32 s9, s8, 8
	v_cndmask_b32_e32 v4, v1, v4, vcc
	s_and_b32 s0, s1, 3
	s_lshl_b32 s7, s1, 10
	s_lshl_b32 s11, s9, 6
	s_lshl_b32 s1, s92, 8
	v_lshlrev_b32_e32 v155, 2, v4
	v_xor_b32_e32 v4, 32, v1
	s_add_i32 s1, s1, s11
	v_cmp_lt_i32_e32 vcc, v4, v5
	v_add_u32_e32 v0, s1, v0
	v_ashrrev_i32_e32 v3, 31, v2
	v_cndmask_b32_e32 v1, v1, v4, vcc
	v_lshlrev_b32_e32 v157, 2, v1
	v_ashrrev_i32_e32 v1, 31, v0
	v_lshl_add_u64 v[4:5], v[2:3], 2, s[76:77]
	v_lshlrev_b64 v[6:7], 7, v[0:1]
	v_lshl_add_u64 v[10:11], v[4:5], 0, v[6:7]
	v_mov_b32_e32 v184, v0
	v_ashrrev_i32_e32 v185, 31, v184
	v_lshlrev_b64 v[184:185], 7, v[184:185]
	v_lshl_add_u64 v[184:185], v[4:5], 0, v[184:185]
	global_load_dwordx4 v[188:191], v[184:185], off offset:16
	global_load_dwordx4 v[192:195], v[184:185], off
	v_add_u32_e32 v184, 0x10, v0
	v_ashrrev_i32_e32 v185, 31, v184
	v_lshlrev_b64 v[184:185], 7, v[184:185]
	v_lshl_add_u64 v[184:185], v[4:5], 0, v[184:185]
	global_load_dwordx4 v[196:199], v[184:185], off offset:16
	global_load_dwordx4 v[200:203], v[184:185], off
	v_add_u32_e32 v184, 0x20, v0
	v_ashrrev_i32_e32 v185, 31, v184
	v_lshlrev_b64 v[184:185], 7, v[184:185]
	v_lshl_add_u64 v[184:185], v[4:5], 0, v[184:185]
	global_load_dwordx4 v[204:207], v[184:185], off offset:16
	global_load_dwordx4 v[208:211], v[184:185], off
	v_add_u32_e32 v184, 0x30, v0
	v_ashrrev_i32_e32 v185, 31, v184
	v_lshlrev_b64 v[184:185], 7, v[184:185]
	v_lshl_add_u64 v[184:185], v[4:5], 0, v[184:185]
	global_load_dwordx4 v[212:215], v[184:185], off offset:16
	global_load_dwordx4 v[216:219], v[184:185], off
	v_add_u32_e32 v184, 0x80, v0
	v_ashrrev_i32_e32 v185, 31, v184
	v_lshlrev_b64 v[184:185], 7, v[184:185]
	v_lshl_add_u64 v[184:185], v[4:5], 0, v[184:185]
	global_load_dwordx4 v[220:223], v[184:185], off offset:16
	global_load_dwordx4 v[224:227], v[184:185], off
	v_add_u32_e32 v184, 0x90, v0
	v_ashrrev_i32_e32 v185, 31, v184
	v_lshlrev_b64 v[184:185], 7, v[184:185]
	v_lshl_add_u64 v[184:185], v[4:5], 0, v[184:185]
	global_load_dwordx4 v[228:231], v[184:185], off offset:16
	global_load_dwordx4 v[232:235], v[184:185], off
	v_add_u32_e32 v184, 0xa0, v0
	v_ashrrev_i32_e32 v185, 31, v184
	v_lshlrev_b64 v[184:185], 7, v[184:185]
	v_lshl_add_u64 v[184:185], v[4:5], 0, v[184:185]
	global_load_dwordx4 v[236:239], v[184:185], off offset:16
	global_load_dwordx4 v[240:243], v[184:185], off
	v_add_u32_e32 v184, 0xb0, v0
	v_ashrrev_i32_e32 v185, 31, v184
	v_lshlrev_b64 v[184:185], 7, v[184:185]
	v_lshl_add_u64 v[184:185], v[4:5], 0, v[184:185]
	global_load_dwordx4 v[244:247], v[184:185], off offset:16
	global_load_dwordx4 v[248:251], v[184:185], off
	s_waitcnt vmcnt(0)
	v_mov_b32_e32 v6, v188
	v_mov_b32_e32 v7, v189
	v_mov_b32_e32 v8, v190
	v_mov_b32_e32 v9, v191
	s_nop 0
	v_mov_b32_e32 v10, v192
	v_mov_b32_e32 v11, v193
	v_mov_b32_e32 v12, v194
	v_mov_b32_e32 v13, v195
	s_waitcnt vmcnt(3)
	v_add_u32_e32 v56, 0x90, v0
	v_ashrrev_i32_e32 v57, 31, v56
	v_add_u32_e32 v58, 0xa0, v0
	v_ashrrev_i32_e32 v59, 31, v58
	s_waitcnt vmcnt(2)
	v_add_u32_e32 v60, 0xb0, v0
	v_ashrrev_i32_e32 v61, 31, v60
	s_lshl_b32 s66, s0, 5
	s_lshl_b32 s4, s88, 8
	s_or_b32 s4, s4, s66
	v_add_u32_e32 v2, s4, v2
	v_ashrrev_i32_e32 v3, 31, v2
	s_ashr_i32 s93, s92, 31
	s_lshl_b64 s[4:5], s[92:93], 19
	v_readlane_b32 s12, v255, 34
	v_readlane_b32 s14, v255, 36
	s_cmp_gt_i32 s92, 63
	v_readlane_b32 s13, v255, 35
	v_readlane_b32 s15, v255, 37
	s_cselect_b32 s6, s15, s13
	s_cselect_b32 s10, s14, s12
	s_ashr_i32 s89, s88, 31
	s_lshl_b64 s[12:13], s[88:89], 19
	s_add_u32 s40, s10, s12
	s_addc_u32 s41, s6, s13
	s_add_i32 s67, s7, 0
	s_add_i32 m0, s67, 0x10000
	v_mov_b32_e32 v136, 0
	v_mov_b32_e32 v131, v136
	v_mov_b32_e32 v135, v136
	v_mov_b32_e32 v129, v136
	v_mov_b32_e32 v133, v136
	s_mov_b32 s1, 0
	v_mov_b32_e32 v15, v6
	v_mov_b32_e32 v14, v10
	v_mov_b32_e32 v16, v12
	v_mov_b32_e32 v17, v8
	v_pk_add_f32 v[14:15], v[14:15], v[16:17]
	v_add_f32_e32 v6, v11, v13
	v_add_f32_e32 v8, v7, v9
	v_mov_b32_e32 v7, v14
	v_mov_b32_e32 v9, v15
	v_pk_add_f32 v[6:7], v[6:7], v[8:9]
	s_nop 0
	v_mov_b32_e32 v8, v6
	v_mov_b32_e32 v9, v7
	s_nop 1
	v_permlane16_swap_b32 v8, v6
	v_permlane16_swap_b32 v9, v7
	s_nop 0
	v_pk_add_f32 v[48:49], v[6:7], v[8:9]
	v_add_u32_e32 v6, 16, v0
	v_ashrrev_i32_e32 v7, 31, v6
	v_lshlrev_b64 v[8:9], 7, v[6:7]
	v_lshl_add_u64 v[12:13], v[4:5], 0, v[8:9]
	v_mov_b32_e32 v8, v196
	v_mov_b32_e32 v9, v197
	v_mov_b32_e32 v10, v198
	v_mov_b32_e32 v11, v199
	s_nop 0
	v_mov_b32_e32 v12, v200
	v_mov_b32_e32 v13, v201
	v_mov_b32_e32 v14, v202
	v_mov_b32_e32 v15, v203
	ds_bpermute_b32 v51, v157, v49
	ds_bpermute_b32 v50, v157, v48
	v_mov_b32_e32 v17, v8
	v_mov_b32_e32 v16, v12
	v_mov_b32_e32 v18, v14
	v_mov_b32_e32 v19, v10
	v_pk_add_f32 v[16:17], v[16:17], v[18:19]
	v_add_f32_e32 v8, v13, v15
	v_add_f32_e32 v10, v9, v11
	v_mov_b32_e32 v9, v16
	v_mov_b32_e32 v11, v17
	v_pk_add_f32 v[8:9], v[8:9], v[10:11]
	s_nop 0
	v_mov_b32_e32 v10, v8
	v_mov_b32_e32 v11, v9
	s_nop 1
	v_permlane16_swap_b32 v10, v8
	v_permlane16_swap_b32 v11, v9
	s_nop 0
	v_pk_add_f32 v[52:53], v[8:9], v[10:11]
	v_add_u32_e32 v8, 32, v0
	v_ashrrev_i32_e32 v9, 31, v8
	v_lshlrev_b64 v[10:11], 7, v[8:9]
	v_lshl_add_u64 v[14:15], v[4:5], 0, v[10:11]
	v_mov_b32_e32 v10, v204
	v_mov_b32_e32 v11, v205
	v_mov_b32_e32 v12, v206
	v_mov_b32_e32 v13, v207
	s_nop 0
	v_mov_b32_e32 v14, v208
	v_mov_b32_e32 v15, v209
	v_mov_b32_e32 v16, v210
	v_mov_b32_e32 v17, v211
	ds_bpermute_b32 v55, v157, v53
	ds_bpermute_b32 v54, v157, v52
	v_mov_b32_e32 v19, v10
	v_mov_b32_e32 v18, v14
	v_mov_b32_e32 v20, v16
	v_mov_b32_e32 v21, v12
	v_pk_add_f32 v[18:19], v[18:19], v[20:21]
	v_add_f32_e32 v10, v15, v17
	v_add_f32_e32 v12, v11, v13
	v_mov_b32_e32 v11, v18
	v_mov_b32_e32 v13, v19
	v_pk_add_f32 v[10:11], v[10:11], v[12:13]
	s_nop 0
	v_mov_b32_e32 v12, v10
	v_mov_b32_e32 v13, v11
	s_nop 1
	v_permlane16_swap_b32 v12, v10
	v_permlane16_swap_b32 v13, v11
	s_nop 0
	v_pk_add_f32 v[64:65], v[10:11], v[12:13]
	v_add_u32_e32 v10, 48, v0
	v_ashrrev_i32_e32 v11, 31, v10
	v_lshlrev_b64 v[12:13], 7, v[10:11]
	v_lshl_add_u64 v[16:17], v[4:5], 0, v[12:13]
	v_mov_b32_e32 v12, v212
	v_mov_b32_e32 v13, v213
	v_mov_b32_e32 v14, v214
	v_mov_b32_e32 v15, v215
	s_nop 0
	v_mov_b32_e32 v16, v216
	v_mov_b32_e32 v17, v217
	v_mov_b32_e32 v18, v218
	v_mov_b32_e32 v19, v219
	ds_bpermute_b32 v67, v157, v65
	ds_bpermute_b32 v66, v157, v64
	v_mov_b32_e32 v21, v12
	v_mov_b32_e32 v20, v16
	v_mov_b32_e32 v22, v18
	v_mov_b32_e32 v23, v14
	v_pk_add_f32 v[20:21], v[20:21], v[22:23]
	v_add_f32_e32 v12, v17, v19
	v_add_f32_e32 v14, v13, v15
	v_mov_b32_e32 v13, v20
	v_mov_b32_e32 v15, v21
	v_pk_add_f32 v[12:13], v[12:13], v[14:15]
	s_nop 0
	v_mov_b32_e32 v14, v12
	v_mov_b32_e32 v15, v13
	s_nop 1
	v_permlane16_swap_b32 v14, v12
	v_permlane16_swap_b32 v15, v13
	s_nop 0
	v_pk_add_f32 v[68:69], v[12:13], v[14:15]
	v_add_u32_e32 v12, 0x80, v0
	v_ashrrev_i32_e32 v13, 31, v12
	v_lshlrev_b64 v[14:15], 7, v[12:13]
	v_lshl_add_u64 v[18:19], v[4:5], 0, v[14:15]
	v_mov_b32_e32 v14, v220
	v_mov_b32_e32 v15, v221
	v_mov_b32_e32 v16, v222
	v_mov_b32_e32 v17, v223
	s_nop 0
	v_mov_b32_e32 v18, v224
	v_mov_b32_e32 v19, v225
	v_mov_b32_e32 v20, v226
	v_mov_b32_e32 v21, v227
	v_lshlrev_b64 v[0:1], 11, v[0:1]
	v_lshl_add_u64 v[0:1], s[44:45], 0, v[0:1]
	ds_bpermute_b32 v71, v157, v69
	ds_bpermute_b32 v70, v157, v68
	v_mov_b32_e32 v23, v14
	v_mov_b32_e32 v22, v18
	v_mov_b32_e32 v24, v20
	v_mov_b32_e32 v25, v16
	v_pk_add_f32 v[22:23], v[22:23], v[24:25]
	v_add_f32_e32 v14, v19, v21
	v_add_f32_e32 v16, v15, v17
	v_mov_b32_e32 v15, v22
	v_mov_b32_e32 v17, v23
	v_pk_add_f32 v[14:15], v[14:15], v[16:17]
	s_nop 0
	v_mov_b32_e32 v16, v14
	v_mov_b32_e32 v17, v15
	s_nop 1
	v_permlane16_swap_b32 v16, v14
	v_permlane16_swap_b32 v17, v15
	s_nop 0
	v_pk_add_f32 v[112:113], v[14:15], v[16:17]
	v_lshlrev_b64 v[14:15], 7, v[56:57]
	v_lshl_add_u64 v[18:19], v[4:5], 0, v[14:15]
	v_mov_b32_e32 v14, v228
	v_mov_b32_e32 v15, v229
	v_mov_b32_e32 v16, v230
	v_mov_b32_e32 v17, v231
	s_nop 0
	v_mov_b32_e32 v18, v232
	v_mov_b32_e32 v19, v233
	v_mov_b32_e32 v20, v234
	v_mov_b32_e32 v21, v235
	ds_bpermute_b32 v115, v157, v113
	ds_bpermute_b32 v114, v157, v112
	v_mov_b32_e32 v23, v14
	v_mov_b32_e32 v22, v18
	v_mov_b32_e32 v24, v20
	v_mov_b32_e32 v25, v16
	v_pk_add_f32 v[22:23], v[22:23], v[24:25]
	v_add_f32_e32 v14, v19, v21
	v_add_f32_e32 v16, v15, v17
	v_mov_b32_e32 v15, v22
	v_mov_b32_e32 v17, v23
	v_pk_add_f32 v[14:15], v[14:15], v[16:17]
	s_nop 0
	v_mov_b32_e32 v16, v14
	v_mov_b32_e32 v17, v15
	s_nop 1
	v_permlane16_swap_b32 v16, v14
	v_permlane16_swap_b32 v17, v15
	s_nop 0
	v_pk_add_f32 v[116:117], v[14:15], v[16:17]
	v_lshlrev_b64 v[14:15], 7, v[58:59]
	v_lshl_add_u64 v[18:19], v[4:5], 0, v[14:15]
	v_mov_b32_e32 v14, v236
	v_mov_b32_e32 v15, v237
	v_mov_b32_e32 v16, v238
	v_mov_b32_e32 v17, v239
	s_nop 0
	v_mov_b32_e32 v18, v240
	v_mov_b32_e32 v19, v241
	v_mov_b32_e32 v20, v242
	v_mov_b32_e32 v21, v243
	ds_bpermute_b32 v119, v157, v117
	ds_bpermute_b32 v118, v157, v116
	v_mov_b32_e32 v23, v14
	v_mov_b32_e32 v22, v18
	v_mov_b32_e32 v24, v20
	v_mov_b32_e32 v25, v16
	v_pk_add_f32 v[22:23], v[22:23], v[24:25]
	v_add_f32_e32 v14, v19, v21
	v_add_f32_e32 v16, v15, v17
	v_mov_b32_e32 v15, v22
	v_mov_b32_e32 v17, v23
	v_pk_add_f32 v[14:15], v[14:15], v[16:17]
	s_nop 0
	v_mov_b32_e32 v16, v14
	v_mov_b32_e32 v17, v15
	s_nop 1
	v_permlane16_swap_b32 v16, v14
	v_permlane16_swap_b32 v17, v15
	s_nop 0
	v_pk_add_f32 v[120:121], v[14:15], v[16:17]
	v_lshlrev_b64 v[14:15], 7, v[60:61]
	v_lshl_add_u64 v[4:5], v[4:5], 0, v[14:15]
	v_mov_b32_e32 v14, v244
	v_mov_b32_e32 v15, v245
	v_mov_b32_e32 v16, v246
	v_mov_b32_e32 v17, v247
	v_mov_b32_e32 v18, v248
	v_mov_b32_e32 v19, v249
	v_mov_b32_e32 v20, v250
	v_mov_b32_e32 v21, v251
	ds_bpermute_b32 v123, v157, v121
	ds_bpermute_b32 v122, v157, v120
	v_mov_b32_e32 v5, v14
	v_mov_b32_e32 v4, v18
	v_mov_b32_e32 v22, v20
	v_mov_b32_e32 v23, v16
	v_pk_add_f32 v[4:5], v[4:5], v[22:23]
	v_add_f32_e32 v14, v19, v21
	v_add_f32_e32 v16, v15, v17
	v_mov_b32_e32 v15, v4
	v_mov_b32_e32 v17, v5
	v_pk_add_f32 v[4:5], v[14:15], v[16:17]
	s_nop 0
	v_mov_b32_e32 v14, v4
	v_mov_b32_e32 v15, v5
	s_nop 1
	v_permlane16_swap_b32 v14, v4
	v_permlane16_swap_b32 v15, v5
	s_nop 0
	v_pk_add_f32 v[124:125], v[4:5], v[14:15]
	v_lshlrev_b64 v[4:5], 2, v[2:3]
	v_lshlrev_b64 v[2:3], 1, v[2:3]
	v_lshl_add_u64 v[74:75], v[0:1], 0, v[2:3]
	v_lshlrev_b64 v[0:1], 11, v[6:7]
	v_lshl_add_u64 v[0:1], s[44:45], 0, v[0:1]
	v_lshl_add_u64 v[76:77], v[0:1], 0, v[2:3]
	v_lshlrev_b64 v[0:1], 11, v[8:9]
	v_lshl_add_u64 v[0:1], s[44:45], 0, v[0:1]
	v_lshl_add_u64 v[78:79], v[0:1], 0, v[2:3]
	v_lshlrev_b64 v[0:1], 11, v[10:11]
	v_lshl_add_u64 v[0:1], s[44:45], 0, v[0:1]
	v_lshl_add_u64 v[80:81], v[0:1], 0, v[2:3]
	v_lshlrev_b64 v[0:1], 11, v[12:13]
	v_lshl_add_u64 v[0:1], s[44:45], 0, v[0:1]
	v_lshl_add_u64 v[138:139], v[0:1], 0, v[2:3]
	v_lshlrev_b64 v[0:1], 11, v[56:57]
	v_lshl_add_u64 v[0:1], s[44:45], 0, v[0:1]
	v_lshl_add_u64 v[56:57], v[0:1], 0, v[2:3]
	v_lshlrev_b64 v[0:1], 11, v[58:59]
	v_lshl_add_u64 v[0:1], s[44:45], 0, v[0:1]
	v_lshl_add_u64 v[58:59], v[0:1], 0, v[2:3]
	v_lshlrev_b64 v[0:1], 11, v[60:61]
	v_lshl_add_u64 v[0:1], s[44:45], 0, v[0:1]
	v_lshl_add_u64 v[62:63], s[28:29], 0, v[4:5]
	v_lshl_add_u64 v[72:73], s[30:31], 0, v[4:5]
	v_lshl_add_u64 v[140:141], v[0:1], 0, v[2:3]
	global_load_dwordx4 v[36:39], v[62:63], off offset:16
	global_load_dwordx4 v[44:47], v[62:63], off
	global_load_dwordx4 v[32:35], v[72:73], off offset:16
	global_load_dwordx4 v[40:43], v[72:73], off
	global_load_dwordx4 v[28:31], v[74:75], off
	global_load_dwordx4 v[24:27], v[76:77], off
	global_load_dwordx4 v[20:23], v[78:79], off
	global_load_dwordx4 v[16:19], v[80:81], off
	global_load_dwordx4 v[12:15], v[138:139], off
	global_load_dwordx4 v[8:11], v[56:57], off
	global_load_dwordx4 v[4:7], v[58:59], off
	global_load_dwordx4 v[0:3], v[140:141], off
	global_load_dwordx4 v[100:103], v[62:63], off offset:528
	global_load_dwordx4 v[108:111], v[62:63], off offset:512
	global_load_dwordx4 v[96:99], v[72:73], off offset:528
	global_load_dwordx4 v[104:107], v[72:73], off offset:512
	global_load_dwordx4 v[92:95], v[74:75], off offset:256
	global_load_dwordx4 v[88:91], v[76:77], off offset:256
	global_load_dwordx4 v[84:87], v[78:79], off offset:256
	s_nop 0
	global_load_dwordx4 v[80:83], v[80:81], off offset:256
	s_nop 0
	global_load_dwordx4 v[76:79], v[138:139], off offset:256
	global_load_dwordx4 v[72:75], v[56:57], off offset:256
	global_load_dwordx4 v[60:63], v[58:59], off offset:256
	s_nop 0
	global_load_dwordx4 v[56:59], v[140:141], off offset:256
	ds_bpermute_b32 v127, v157, v125
	global_load_lds_dwordx4 v130, s[40:41]
	s_add_i32 m0, s67, 0x12000
	s_add_u32 s12, s40, 0x40000
	global_load_lds_dwordx4 v134, s[40:41]
	s_addc_u32 s13, s41, 0
	s_add_i32 m0, s67, 0x14000
	ds_bpermute_b32 v126, v157, v124
	global_load_lds_dwordx4 v130, s[12:13]
	s_add_i32 m0, s67, 0x16000
	s_add_u32 s74, s42, s4
	s_addc_u32 s75, s43, s5
	s_add_i32 s68, s67, 0x2000
	global_load_lds_dwordx4 v134, s[12:13]
	s_mov_b32 m0, s67
	s_add_u32 s4, s74, 0x40000
	global_load_lds_dwordx4 v128, s[74:75]
	s_mov_b32 m0, s68
	s_addc_u32 s5, s75, 0
	s_add_i32 s69, s67, 0x4000
	global_load_lds_dwordx4 v132, s[74:75]
	s_mov_b32 m0, s69
	s_add_i32 s89, s67, 0x6000
	global_load_lds_dwordx4 v128, s[4:5]
	s_mov_b32 m0, s89
	s_cmp_eq_u32 s9, 1
	global_load_lds_dwordx4 v132, s[4:5]
	v_lshl_add_u64 v[138:139], s[40:41], 0, v[130:131]
	v_lshl_add_u64 v[140:141], s[40:41], 0, v[134:135]
	v_lshl_add_u64 v[142:143], s[74:75], 0, v[128:129]
	v_lshl_add_u64 v[144:145], s[74:75], 0, v[132:133]
	s_cselect_b64 s[4:5], -1, 0
	s_cmp_lg_u32 s9, 1
	s_cbranch_scc1 .LBB0_1503
	s_barrier

.LBB0_1532:
	s_or_b64 exec, exec, s[46:47]
	s_andn2_b64 vcc, exec, s[8:9]
	s_mov_b64 s[8:9], -1
	s_cbranch_vccnz .LBB0_1505
	v_mov_b32_e32 v1, v151
	v_mov_b32_e32 v0, v153
	s_lshl_b32 s8, s36, 8
	s_add_i32 s8, s8, s11
	v_add_u32_e32 v0, s8, v0
	s_waitcnt lgkmcnt(0)
	v_lshlrev_b32_e32 v2, 3, v1
	v_ashrrev_i32_e32 v3, 31, v2
	v_ashrrev_i32_e32 v1, 31, v0
	v_lshl_add_u64 v[6:7], v[2:3], 2, s[76:77]
	v_lshlrev_b64 v[4:5], 7, v[0:1]
	v_lshl_add_u64 v[4:5], v[6:7], 0, v[4:5]
	v_mov_b32_e32 v100, v0
	v_ashrrev_i32_e32 v101, 31, v100
	v_lshlrev_b64 v[100:101], 7, v[100:101]
	v_lshl_add_u64 v[100:101], v[6:7], 0, v[100:101]
	global_load_dwordx4 v[104:107], v[100:101], off offset:16
	global_load_dwordx4 v[108:111], v[100:101], off
	v_add_u32_e32 v100, 0x10, v0
	v_ashrrev_i32_e32 v101, 31, v100
	v_lshlrev_b64 v[100:101], 7, v[100:101]
	v_lshl_add_u64 v[100:101], v[6:7], 0, v[100:101]
	global_load_dwordx4 v[124:127], v[100:101], off offset:16
	global_load_dwordx4 v[180:183], v[100:101], off
	v_add_u32_e32 v100, 0x20, v0
	v_ashrrev_i32_e32 v101, 31, v100
	v_lshlrev_b64 v[100:101], 7, v[100:101]
	v_lshl_add_u64 v[100:101], v[6:7], 0, v[100:101]
	global_load_dwordx4 v[184:187], v[100:101], off offset:16
	global_load_dwordx4 v[188:191], v[100:101], off
	v_add_u32_e32 v100, 0x30, v0
	v_ashrrev_i32_e32 v101, 31, v100
	v_lshlrev_b64 v[100:101], 7, v[100:101]
	v_lshl_add_u64 v[100:101], v[6:7], 0, v[100:101]
	global_load_dwordx4 v[192:195], v[100:101], off offset:16
	global_load_dwordx4 v[196:199], v[100:101], off
	v_add_u32_e32 v100, 0x80, v0
	v_ashrrev_i32_e32 v101, 31, v100
	v_lshlrev_b64 v[100:101], 7, v[100:101]
	v_lshl_add_u64 v[100:101], v[6:7], 0, v[100:101]
	global_load_dwordx4 v[200:203], v[100:101], off offset:16
	global_load_dwordx4 v[204:207], v[100:101], off
	v_add_u32_e32 v100, 0x90, v0
	v_ashrrev_i32_e32 v101, 31, v100
	v_lshlrev_b64 v[100:101], 7, v[100:101]
	v_lshl_add_u64 v[100:101], v[6:7], 0, v[100:101]
	global_load_dwordx4 v[208:211], v[100:101], off offset:16
	global_load_dwordx4 v[212:215], v[100:101], off
	v_add_u32_e32 v100, 0xa0, v0
	v_ashrrev_i32_e32 v101, 31, v100
	v_lshlrev_b64 v[100:101], 7, v[100:101]
	v_lshl_add_u64 v[100:101], v[6:7], 0, v[100:101]
	global_load_dwordx4 v[216:219], v[100:101], off offset:16
	global_load_dwordx4 v[220:223], v[100:101], off
	v_add_u32_e32 v100, 0xb0, v0
	v_ashrrev_i32_e32 v101, 31, v100
	v_lshlrev_b64 v[100:101], 7, v[100:101]
	v_lshl_add_u64 v[100:101], v[6:7], 0, v[100:101]
	global_load_dwordx4 v[224:227], v[100:101], off offset:16
	global_load_dwordx4 v[228:231], v[100:101], off
	s_waitcnt vmcnt(0)
	v_mov_b32_e32 v8, v104
	v_mov_b32_e32 v9, v105
	v_mov_b32_e32 v10, v106
	v_mov_b32_e32 v11, v107
	v_mov_b32_e32 v12, v108
	v_mov_b32_e32 v13, v109
	v_mov_b32_e32 v14, v110
	v_mov_b32_e32 v15, v111
	v_add_u32_e32 v56, 0x90, v0
	v_ashrrev_i32_e32 v57, 31, v56
	v_add_u32_e32 v58, 0xa0, v0
	v_ashrrev_i32_e32 v59, 31, v58
	v_add_u32_e32 v60, 0xb0, v0
	v_ashrrev_i32_e32 v61, 31, v60
	s_lshl_b32 s8, s34, 8
	s_or_b32 s8, s8, s66
	v_add_u32_e32 v2, s8, v2
	v_ashrrev_i32_e32 v3, 31, v2
	s_andn2_b64 vcc, exec, s[4:5]
	v_mov_b32_e32 v5, v8
	v_mov_b32_e32 v4, v12
	v_mov_b32_e32 v16, v14
	v_mov_b32_e32 v17, v10
	v_pk_add_f32 v[4:5], v[4:5], v[16:17]
	v_add_f32_e32 v8, v13, v15
	v_add_f32_e32 v10, v9, v11
	v_mov_b32_e32 v9, v4
	v_mov_b32_e32 v11, v5
	v_pk_add_f32 v[4:5], v[8:9], v[10:11]
	s_nop 0
	v_mov_b32_e32 v8, v4
	v_mov_b32_e32 v9, v5
	s_nop 1
	v_permlane16_swap_b32 v8, v4
	v_permlane16_swap_b32 v9, v5
	s_nop 0
	v_pk_add_f32 v[48:49], v[4:5], v[8:9]
	v_add_u32_e32 v4, 16, v0
	v_ashrrev_i32_e32 v5, 31, v4
	v_lshlrev_b64 v[8:9], 7, v[4:5]
	v_lshl_add_u64 v[12:13], v[6:7], 0, v[8:9]
	v_mov_b32_e32 v8, v124
	v_mov_b32_e32 v9, v125
	v_mov_b32_e32 v10, v126
	v_mov_b32_e32 v11, v127
	s_nop 0
	v_mov_b32_e32 v12, v180
	v_mov_b32_e32 v13, v181
	v_mov_b32_e32 v14, v182
	v_mov_b32_e32 v15, v183
	ds_bpermute_b32 v51, v157, v49
	ds_bpermute_b32 v50, v157, v48
	v_mov_b32_e32 v17, v8
	v_mov_b32_e32 v16, v12
	v_mov_b32_e32 v18, v14
	v_mov_b32_e32 v19, v10
	v_pk_add_f32 v[16:17], v[16:17], v[18:19]
	v_add_f32_e32 v8, v13, v15
	v_add_f32_e32 v10, v9, v11
	v_mov_b32_e32 v9, v16
	v_mov_b32_e32 v11, v17
	v_pk_add_f32 v[8:9], v[8:9], v[10:11]
	s_nop 0
	v_mov_b32_e32 v10, v8
	v_mov_b32_e32 v11, v9
	s_nop 1
	v_permlane16_swap_b32 v10, v8
	v_permlane16_swap_b32 v11, v9
	s_nop 0
	v_pk_add_f32 v[52:53], v[8:9], v[10:11]
	v_add_u32_e32 v8, 32, v0
	v_ashrrev_i32_e32 v9, 31, v8
	v_lshlrev_b64 v[10:11], 7, v[8:9]
	v_lshl_add_u64 v[14:15], v[6:7], 0, v[10:11]
	v_mov_b32_e32 v10, v184
	v_mov_b32_e32 v11, v185
	v_mov_b32_e32 v12, v186
	v_mov_b32_e32 v13, v187
	s_nop 0
	v_mov_b32_e32 v14, v188
	v_mov_b32_e32 v15, v189
	v_mov_b32_e32 v16, v190
	v_mov_b32_e32 v17, v191
	ds_bpermute_b32 v55, v157, v53
	ds_bpermute_b32 v54, v157, v52
	v_mov_b32_e32 v19, v10
	v_mov_b32_e32 v18, v14
	v_mov_b32_e32 v20, v16
	v_mov_b32_e32 v21, v12
	v_pk_add_f32 v[18:19], v[18:19], v[20:21]
	v_add_f32_e32 v10, v15, v17
	v_add_f32_e32 v12, v11, v13
	v_mov_b32_e32 v11, v18
	v_mov_b32_e32 v13, v19
	v_pk_add_f32 v[10:11], v[10:11], v[12:13]
	s_nop 0
	v_mov_b32_e32 v12, v10
	v_mov_b32_e32 v13, v11
	s_nop 1
	v_permlane16_swap_b32 v12, v10
	v_permlane16_swap_b32 v13, v11
	s_nop 0
	v_pk_add_f32 v[64:65], v[10:11], v[12:13]
	v_add_u32_e32 v10, 48, v0
	v_ashrrev_i32_e32 v11, 31, v10
	v_lshlrev_b64 v[12:13], 7, v[10:11]
	v_lshl_add_u64 v[16:17], v[6:7], 0, v[12:13]
	v_mov_b32_e32 v12, v192
	v_mov_b32_e32 v13, v193
	v_mov_b32_e32 v14, v194
	v_mov_b32_e32 v15, v195
	s_nop 0
	v_mov_b32_e32 v16, v196
	v_mov_b32_e32 v17, v197
	v_mov_b32_e32 v18, v198
	v_mov_b32_e32 v19, v199
	ds_bpermute_b32 v67, v157, v65
	ds_bpermute_b32 v66, v157, v64
	v_mov_b32_e32 v21, v12
	v_mov_b32_e32 v20, v16
	v_mov_b32_e32 v22, v18
	v_mov_b32_e32 v23, v14
	v_pk_add_f32 v[20:21], v[20:21], v[22:23]
	v_add_f32_e32 v12, v17, v19
	v_add_f32_e32 v14, v13, v15
	v_mov_b32_e32 v13, v20
	v_mov_b32_e32 v15, v21
	v_pk_add_f32 v[12:13], v[12:13], v[14:15]
	s_nop 0
	v_mov_b32_e32 v14, v12
	v_mov_b32_e32 v15, v13
	s_nop 1
	v_permlane16_swap_b32 v14, v12
	v_permlane16_swap_b32 v15, v13
	s_nop 0
	v_pk_add_f32 v[68:69], v[12:13], v[14:15]
	v_add_u32_e32 v12, 0x80, v0
	v_ashrrev_i32_e32 v13, 31, v12
	v_lshlrev_b64 v[14:15], 7, v[12:13]
	v_lshl_add_u64 v[18:19], v[6:7], 0, v[14:15]
	v_mov_b32_e32 v14, v200
	v_mov_b32_e32 v15, v201
	v_mov_b32_e32 v16, v202
	v_mov_b32_e32 v17, v203
	s_nop 0
	v_mov_b32_e32 v18, v204
	v_mov_b32_e32 v19, v205
	v_mov_b32_e32 v20, v206
	v_mov_b32_e32 v21, v207
	v_lshlrev_b64 v[0:1], 11, v[0:1]
	v_lshl_add_u64 v[0:1], s[44:45], 0, v[0:1]
	ds_bpermute_b32 v71, v157, v69
	ds_bpermute_b32 v70, v157, v68
	v_mov_b32_e32 v23, v14
	v_mov_b32_e32 v22, v18
	v_mov_b32_e32 v24, v20
	v_mov_b32_e32 v25, v16
	v_pk_add_f32 v[22:23], v[22:23], v[24:25]
	v_add_f32_e32 v14, v19, v21
	v_add_f32_e32 v16, v15, v17
	v_mov_b32_e32 v15, v22
	v_mov_b32_e32 v17, v23
	v_pk_add_f32 v[14:15], v[14:15], v[16:17]
	s_nop 0
	v_mov_b32_e32 v16, v14
	v_mov_b32_e32 v17, v15
	s_nop 1
	v_permlane16_swap_b32 v16, v14
	v_permlane16_swap_b32 v17, v15
	s_nop 0
	v_pk_add_f32 v[112:113], v[14:15], v[16:17]
	v_lshlrev_b64 v[14:15], 7, v[56:57]
	v_lshl_add_u64 v[18:19], v[6:7], 0, v[14:15]
	v_mov_b32_e32 v14, v208
	v_mov_b32_e32 v15, v209
	v_mov_b32_e32 v16, v210
	v_mov_b32_e32 v17, v211
	s_nop 0
	v_mov_b32_e32 v18, v212
	v_mov_b32_e32 v19, v213
	v_mov_b32_e32 v20, v214
	v_mov_b32_e32 v21, v215
	ds_bpermute_b32 v115, v157, v113
	ds_bpermute_b32 v114, v157, v112
	v_mov_b32_e32 v23, v14
	v_mov_b32_e32 v22, v18
	v_mov_b32_e32 v24, v20
	v_mov_b32_e32 v25, v16
	v_pk_add_f32 v[22:23], v[22:23], v[24:25]
	v_add_f32_e32 v14, v19, v21
	v_add_f32_e32 v16, v15, v17
	v_mov_b32_e32 v15, v22
	v_mov_b32_e32 v17, v23
	v_pk_add_f32 v[14:15], v[14:15], v[16:17]
	s_nop 0
	v_mov_b32_e32 v16, v14
	v_mov_b32_e32 v17, v15
	s_nop 1
	v_permlane16_swap_b32 v16, v14
	v_permlane16_swap_b32 v17, v15
	s_nop 0
	v_pk_add_f32 v[116:117], v[14:15], v[16:17]
	v_lshlrev_b64 v[14:15], 7, v[58:59]
	v_lshl_add_u64 v[18:19], v[6:7], 0, v[14:15]
	v_mov_b32_e32 v14, v216
	v_mov_b32_e32 v15, v217
	v_mov_b32_e32 v16, v218
	v_mov_b32_e32 v17, v219
	s_nop 0
	v_mov_b32_e32 v18, v220
	v_mov_b32_e32 v19, v221
	v_mov_b32_e32 v20, v222
	v_mov_b32_e32 v21, v223
	ds_bpermute_b32 v119, v157, v117
	ds_bpermute_b32 v118, v157, v116
	v_mov_b32_e32 v23, v14
	v_mov_b32_e32 v22, v18
	v_mov_b32_e32 v24, v20
	v_mov_b32_e32 v25, v16
	v_pk_add_f32 v[22:23], v[22:23], v[24:25]
	v_add_f32_e32 v14, v19, v21
	v_add_f32_e32 v16, v15, v17
	v_mov_b32_e32 v15, v22
	v_mov_b32_e32 v17, v23
	v_pk_add_f32 v[14:15], v[14:15], v[16:17]
	s_nop 0
	v_mov_b32_e32 v16, v14
	v_mov_b32_e32 v17, v15
	s_nop 1
	v_permlane16_swap_b32 v16, v14
	v_permlane16_swap_b32 v17, v15
	s_nop 0
	v_pk_add_f32 v[120:121], v[14:15], v[16:17]
	v_lshlrev_b64 v[14:15], 7, v[60:61]
	v_lshl_add_u64 v[6:7], v[6:7], 0, v[14:15]
	v_mov_b32_e32 v14, v224
	v_mov_b32_e32 v15, v225
	v_mov_b32_e32 v16, v226
	v_mov_b32_e32 v17, v227
	v_mov_b32_e32 v18, v228
	v_mov_b32_e32 v19, v229
	v_mov_b32_e32 v20, v230
	v_mov_b32_e32 v21, v231
	ds_bpermute_b32 v123, v157, v121
	ds_bpermute_b32 v122, v157, v120
	v_mov_b32_e32 v7, v14
	v_mov_b32_e32 v6, v18
	v_mov_b32_e32 v22, v20
	v_mov_b32_e32 v23, v16
	v_pk_add_f32 v[6:7], v[6:7], v[22:23]
	v_add_f32_e32 v14, v19, v21
	v_add_f32_e32 v16, v15, v17
	v_mov_b32_e32 v15, v6
	v_mov_b32_e32 v17, v7
	v_pk_add_f32 v[6:7], v[14:15], v[16:17]
	s_nop 0
	v_mov_b32_e32 v14, v6
	v_mov_b32_e32 v15, v7
	s_nop 1
	v_permlane16_swap_b32 v14, v6
	v_permlane16_swap_b32 v15, v7
	s_nop 0
	v_pk_add_f32 v[124:125], v[6:7], v[14:15]
	v_lshlrev_b64 v[6:7], 2, v[2:3]
	v_lshlrev_b64 v[2:3], 1, v[2:3]
	v_lshl_add_u64 v[74:75], v[0:1], 0, v[2:3]
	v_lshlrev_b64 v[0:1], 11, v[4:5]
	v_lshl_add_u64 v[0:1], s[44:45], 0, v[0:1]
	v_lshl_add_u64 v[76:77], v[0:1], 0, v[2:3]
	v_lshlrev_b64 v[0:1], 11, v[8:9]
	v_lshl_add_u64 v[0:1], s[44:45], 0, v[0:1]
	v_lshl_add_u64 v[78:79], v[0:1], 0, v[2:3]
	v_lshlrev_b64 v[0:1], 11, v[10:11]
	v_lshl_add_u64 v[0:1], s[44:45], 0, v[0:1]
	v_lshl_add_u64 v[80:81], v[0:1], 0, v[2:3]
	v_lshlrev_b64 v[0:1], 11, v[12:13]
	v_lshl_add_u64 v[0:1], s[44:45], 0, v[0:1]
	v_lshl_add_u64 v[146:147], v[0:1], 0, v[2:3]
	v_lshlrev_b64 v[0:1], 11, v[56:57]
	v_lshl_add_u64 v[0:1], s[44:45], 0, v[0:1]
	v_lshl_add_u64 v[56:57], v[0:1], 0, v[2:3]
	v_lshlrev_b64 v[0:1], 11, v[58:59]
	v_lshl_add_u64 v[0:1], s[44:45], 0, v[0:1]
	v_lshl_add_u64 v[58:59], v[0:1], 0, v[2:3]
	v_lshlrev_b64 v[0:1], 11, v[60:61]
	v_lshl_add_u64 v[0:1], s[44:45], 0, v[0:1]
	v_lshl_add_u64 v[62:63], s[28:29], 0, v[6:7]
	v_lshl_add_u64 v[72:73], s[30:31], 0, v[6:7]
	v_lshl_add_u64 v[148:149], v[0:1], 0, v[2:3]
	global_load_dwordx4 v[36:39], v[62:63], off offset:16
	global_load_dwordx4 v[44:47], v[62:63], off
	global_load_dwordx4 v[32:35], v[72:73], off offset:16
	global_load_dwordx4 v[40:43], v[72:73], off
	global_load_dwordx4 v[28:31], v[74:75], off
	global_load_dwordx4 v[24:27], v[76:77], off
	global_load_dwordx4 v[20:23], v[78:79], off
	global_load_dwordx4 v[16:19], v[80:81], off
	global_load_dwordx4 v[12:15], v[146:147], off
	global_load_dwordx4 v[8:11], v[56:57], off
	global_load_dwordx4 v[4:7], v[58:59], off
	global_load_dwordx4 v[0:3], v[148:149], off
	global_load_dwordx4 v[104:107], v[62:63], off offset:528
	global_load_dwordx4 v[108:111], v[62:63], off offset:512
	global_load_dwordx4 v[96:99], v[72:73], off offset:528
	global_load_dwordx4 v[100:103], v[72:73], off offset:512
	global_load_dwordx4 v[92:95], v[74:75], off offset:256
	global_load_dwordx4 v[88:91], v[76:77], off offset:256
	global_load_dwordx4 v[84:87], v[78:79], off offset:256
	s_nop 0
	global_load_dwordx4 v[80:83], v[80:81], off offset:256
	s_nop 0
	global_load_dwordx4 v[76:79], v[146:147], off offset:256
	global_load_dwordx4 v[72:75], v[56:57], off offset:256
	global_load_dwordx4 v[60:63], v[58:59], off offset:256
	s_nop 0
	global_load_dwordx4 v[56:59], v[148:149], off offset:256
	ds_bpermute_b32 v127, v157, v125
	ds_bpermute_b32 v126, v157, v124
	s_cbranch_vccnz .LBB0_1504
	s_barrier
	s_branch .LBB0_1504

.LBB0_1673:
	v_readlane_b32 s0, v255, 32
	v_readlane_b32 s1, v255, 33
	s_and_b64 vcc, exec, s[0:1]
	s_cbranch_vccnz .LBB0_1713
	v_ashrrev_i32_e32 v2, 31, v0
	v_lshrrev_b32_e32 v2, 26, v2
	v_add_u32_e32 v2, v0, v2
	v_ashrrev_i32_e32 v137, 6, v2
	v_bfe_i32 v2, v0, 27, 1
	v_lshlrev_b32_e32 v1, 4, v0
	v_lshrrev_b32_e32 v2, 22, v2
	v_add_u32_e32 v2, v1, v2
	v_and_b32_e32 v2, 0xfffffc00, v2
	v_sub_u32_e32 v2, v1, v2
	v_lshrrev_b32_e32 v3, 4, v2
	v_bitop3_b32 v2, v3, v2, 32 bitop3:0x6c
	v_ashrrev_i32_e32 v4, 31, v2
	v_lshrrev_b32_e32 v4, 26, v4
	v_lshlrev_b32_e32 v3, 3, v137
	v_add_u32_e32 v4, v2, v4
	v_and_b32_e32 v3, -16, v3
	v_ashrrev_i32_e32 v149, 6, v4
	v_and_b32_e32 v4, 0xc0, v4
	v_add_u32_e32 v3, v149, v3
	v_lshlrev_b32_e32 v5, 5, v137
	v_sub_u32_e32 v2, v2, v4
	v_mov_b32_e32 v4, 1
	v_and_b32_e32 v147, 32, v5
	v_ashrrev_i16_sdwa v2, v4, sext(v2) dst_sel:DWORD dst_unused:UNUSED_PAD src0_sel:DWORD src1_sel:BYTE_0
	v_lshlrev_b32_e32 v5, 1, v3
	v_lshrrev_b32_e32 v6, 2, v3
	v_and_b32_e32 v7, 3, v149
	s_mov_b32 s6, 0xffffe0
	v_bfe_i32 v161, v2, 0, 16
	v_and_b32_e32 v5, 24, v5
	v_and_b32_e32 v6, 4, v6
	v_and_or_b32 v7, v3, s6, v7
	s_movk_i32 s11, 0xb00
	v_add_u32_e32 v2, v147, v161
	v_or3_b32 v5, v7, v6, v5
	v_mul_lo_u32 v3, v3, s11
	v_add_lshl_u32 v128, v2, v3, 1
	v_mul_u32_u24_e32 v3, 0xb00, v5
	v_add_u32_e32 v1, 0x2000, v1
	v_add_lshl_u32 v130, v3, v2, 1
	v_ashrrev_i32_e32 v2, 31, v1
	v_lshrrev_b32_e32 v2, 22, v2
	v_add_u32_e32 v2, v1, v2
	v_ashrrev_i32_e32 v163, 10, v2
	v_mul_i32_i24_e32 v2, 0x400, v163
	v_sub_u32_e32 v1, v1, v2
	v_lshrrev_b32_e32 v2, 4, v1
	v_bitop3_b32 v1, v2, v1, 32 bitop3:0x6c
	v_ashrrev_i32_e32 v3, 31, v1
	v_lshrrev_b32_e32 v3, 26, v3
	v_lshlrev_b32_e32 v2, 3, v163
	v_add_u32_e32 v3, v1, v3
	v_and_b32_e32 v2, -16, v2
	v_ashrrev_i32_e32 v165, 6, v3
	v_and_b32_e32 v3, 0xc0, v3
	v_add_u32_e32 v2, v165, v2
	v_lshlrev_b32_e32 v5, 5, v163
	v_sub_u32_e32 v1, v1, v3
	v_and_b32_e32 v167, 32, v5
	v_ashrrev_i16_sdwa v1, v4, sext(v1) dst_sel:DWORD dst_unused:UNUSED_PAD src0_sel:DWORD src1_sel:BYTE_0
	v_lshlrev_b32_e32 v3, 1, v2
	v_lshrrev_b32_e32 v4, 2, v2
	v_and_b32_e32 v5, 3, v165
	v_bfe_i32 v169, v1, 0, 16
	v_and_b32_e32 v3, 24, v3
	v_and_b32_e32 v4, 4, v4
	v_and_or_b32 v5, v2, s6, v5
	v_add_u32_e32 v1, v167, v169
	v_or3_b32 v3, v5, v4, v3
	v_mul_lo_u32 v2, v2, s11
	v_bfe_u32 v151, v0, 4, 2
	v_add_lshl_u32 v132, v1, v2, 1
	v_mul_u32_u24_e32 v2, 0xb00, v3
	v_and_b32_e32 v153, 15, v0
	v_add_lshl_u32 v134, v2, v1, 1
	v_mov_b32_e32 v1, v151
	v_mov_b32_e32 v0, v153
	s_add_u32 s0, s20, 0x1000
	v_lshlrev_b32_e32 v2, 3, v1
	v_mbcnt_lo_u32_b32 v1, -1, 0
	v_mbcnt_hi_u32_b32 v1, -1, v1
	v_and_b32_e32 v5, 64, v1
	v_xor_b32_e32 v4, 16, v1
	v_add_u32_e32 v5, 64, v5
	v_cmp_lt_i32_e32 vcc, v4, v5
	s_addc_u32 s1, s21, 0
	s_ashr_i32 s5, s10, 6
	s_ashr_i32 s12, s10, 8
	v_cndmask_b32_e32 v4, v1, v4, vcc
	s_and_b32 s4, s5, 3
	s_lshl_b32 s9, s5, 10
	s_lshl_b32 s15, s12, 6
	s_lshl_b32 s5, s80, 8
	v_lshlrev_b32_e32 v155, 2, v4
	v_xor_b32_e32 v4, 32, v1
	s_add_i32 s5, s5, s15
	v_cmp_lt_i32_e32 vcc, v4, v5
	v_add_u32_e32 v0, s5, v0
	v_ashrrev_i32_e32 v3, 31, v2
	v_cndmask_b32_e32 v1, v1, v4, vcc
	v_lshlrev_b32_e32 v157, 2, v1
	v_ashrrev_i32_e32 v1, 31, v0
	v_lshl_add_u64 v[6:7], v[2:3], 2, s[62:63]
	v_lshlrev_b64 v[4:5], 7, v[0:1]
	v_lshl_add_u64 v[4:5], v[6:7], 0, v[4:5]
	v_mov_b32_e32 v184, v0
	v_ashrrev_i32_e32 v185, 31, v184
	v_lshlrev_b64 v[184:185], 7, v[184:185]
	v_lshl_add_u64 v[184:185], v[6:7], 0, v[184:185]
	global_load_dwordx4 v[188:191], v[184:185], off offset:16
	global_load_dwordx4 v[192:195], v[184:185], off
	v_add_u32_e32 v184, 0x10, v0
	v_ashrrev_i32_e32 v185, 31, v184
	v_lshlrev_b64 v[184:185], 7, v[184:185]
	v_lshl_add_u64 v[184:185], v[6:7], 0, v[184:185]
	global_load_dwordx4 v[196:199], v[184:185], off offset:16
	global_load_dwordx4 v[200:203], v[184:185], off
	v_add_u32_e32 v184, 0x20, v0
	v_ashrrev_i32_e32 v185, 31, v184
	v_lshlrev_b64 v[184:185], 7, v[184:185]
	v_lshl_add_u64 v[184:185], v[6:7], 0, v[184:185]
	global_load_dwordx4 v[204:207], v[184:185], off offset:16
	global_load_dwordx4 v[208:211], v[184:185], off
	v_add_u32_e32 v184, 0x30, v0
	v_ashrrev_i32_e32 v185, 31, v184
	v_lshlrev_b64 v[184:185], 7, v[184:185]
	v_lshl_add_u64 v[184:185], v[6:7], 0, v[184:185]
	global_load_dwordx4 v[212:215], v[184:185], off offset:16
	global_load_dwordx4 v[216:219], v[184:185], off
	v_add_u32_e32 v184, 0x80, v0
	v_ashrrev_i32_e32 v185, 31, v184
	v_lshlrev_b64 v[184:185], 7, v[184:185]
	v_lshl_add_u64 v[184:185], v[6:7], 0, v[184:185]
	global_load_dwordx4 v[220:223], v[184:185], off offset:16
	global_load_dwordx4 v[224:227], v[184:185], off
	v_add_u32_e32 v184, 0x90, v0
	v_ashrrev_i32_e32 v185, 31, v184
	v_lshlrev_b64 v[184:185], 7, v[184:185]
	v_lshl_add_u64 v[184:185], v[6:7], 0, v[184:185]
	global_load_dwordx4 v[228:231], v[184:185], off offset:16
	global_load_dwordx4 v[232:235], v[184:185], off
	v_add_u32_e32 v184, 0xa0, v0
	v_ashrrev_i32_e32 v185, 31, v184
	v_lshlrev_b64 v[184:185], 7, v[184:185]
	v_lshl_add_u64 v[184:185], v[6:7], 0, v[184:185]
	global_load_dwordx4 v[236:239], v[184:185], off offset:16
	global_load_dwordx4 v[240:243], v[184:185], off
	v_add_u32_e32 v184, 0xb0, v0
	v_ashrrev_i32_e32 v185, 31, v184
	v_lshlrev_b64 v[184:185], 7, v[184:185]
	v_lshl_add_u64 v[184:185], v[6:7], 0, v[184:185]
	global_load_dwordx4 v[244:247], v[184:185], off offset:16
	global_load_dwordx4 v[248:251], v[184:185], off
	s_waitcnt vmcnt(0)
	v_mov_b32_e32 v8, v188
	v_mov_b32_e32 v9, v189
	v_mov_b32_e32 v10, v190
	v_mov_b32_e32 v11, v191
	v_mov_b32_e32 v12, v192
	v_mov_b32_e32 v13, v193
	v_mov_b32_e32 v14, v194
	v_mov_b32_e32 v15, v195
	v_add_u32_e32 v56, 0x90, v0
	v_ashrrev_i32_e32 v57, 31, v56
	v_add_u32_e32 v58, 0xa0, v0
	v_ashrrev_i32_e32 v59, 31, v58
	v_add_u32_e32 v60, 0xb0, v0
	v_ashrrev_i32_e32 v61, 31, v60
	s_lshl_b32 s66, s4, 5
	s_lshl_b32 s6, s79, 8
	s_or_b32 s6, s6, s66
	v_add_u32_e32 v2, s6, v2
	v_ashrrev_i32_e32 v3, 31, v2
	v_readlane_b32 s6, v255, 48
	v_readlane_b32 s7, v255, 49
	s_cmp_gt_i32 s80, 63
	v_readlane_b32 s34, v255, 44
	v_readlane_b32 s36, v255, 46
	v_readlane_b32 s35, v255, 45
	v_readlane_b32 s37, v255, 47
	s_mul_hi_i32 s14, s79, 0x160000
	s_mul_i32 s13, s80, 0x160000
	s_mul_hi_i32 s8, s80, 0x160000
	v_mov_b32_e32 v136, 0
	v_mov_b32_e32 v131, v136
	v_mov_b32_e32 v135, v136
	v_mov_b32_e32 v129, v136
	v_mov_b32_e32 v133, v136
	s_mov_b32 s5, 0
	v_mov_b32_e32 v5, v8
	v_mov_b32_e32 v4, v12
	v_mov_b32_e32 v16, v14
	v_mov_b32_e32 v17, v10
	v_pk_add_f32 v[4:5], v[4:5], v[16:17]
	v_add_f32_e32 v8, v13, v15
	v_add_f32_e32 v10, v9, v11
	v_mov_b32_e32 v9, v4
	v_mov_b32_e32 v11, v5
	v_pk_add_f32 v[4:5], v[8:9], v[10:11]
	s_nop 0
	v_mov_b32_e32 v8, v4
	v_mov_b32_e32 v9, v5
	s_nop 1
	v_permlane16_swap_b32 v8, v4
	v_permlane16_swap_b32 v9, v5
	s_nop 0
	v_pk_add_f32 v[48:49], v[4:5], v[8:9]
	v_add_u32_e32 v4, 16, v0
	v_ashrrev_i32_e32 v5, 31, v4
	v_lshlrev_b64 v[8:9], 7, v[4:5]
	v_lshl_add_u64 v[12:13], v[6:7], 0, v[8:9]
	v_mov_b32_e32 v8, v196
	v_mov_b32_e32 v9, v197
	v_mov_b32_e32 v10, v198
	v_mov_b32_e32 v11, v199
	s_nop 0
	v_mov_b32_e32 v12, v200
	v_mov_b32_e32 v13, v201
	v_mov_b32_e32 v14, v202
	v_mov_b32_e32 v15, v203
	ds_bpermute_b32 v51, v157, v49
	ds_bpermute_b32 v50, v157, v48
	v_mov_b32_e32 v17, v8
	v_mov_b32_e32 v16, v12
	v_mov_b32_e32 v18, v14
	v_mov_b32_e32 v19, v10
	v_pk_add_f32 v[16:17], v[16:17], v[18:19]
	v_add_f32_e32 v8, v13, v15
	v_add_f32_e32 v10, v9, v11
	v_mov_b32_e32 v9, v16
	v_mov_b32_e32 v11, v17
	v_pk_add_f32 v[8:9], v[8:9], v[10:11]
	s_nop 0
	v_mov_b32_e32 v10, v8
	v_mov_b32_e32 v11, v9
	s_nop 1
	v_permlane16_swap_b32 v10, v8
	v_permlane16_swap_b32 v11, v9
	s_nop 0
	v_pk_add_f32 v[52:53], v[8:9], v[10:11]
	v_add_u32_e32 v8, 32, v0
	v_ashrrev_i32_e32 v9, 31, v8
	v_lshlrev_b64 v[10:11], 7, v[8:9]
	v_lshl_add_u64 v[14:15], v[6:7], 0, v[10:11]
	v_mov_b32_e32 v10, v204
	v_mov_b32_e32 v11, v205
	v_mov_b32_e32 v12, v206
	v_mov_b32_e32 v13, v207
	s_nop 0
	v_mov_b32_e32 v14, v208
	v_mov_b32_e32 v15, v209
	v_mov_b32_e32 v16, v210
	v_mov_b32_e32 v17, v211
	ds_bpermute_b32 v55, v157, v53
	ds_bpermute_b32 v54, v157, v52
	v_mov_b32_e32 v19, v10
	v_mov_b32_e32 v18, v14
	v_mov_b32_e32 v20, v16
	v_mov_b32_e32 v21, v12
	v_pk_add_f32 v[18:19], v[18:19], v[20:21]
	v_add_f32_e32 v10, v15, v17
	v_add_f32_e32 v12, v11, v13
	v_mov_b32_e32 v11, v18
	v_mov_b32_e32 v13, v19
	v_pk_add_f32 v[10:11], v[10:11], v[12:13]
	s_nop 0
	v_mov_b32_e32 v12, v10
	v_mov_b32_e32 v13, v11
	s_nop 1
	v_permlane16_swap_b32 v12, v10
	v_permlane16_swap_b32 v13, v11
	s_nop 0
	v_pk_add_f32 v[64:65], v[10:11], v[12:13]
	v_add_u32_e32 v10, 48, v0
	v_ashrrev_i32_e32 v11, 31, v10
	v_lshlrev_b64 v[12:13], 7, v[10:11]
	v_lshl_add_u64 v[16:17], v[6:7], 0, v[12:13]
	v_mov_b32_e32 v12, v212
	v_mov_b32_e32 v13, v213
	v_mov_b32_e32 v14, v214
	v_mov_b32_e32 v15, v215
	s_nop 0
	v_mov_b32_e32 v16, v216
	v_mov_b32_e32 v17, v217
	v_mov_b32_e32 v18, v218
	v_mov_b32_e32 v19, v219
	ds_bpermute_b32 v67, v157, v65
	ds_bpermute_b32 v66, v157, v64
	v_mov_b32_e32 v21, v12
	v_mov_b32_e32 v20, v16
	v_mov_b32_e32 v22, v18
	v_mov_b32_e32 v23, v14
	v_pk_add_f32 v[20:21], v[20:21], v[22:23]
	v_add_f32_e32 v12, v17, v19
	v_add_f32_e32 v14, v13, v15
	v_mov_b32_e32 v13, v20
	v_mov_b32_e32 v15, v21
	v_pk_add_f32 v[12:13], v[12:13], v[14:15]
	s_nop 0
	v_mov_b32_e32 v14, v12
	v_mov_b32_e32 v15, v13
	s_nop 1
	v_permlane16_swap_b32 v14, v12
	v_permlane16_swap_b32 v15, v13
	s_nop 0
	v_pk_add_f32 v[68:69], v[12:13], v[14:15]
	v_add_u32_e32 v12, 0x80, v0
	v_ashrrev_i32_e32 v13, 31, v12
	v_lshlrev_b64 v[14:15], 7, v[12:13]
	v_lshl_add_u64 v[18:19], v[6:7], 0, v[14:15]
	v_mov_b32_e32 v14, v220
	v_mov_b32_e32 v15, v221
	v_mov_b32_e32 v16, v222
	v_mov_b32_e32 v17, v223
	s_nop 0
	v_mov_b32_e32 v18, v224
	v_mov_b32_e32 v19, v225
	v_mov_b32_e32 v20, v226
	v_mov_b32_e32 v21, v227
	v_lshlrev_b64 v[0:1], 11, v[0:1]
	v_lshl_add_u64 v[0:1], s[44:45], 0, v[0:1]
	ds_bpermute_b32 v71, v157, v69
	ds_bpermute_b32 v70, v157, v68
	v_mov_b32_e32 v23, v14
	v_mov_b32_e32 v22, v18
	v_mov_b32_e32 v24, v20
	v_mov_b32_e32 v25, v16
	v_pk_add_f32 v[22:23], v[22:23], v[24:25]
	v_add_f32_e32 v14, v19, v21
	v_add_f32_e32 v16, v15, v17
	v_mov_b32_e32 v15, v22
	v_mov_b32_e32 v17, v23
	v_pk_add_f32 v[14:15], v[14:15], v[16:17]
	s_nop 0
	v_mov_b32_e32 v16, v14
	v_mov_b32_e32 v17, v15
	s_nop 1
	v_permlane16_swap_b32 v16, v14
	v_permlane16_swap_b32 v17, v15
	s_nop 0
	v_pk_add_f32 v[112:113], v[14:15], v[16:17]
	v_lshlrev_b64 v[14:15], 7, v[56:57]
	v_lshl_add_u64 v[18:19], v[6:7], 0, v[14:15]
	v_mov_b32_e32 v14, v228
	v_mov_b32_e32 v15, v229
	v_mov_b32_e32 v16, v230
	v_mov_b32_e32 v17, v231
	s_nop 0
	v_mov_b32_e32 v18, v232
	v_mov_b32_e32 v19, v233
	v_mov_b32_e32 v20, v234
	v_mov_b32_e32 v21, v235
	ds_bpermute_b32 v115, v157, v113
	ds_bpermute_b32 v114, v157, v112
	v_mov_b32_e32 v23, v14
	v_mov_b32_e32 v22, v18
	v_mov_b32_e32 v24, v20
	v_mov_b32_e32 v25, v16
	v_pk_add_f32 v[22:23], v[22:23], v[24:25]
	v_add_f32_e32 v14, v19, v21
	v_add_f32_e32 v16, v15, v17
	v_mov_b32_e32 v15, v22
	v_mov_b32_e32 v17, v23
	v_pk_add_f32 v[14:15], v[14:15], v[16:17]
	s_nop 0
	v_mov_b32_e32 v16, v14
	v_mov_b32_e32 v17, v15
	s_nop 1
	v_permlane16_swap_b32 v16, v14
	v_permlane16_swap_b32 v17, v15
	s_nop 0
	v_pk_add_f32 v[116:117], v[14:15], v[16:17]
	v_lshlrev_b64 v[14:15], 7, v[58:59]
	v_lshl_add_u64 v[18:19], v[6:7], 0, v[14:15]
	v_mov_b32_e32 v14, v236
	v_mov_b32_e32 v15, v237
	v_mov_b32_e32 v16, v238
	v_mov_b32_e32 v17, v239
	s_nop 0
	v_mov_b32_e32 v18, v240
	v_mov_b32_e32 v19, v241
	v_mov_b32_e32 v20, v242
	v_mov_b32_e32 v21, v243
	ds_bpermute_b32 v119, v157, v117
	ds_bpermute_b32 v118, v157, v116
	v_mov_b32_e32 v23, v14
	v_mov_b32_e32 v22, v18
	v_mov_b32_e32 v24, v20
	v_mov_b32_e32 v25, v16
	v_pk_add_f32 v[22:23], v[22:23], v[24:25]
	v_add_f32_e32 v14, v19, v21
	v_add_f32_e32 v16, v15, v17
	v_mov_b32_e32 v15, v22
	v_mov_b32_e32 v17, v23
	v_pk_add_f32 v[14:15], v[14:15], v[16:17]
	s_nop 0
	v_mov_b32_e32 v16, v14
	v_mov_b32_e32 v17, v15
	s_nop 1
	v_permlane16_swap_b32 v16, v14
	v_permlane16_swap_b32 v17, v15
	s_nop 0
	v_pk_add_f32 v[120:121], v[14:15], v[16:17]
	v_lshlrev_b64 v[14:15], 7, v[60:61]
	v_lshl_add_u64 v[6:7], v[6:7], 0, v[14:15]
	v_mov_b32_e32 v14, v244
	v_mov_b32_e32 v15, v245
	v_mov_b32_e32 v16, v246
	v_mov_b32_e32 v17, v247
	v_mov_b32_e32 v18, v248
	v_mov_b32_e32 v19, v249
	v_mov_b32_e32 v20, v250
	v_mov_b32_e32 v21, v251
	ds_bpermute_b32 v123, v157, v121
	ds_bpermute_b32 v122, v157, v120
	v_mov_b32_e32 v7, v14
	v_mov_b32_e32 v6, v18
	v_mov_b32_e32 v22, v20
	v_mov_b32_e32 v23, v16
	v_pk_add_f32 v[6:7], v[6:7], v[22:23]
	v_add_f32_e32 v14, v19, v21
	v_add_f32_e32 v16, v15, v17
	v_mov_b32_e32 v15, v6
	v_mov_b32_e32 v17, v7
	v_pk_add_f32 v[6:7], v[14:15], v[16:17]
	s_nop 0
	v_mov_b32_e32 v14, v6
	v_mov_b32_e32 v15, v7
	s_nop 1
	v_permlane16_swap_b32 v14, v6
	v_permlane16_swap_b32 v15, v7
	s_nop 0
	v_pk_add_f32 v[124:125], v[6:7], v[14:15]
	v_lshlrev_b64 v[6:7], 2, v[2:3]
	v_lshlrev_b64 v[2:3], 1, v[2:3]
	v_lshl_add_u64 v[74:75], v[0:1], 0, v[2:3]
	v_lshlrev_b64 v[0:1], 11, v[4:5]
	v_lshl_add_u64 v[0:1], s[44:45], 0, v[0:1]
	v_lshl_add_u64 v[76:77], v[0:1], 0, v[2:3]
	v_lshlrev_b64 v[0:1], 11, v[8:9]
	v_lshl_add_u64 v[0:1], s[44:45], 0, v[0:1]
	v_lshl_add_u64 v[78:79], v[0:1], 0, v[2:3]
	v_lshlrev_b64 v[0:1], 11, v[10:11]
	v_lshl_add_u64 v[0:1], s[44:45], 0, v[0:1]
	v_lshl_add_u64 v[80:81], v[0:1], 0, v[2:3]
	v_lshlrev_b64 v[0:1], 11, v[12:13]
	v_lshl_add_u64 v[0:1], s[44:45], 0, v[0:1]
	v_lshl_add_u64 v[138:139], v[0:1], 0, v[2:3]
	v_lshlrev_b64 v[0:1], 11, v[56:57]
	v_lshl_add_u64 v[0:1], s[44:45], 0, v[0:1]
	v_lshl_add_u64 v[56:57], v[0:1], 0, v[2:3]
	v_lshlrev_b64 v[0:1], 11, v[58:59]
	v_lshl_add_u64 v[0:1], s[44:45], 0, v[0:1]
	v_lshl_add_u64 v[58:59], v[0:1], 0, v[2:3]
	v_lshlrev_b64 v[0:1], 11, v[60:61]
	v_lshl_add_u64 v[62:63], s[6:7], 0, v[6:7]
	v_lshl_add_u64 v[0:1], s[44:45], 0, v[0:1]
	s_cselect_b32 s7, s36, s34
	s_mul_i32 s34, s79, 0x160000
	v_lshl_add_u64 v[72:73], s[0:1], 0, v[6:7]
	v_lshl_add_u64 v[140:141], v[0:1], 0, v[2:3]
	s_cselect_b32 s6, s37, s35
	s_add_u32 s74, s7, s34
	global_load_dwordx4 v[36:39], v[62:63], off offset:16
	global_load_dwordx4 v[44:47], v[62:63], off
	global_load_dwordx4 v[32:35], v[72:73], off offset:16
	global_load_dwordx4 v[40:43], v[72:73], off
	global_load_dwordx4 v[28:31], v[74:75], off
	global_load_dwordx4 v[24:27], v[76:77], off
	global_load_dwordx4 v[20:23], v[78:79], off
	global_load_dwordx4 v[16:19], v[80:81], off
	global_load_dwordx4 v[12:15], v[138:139], off
	global_load_dwordx4 v[8:11], v[56:57], off
	global_load_dwordx4 v[4:7], v[58:59], off
	global_load_dwordx4 v[0:3], v[140:141], off
	global_load_dwordx4 v[100:103], v[62:63], off offset:528
	global_load_dwordx4 v[108:111], v[62:63], off offset:512
	global_load_dwordx4 v[96:99], v[72:73], off offset:528
	global_load_dwordx4 v[104:107], v[72:73], off offset:512
	global_load_dwordx4 v[92:95], v[74:75], off offset:256
	global_load_dwordx4 v[88:91], v[76:77], off offset:256
	global_load_dwordx4 v[84:87], v[78:79], off offset:256
	s_nop 0
	global_load_dwordx4 v[80:83], v[80:81], off offset:256
	s_nop 0
	global_load_dwordx4 v[76:79], v[138:139], off offset:256
	global_load_dwordx4 v[72:75], v[56:57], off offset:256
	global_load_dwordx4 v[60:63], v[58:59], off offset:256
	s_nop 0
	global_load_dwordx4 v[56:59], v[140:141], off offset:256
	s_addc_u32 s75, s6, s14
	s_add_i32 s67, s9, 0
	s_add_i32 m0, s67, 0x10000
	ds_bpermute_b32 v127, v157, v125
	global_load_lds_dwordx4 v130, s[74:75]
	s_add_i32 m0, s67, 0x12000
	s_add_u32 s6, s74, 0xb0000
	global_load_lds_dwordx4 v134, s[74:75]
	s_addc_u32 s7, s75, 0
	s_add_i32 m0, s67, 0x14000
	ds_bpermute_b32 v126, v157, v124
	global_load_lds_dwordx4 v130, s[6:7]
	s_add_i32 m0, s67, 0x16000
	s_add_u32 s40, s42, s13
	s_addc_u32 s41, s43, s8
	s_add_i32 s68, s67, 0x2000
	global_load_lds_dwordx4 v134, s[6:7]
	s_mov_b32 m0, s67
	s_add_u32 s6, s40, 0xb0000
	global_load_lds_dwordx4 v128, s[40:41]
	s_mov_b32 m0, s68
	s_addc_u32 s7, s41, 0
	s_add_i32 s69, s67, 0x4000
	global_load_lds_dwordx4 v132, s[40:41]
	s_mov_b32 m0, s69
	s_add_i32 s88, s67, 0x6000
	global_load_lds_dwordx4 v128, s[6:7]
	s_mov_b32 m0, s88
	s_cmp_eq_u32 s12, 1
	global_load_lds_dwordx4 v132, s[6:7]
	v_lshl_add_u64 v[138:139], s[74:75], 0, v[130:131]
	v_lshl_add_u64 v[140:141], s[74:75], 0, v[134:135]
	v_lshl_add_u64 v[142:143], s[40:41], 0, v[128:129]
	v_lshl_add_u64 v[144:145], s[40:41], 0, v[132:133]
	s_cselect_b64 s[6:7], -1, 0
	s_cmp_lg_u32 s12, 1
	s_cbranch_scc1 .LBB0_1676
	s_barrier

.LBB0_1709:
	s_or_b64 exec, exec, s[46:47]
	s_and_b64 vcc, exec, s[10:11]
	s_mov_b64 s[10:11], -1
	s_cbranch_vccnz .LBB0_1678
	v_mov_b32_e32 v0, v153
	v_mov_b32_e32 v1, v151
	s_lshl_b32 s10, s78, 8
	s_add_i32 s10, s10, s15
	v_add_u32_e32 v0, s10, v0
	s_waitcnt lgkmcnt(0)
	v_lshlrev_b32_e32 v2, 3, v1
	v_ashrrev_i32_e32 v3, 31, v2
	v_ashrrev_i32_e32 v1, 31, v0
	v_lshl_add_u64 v[6:7], v[2:3], 2, s[62:63]
	v_lshlrev_b64 v[4:5], 7, v[0:1]
	v_lshl_add_u64 v[4:5], v[6:7], 0, v[4:5]
	v_mov_b32_e32 v100, v0
	v_ashrrev_i32_e32 v101, 31, v100
	v_lshlrev_b64 v[100:101], 7, v[100:101]
	v_lshl_add_u64 v[100:101], v[6:7], 0, v[100:101]
	global_load_dwordx4 v[104:107], v[100:101], off offset:16
	global_load_dwordx4 v[108:111], v[100:101], off
	v_add_u32_e32 v100, 0x10, v0
	v_ashrrev_i32_e32 v101, 31, v100
	v_lshlrev_b64 v[100:101], 7, v[100:101]
	v_lshl_add_u64 v[100:101], v[6:7], 0, v[100:101]
	global_load_dwordx4 v[124:127], v[100:101], off offset:16
	global_load_dwordx4 v[180:183], v[100:101], off
	v_add_u32_e32 v100, 0x20, v0
	v_ashrrev_i32_e32 v101, 31, v100
	v_lshlrev_b64 v[100:101], 7, v[100:101]
	v_lshl_add_u64 v[100:101], v[6:7], 0, v[100:101]
	global_load_dwordx4 v[184:187], v[100:101], off offset:16
	global_load_dwordx4 v[188:191], v[100:101], off
	v_add_u32_e32 v100, 0x30, v0
	v_ashrrev_i32_e32 v101, 31, v100
	v_lshlrev_b64 v[100:101], 7, v[100:101]
	v_lshl_add_u64 v[100:101], v[6:7], 0, v[100:101]
	global_load_dwordx4 v[192:195], v[100:101], off offset:16
	global_load_dwordx4 v[196:199], v[100:101], off
	v_add_u32_e32 v100, 0x80, v0
	v_ashrrev_i32_e32 v101, 31, v100
	v_lshlrev_b64 v[100:101], 7, v[100:101]
	v_lshl_add_u64 v[100:101], v[6:7], 0, v[100:101]
	global_load_dwordx4 v[200:203], v[100:101], off offset:16
	global_load_dwordx4 v[204:207], v[100:101], off
	v_add_u32_e32 v100, 0x90, v0
	v_ashrrev_i32_e32 v101, 31, v100
	v_lshlrev_b64 v[100:101], 7, v[100:101]
	v_lshl_add_u64 v[100:101], v[6:7], 0, v[100:101]
	global_load_dwordx4 v[208:211], v[100:101], off offset:16
	global_load_dwordx4 v[212:215], v[100:101], off
	v_add_u32_e32 v100, 0xa0, v0
	v_ashrrev_i32_e32 v101, 31, v100
	v_lshlrev_b64 v[100:101], 7, v[100:101]
	v_lshl_add_u64 v[100:101], v[6:7], 0, v[100:101]
	global_load_dwordx4 v[216:219], v[100:101], off offset:16
	global_load_dwordx4 v[220:223], v[100:101], off
	v_add_u32_e32 v100, 0xb0, v0
	v_ashrrev_i32_e32 v101, 31, v100
	v_lshlrev_b64 v[100:101], 7, v[100:101]
	v_lshl_add_u64 v[100:101], v[6:7], 0, v[100:101]
	global_load_dwordx4 v[224:227], v[100:101], off offset:16
	global_load_dwordx4 v[228:231], v[100:101], off
	s_waitcnt vmcnt(0)
	v_mov_b32_e32 v8, v104
	v_mov_b32_e32 v9, v105
	v_mov_b32_e32 v10, v106
	v_mov_b32_e32 v11, v107
	v_mov_b32_e32 v12, v108
	v_mov_b32_e32 v13, v109
	v_mov_b32_e32 v14, v110
	v_mov_b32_e32 v15, v111
	v_add_u32_e32 v56, 0x90, v0
	v_ashrrev_i32_e32 v57, 31, v56
	v_add_u32_e32 v58, 0xa0, v0
	v_ashrrev_i32_e32 v59, 31, v58
	v_add_u32_e32 v60, 0xb0, v0
	v_ashrrev_i32_e32 v61, 31, v60
	s_lshl_b32 s10, s73, 8
	s_or_b32 s10, s10, s66
	v_add_u32_e32 v2, s10, v2
	v_ashrrev_i32_e32 v3, 31, v2
	v_readlane_b32 s10, v255, 48
	v_readlane_b32 s11, v255, 49
	s_andn2_b64 vcc, exec, s[6:7]
	v_mov_b32_e32 v5, v8
	v_mov_b32_e32 v4, v12
	v_mov_b32_e32 v16, v14
	v_mov_b32_e32 v17, v10
	v_pk_add_f32 v[4:5], v[4:5], v[16:17]
	v_add_f32_e32 v8, v13, v15
	v_add_f32_e32 v10, v9, v11
	v_mov_b32_e32 v9, v4
	v_mov_b32_e32 v11, v5
	v_pk_add_f32 v[4:5], v[8:9], v[10:11]
	s_nop 0
	v_mov_b32_e32 v8, v4
	v_mov_b32_e32 v9, v5
	s_nop 1
	v_permlane16_swap_b32 v8, v4
	v_permlane16_swap_b32 v9, v5
	s_nop 0
	v_pk_add_f32 v[48:49], v[4:5], v[8:9]
	v_add_u32_e32 v4, 16, v0
	v_ashrrev_i32_e32 v5, 31, v4
	v_lshlrev_b64 v[8:9], 7, v[4:5]
	v_lshl_add_u64 v[12:13], v[6:7], 0, v[8:9]
	v_mov_b32_e32 v8, v124
	v_mov_b32_e32 v9, v125
	v_mov_b32_e32 v10, v126
	v_mov_b32_e32 v11, v127
	s_nop 0
	v_mov_b32_e32 v12, v180
	v_mov_b32_e32 v13, v181
	v_mov_b32_e32 v14, v182
	v_mov_b32_e32 v15, v183
	ds_bpermute_b32 v51, v157, v49
	ds_bpermute_b32 v50, v157, v48
	v_mov_b32_e32 v17, v8
	v_mov_b32_e32 v16, v12
	v_mov_b32_e32 v18, v14
	v_mov_b32_e32 v19, v10
	v_pk_add_f32 v[16:17], v[16:17], v[18:19]
	v_add_f32_e32 v8, v13, v15
	v_add_f32_e32 v10, v9, v11
	v_mov_b32_e32 v9, v16
	v_mov_b32_e32 v11, v17
	v_pk_add_f32 v[8:9], v[8:9], v[10:11]
	s_nop 0
	v_mov_b32_e32 v10, v8
	v_mov_b32_e32 v11, v9
	s_nop 1
	v_permlane16_swap_b32 v10, v8
	v_permlane16_swap_b32 v11, v9
	s_nop 0
	v_pk_add_f32 v[52:53], v[8:9], v[10:11]
	v_add_u32_e32 v8, 32, v0
	v_ashrrev_i32_e32 v9, 31, v8
	v_lshlrev_b64 v[10:11], 7, v[8:9]
	v_lshl_add_u64 v[14:15], v[6:7], 0, v[10:11]
	v_mov_b32_e32 v10, v184
	v_mov_b32_e32 v11, v185
	v_mov_b32_e32 v12, v186
	v_mov_b32_e32 v13, v187
	s_nop 0
	v_mov_b32_e32 v14, v188
	v_mov_b32_e32 v15, v189
	v_mov_b32_e32 v16, v190
	v_mov_b32_e32 v17, v191
	ds_bpermute_b32 v55, v157, v53
	ds_bpermute_b32 v54, v157, v52
	v_mov_b32_e32 v19, v10
	v_mov_b32_e32 v18, v14
	v_mov_b32_e32 v20, v16
	v_mov_b32_e32 v21, v12
	v_pk_add_f32 v[18:19], v[18:19], v[20:21]
	v_add_f32_e32 v10, v15, v17
	v_add_f32_e32 v12, v11, v13
	v_mov_b32_e32 v11, v18
	v_mov_b32_e32 v13, v19
	v_pk_add_f32 v[10:11], v[10:11], v[12:13]
	s_nop 0
	v_mov_b32_e32 v12, v10
	v_mov_b32_e32 v13, v11
	s_nop 1
	v_permlane16_swap_b32 v12, v10
	v_permlane16_swap_b32 v13, v11
	s_nop 0
	v_pk_add_f32 v[64:65], v[10:11], v[12:13]
	v_add_u32_e32 v10, 48, v0
	v_ashrrev_i32_e32 v11, 31, v10
	v_lshlrev_b64 v[12:13], 7, v[10:11]
	v_lshl_add_u64 v[16:17], v[6:7], 0, v[12:13]
	v_mov_b32_e32 v12, v192
	v_mov_b32_e32 v13, v193
	v_mov_b32_e32 v14, v194
	v_mov_b32_e32 v15, v195
	s_nop 0
	v_mov_b32_e32 v16, v196
	v_mov_b32_e32 v17, v197
	v_mov_b32_e32 v18, v198
	v_mov_b32_e32 v19, v199
	ds_bpermute_b32 v67, v157, v65
	ds_bpermute_b32 v66, v157, v64
	v_mov_b32_e32 v21, v12
	v_mov_b32_e32 v20, v16
	v_mov_b32_e32 v22, v18
	v_mov_b32_e32 v23, v14
	v_pk_add_f32 v[20:21], v[20:21], v[22:23]
	v_add_f32_e32 v12, v17, v19
	v_add_f32_e32 v14, v13, v15
	v_mov_b32_e32 v13, v20
	v_mov_b32_e32 v15, v21
	v_pk_add_f32 v[12:13], v[12:13], v[14:15]
	s_nop 0
	v_mov_b32_e32 v14, v12
	v_mov_b32_e32 v15, v13
	s_nop 1
	v_permlane16_swap_b32 v14, v12
	v_permlane16_swap_b32 v15, v13
	s_nop 0
	v_pk_add_f32 v[68:69], v[12:13], v[14:15]
	v_add_u32_e32 v12, 0x80, v0
	v_ashrrev_i32_e32 v13, 31, v12
	v_lshlrev_b64 v[14:15], 7, v[12:13]
	v_lshl_add_u64 v[18:19], v[6:7], 0, v[14:15]
	v_mov_b32_e32 v14, v200
	v_mov_b32_e32 v15, v201
	v_mov_b32_e32 v16, v202
	v_mov_b32_e32 v17, v203
	s_nop 0
	v_mov_b32_e32 v18, v204
	v_mov_b32_e32 v19, v205
	v_mov_b32_e32 v20, v206
	v_mov_b32_e32 v21, v207
	v_lshlrev_b64 v[0:1], 11, v[0:1]
	v_lshl_add_u64 v[0:1], s[44:45], 0, v[0:1]
	ds_bpermute_b32 v71, v157, v69
	ds_bpermute_b32 v70, v157, v68
	v_mov_b32_e32 v23, v14
	v_mov_b32_e32 v22, v18
	v_mov_b32_e32 v24, v20
	v_mov_b32_e32 v25, v16
	v_pk_add_f32 v[22:23], v[22:23], v[24:25]
	v_add_f32_e32 v14, v19, v21
	v_add_f32_e32 v16, v15, v17
	v_mov_b32_e32 v15, v22
	v_mov_b32_e32 v17, v23
	v_pk_add_f32 v[14:15], v[14:15], v[16:17]
	s_nop 0
	v_mov_b32_e32 v16, v14
	v_mov_b32_e32 v17, v15
	s_nop 1
	v_permlane16_swap_b32 v16, v14
	v_permlane16_swap_b32 v17, v15
	s_nop 0
	v_pk_add_f32 v[112:113], v[14:15], v[16:17]
	v_lshlrev_b64 v[14:15], 7, v[56:57]
	v_lshl_add_u64 v[18:19], v[6:7], 0, v[14:15]
	v_mov_b32_e32 v14, v208
	v_mov_b32_e32 v15, v209
	v_mov_b32_e32 v16, v210
	v_mov_b32_e32 v17, v211
	s_nop 0
	v_mov_b32_e32 v18, v212
	v_mov_b32_e32 v19, v213
	v_mov_b32_e32 v20, v214
	v_mov_b32_e32 v21, v215
	ds_bpermute_b32 v115, v157, v113
	ds_bpermute_b32 v114, v157, v112
	v_mov_b32_e32 v23, v14
	v_mov_b32_e32 v22, v18
	v_mov_b32_e32 v24, v20
	v_mov_b32_e32 v25, v16
	v_pk_add_f32 v[22:23], v[22:23], v[24:25]
	v_add_f32_e32 v14, v19, v21
	v_add_f32_e32 v16, v15, v17
	v_mov_b32_e32 v15, v22
	v_mov_b32_e32 v17, v23
	v_pk_add_f32 v[14:15], v[14:15], v[16:17]
	s_nop 0
	v_mov_b32_e32 v16, v14
	v_mov_b32_e32 v17, v15
	s_nop 1
	v_permlane16_swap_b32 v16, v14
	v_permlane16_swap_b32 v17, v15
	s_nop 0
	v_pk_add_f32 v[116:117], v[14:15], v[16:17]
	v_lshlrev_b64 v[14:15], 7, v[58:59]
	v_lshl_add_u64 v[18:19], v[6:7], 0, v[14:15]
	v_mov_b32_e32 v14, v216
	v_mov_b32_e32 v15, v217
	v_mov_b32_e32 v16, v218
	v_mov_b32_e32 v17, v219
	s_nop 0
	v_mov_b32_e32 v18, v220
	v_mov_b32_e32 v19, v221
	v_mov_b32_e32 v20, v222
	v_mov_b32_e32 v21, v223
	ds_bpermute_b32 v119, v157, v117
	ds_bpermute_b32 v118, v157, v116
	v_mov_b32_e32 v23, v14
	v_mov_b32_e32 v22, v18
	v_mov_b32_e32 v24, v20
	v_mov_b32_e32 v25, v16
	v_pk_add_f32 v[22:23], v[22:23], v[24:25]
	v_add_f32_e32 v14, v19, v21
	v_add_f32_e32 v16, v15, v17
	v_mov_b32_e32 v15, v22
	v_mov_b32_e32 v17, v23
	v_pk_add_f32 v[14:15], v[14:15], v[16:17]
	s_nop 0
	v_mov_b32_e32 v16, v14
	v_mov_b32_e32 v17, v15
	s_nop 1
	v_permlane16_swap_b32 v16, v14
	v_permlane16_swap_b32 v17, v15
	s_nop 0
	v_pk_add_f32 v[120:121], v[14:15], v[16:17]
	v_lshlrev_b64 v[14:15], 7, v[60:61]
	v_lshl_add_u64 v[6:7], v[6:7], 0, v[14:15]
	v_mov_b32_e32 v14, v224
	v_mov_b32_e32 v15, v225
	v_mov_b32_e32 v16, v226
	v_mov_b32_e32 v17, v227
	v_mov_b32_e32 v18, v228
	v_mov_b32_e32 v19, v229
	v_mov_b32_e32 v20, v230
	v_mov_b32_e32 v21, v231
	ds_bpermute_b32 v123, v157, v121
	ds_bpermute_b32 v122, v157, v120
	v_mov_b32_e32 v7, v14
	v_mov_b32_e32 v6, v18
	v_mov_b32_e32 v22, v20
	v_mov_b32_e32 v23, v16
	v_pk_add_f32 v[6:7], v[6:7], v[22:23]
	v_add_f32_e32 v14, v19, v21
	v_add_f32_e32 v16, v15, v17
	v_mov_b32_e32 v15, v6
	v_mov_b32_e32 v17, v7
	v_pk_add_f32 v[6:7], v[14:15], v[16:17]
	s_nop 0
	v_mov_b32_e32 v14, v6
	v_mov_b32_e32 v15, v7
	s_nop 1
	v_permlane16_swap_b32 v14, v6
	v_permlane16_swap_b32 v15, v7
	s_nop 0
	v_pk_add_f32 v[124:125], v[6:7], v[14:15]
	v_lshlrev_b64 v[6:7], 2, v[2:3]
	v_lshlrev_b64 v[2:3], 1, v[2:3]
	v_lshl_add_u64 v[74:75], v[0:1], 0, v[2:3]
	v_lshlrev_b64 v[0:1], 11, v[4:5]
	v_lshl_add_u64 v[0:1], s[44:45], 0, v[0:1]
	v_lshl_add_u64 v[76:77], v[0:1], 0, v[2:3]
	v_lshlrev_b64 v[0:1], 11, v[8:9]
	v_lshl_add_u64 v[0:1], s[44:45], 0, v[0:1]
	v_lshl_add_u64 v[78:79], v[0:1], 0, v[2:3]
	v_lshlrev_b64 v[0:1], 11, v[10:11]
	v_lshl_add_u64 v[0:1], s[44:45], 0, v[0:1]
	v_lshl_add_u64 v[80:81], v[0:1], 0, v[2:3]
	v_lshlrev_b64 v[0:1], 11, v[12:13]
	v_lshl_add_u64 v[0:1], s[44:45], 0, v[0:1]
	v_lshl_add_u64 v[146:147], v[0:1], 0, v[2:3]
	v_lshlrev_b64 v[0:1], 11, v[56:57]
	v_lshl_add_u64 v[0:1], s[44:45], 0, v[0:1]
	v_lshl_add_u64 v[56:57], v[0:1], 0, v[2:3]
	v_lshlrev_b64 v[0:1], 11, v[58:59]
	v_lshl_add_u64 v[0:1], s[44:45], 0, v[0:1]
	v_lshl_add_u64 v[58:59], v[0:1], 0, v[2:3]
	v_lshlrev_b64 v[0:1], 11, v[60:61]
	v_lshl_add_u64 v[0:1], s[44:45], 0, v[0:1]
	v_lshl_add_u64 v[62:63], s[10:11], 0, v[6:7]
	v_lshl_add_u64 v[72:73], s[0:1], 0, v[6:7]
	v_lshl_add_u64 v[148:149], v[0:1], 0, v[2:3]
	global_load_dwordx4 v[36:39], v[62:63], off offset:16
	global_load_dwordx4 v[44:47], v[62:63], off
	global_load_dwordx4 v[32:35], v[72:73], off offset:16
	global_load_dwordx4 v[40:43], v[72:73], off
	global_load_dwordx4 v[28:31], v[74:75], off
	global_load_dwordx4 v[24:27], v[76:77], off
	global_load_dwordx4 v[20:23], v[78:79], off
	global_load_dwordx4 v[16:19], v[80:81], off
	global_load_dwordx4 v[12:15], v[146:147], off
	global_load_dwordx4 v[8:11], v[56:57], off
	global_load_dwordx4 v[4:7], v[58:59], off
	global_load_dwordx4 v[0:3], v[148:149], off
	global_load_dwordx4 v[104:107], v[62:63], off offset:528
	global_load_dwordx4 v[108:111], v[62:63], off offset:512
	global_load_dwordx4 v[96:99], v[72:73], off offset:528
	global_load_dwordx4 v[100:103], v[72:73], off offset:512
	global_load_dwordx4 v[92:95], v[74:75], off offset:256
	global_load_dwordx4 v[88:91], v[76:77], off offset:256
	global_load_dwordx4 v[84:87], v[78:79], off offset:256
	s_nop 0
	global_load_dwordx4 v[80:83], v[80:81], off offset:256
	s_nop 0
	global_load_dwordx4 v[76:79], v[146:147], off offset:256
	global_load_dwordx4 v[72:75], v[56:57], off offset:256
	global_load_dwordx4 v[60:63], v[58:59], off offset:256
	s_nop 0
	global_load_dwordx4 v[56:59], v[148:149], off offset:256
	ds_bpermute_b32 v127, v157, v125
	ds_bpermute_b32 v126, v157, v124
	s_cbranch_vccnz .LBB0_1677
	s_barrier
	s_branch .LBB0_1677

.LBB0_2361:
	v_readlane_b32 s0, v255, 32
	v_readlane_b32 s1, v255, 33
	s_and_b64 vcc, exec, s[0:1]
	s_cbranch_vccnz .LBB0_2397
	v_ashrrev_i32_e32 v2, 31, v0
	v_lshrrev_b32_e32 v2, 26, v2
	v_add_u32_e32 v2, v0, v2
	v_ashrrev_i32_e32 v137, 6, v2
	v_bfe_i32 v2, v0, 27, 1
	v_lshlrev_b32_e32 v1, 4, v0
	v_lshrrev_b32_e32 v2, 22, v2
	v_add_u32_e32 v2, v1, v2
	v_and_b32_e32 v2, 0xfffffc00, v2
	v_sub_u32_e32 v2, v1, v2
	v_lshrrev_b32_e32 v3, 4, v2
	v_bitop3_b32 v2, v3, v2, 32 bitop3:0x6c
	v_ashrrev_i32_e32 v4, 31, v2
	v_lshrrev_b32_e32 v4, 26, v4
	v_add_u32_e32 v4, v2, v4
	v_lshlrev_b32_e32 v3, 3, v137
	v_ashrrev_i32_e32 v147, 6, v4
	v_and_b32_e32 v4, 0xc0, v4
	v_and_b32_e32 v3, -16, v3
	v_sub_u32_e32 v2, v2, v4
	v_mov_b32_e32 v4, 1
	v_add_u32_e32 v3, v147, v3
	v_ashrrev_i16_sdwa v2, v4, sext(v2) dst_sel:DWORD dst_unused:UNUSED_PAD src0_sel:DWORD src1_sel:BYTE_0
	v_lshlrev_b32_e32 v5, 5, v137
	v_bfe_i32 v149, v2, 0, 16
	v_lshlrev_b32_e32 v2, 1, v3
	v_lshrrev_b32_e32 v6, 2, v3
	v_and_b32_e32 v7, 3, v147
	s_mov_b32 s6, 0x1fffe0
	v_and_b32_e32 v5, 32, v5
	v_and_b32_e32 v2, 24, v2
	v_and_b32_e32 v6, 4, v6
	v_and_or_b32 v7, v3, s6, v7
	v_or3_b32 v2, v7, v6, v2
	v_add_lshl_u32 v5, v5, v149, 1
	v_add_u32_e32 v1, 0x2000, v1
	v_lshl_add_u32 v130, v2, 11, v5
	v_ashrrev_i32_e32 v2, 31, v1
	v_lshrrev_b32_e32 v2, 22, v2
	v_add_u32_e32 v2, v1, v2
	v_ashrrev_i32_e32 v161, 10, v2
	v_mul_i32_i24_e32 v2, 0x400, v161
	v_sub_u32_e32 v1, v1, v2
	v_lshrrev_b32_e32 v2, 4, v1
	v_bitop3_b32 v1, v2, v1, 32 bitop3:0x6c
	v_lshl_add_u32 v128, v3, 11, v5
	v_ashrrev_i32_e32 v3, 31, v1
	v_lshrrev_b32_e32 v3, 26, v3
	v_add_u32_e32 v3, v1, v3
	v_lshlrev_b32_e32 v2, 3, v161
	v_ashrrev_i32_e32 v163, 6, v3
	v_and_b32_e32 v3, 0xc0, v3
	v_and_b32_e32 v2, -16, v2
	v_sub_u32_e32 v1, v1, v3
	v_add_u32_e32 v2, v163, v2
	v_ashrrev_i16_sdwa v1, v4, sext(v1) dst_sel:DWORD dst_unused:UNUSED_PAD src0_sel:DWORD src1_sel:BYTE_0
	v_lshlrev_b32_e32 v5, 5, v161
	v_bfe_i32 v165, v1, 0, 16
	v_lshlrev_b32_e32 v1, 1, v2
	v_lshrrev_b32_e32 v3, 2, v2
	v_and_b32_e32 v4, 3, v163
	v_and_b32_e32 v5, 32, v5
	v_and_b32_e32 v1, 24, v1
	v_and_b32_e32 v3, 4, v3
	v_and_or_b32 v4, v2, s6, v4
	v_bfe_u32 v151, v0, 4, 2
	v_or3_b32 v1, v4, v3, v1
	v_add_lshl_u32 v3, v5, v165, 1
	v_and_b32_e32 v153, 15, v0
	v_lshl_add_u32 v134, v1, 11, v3
	v_mov_b32_e32 v0, v153
	v_mov_b32_e32 v1, v151
	v_lshl_add_u32 v132, v2, 11, v3
	v_lshlrev_b32_e32 v2, 3, v1
	v_mbcnt_lo_u32_b32 v1, -1, 0
	v_mbcnt_hi_u32_b32 v1, -1, v1
	v_and_b32_e32 v5, 64, v1
	v_xor_b32_e32 v4, 16, v1
	v_add_u32_e32 v5, 64, v5
	s_add_u32 s0, s30, 0x1000
	v_cmp_lt_i32_e32 vcc, v4, v5
	s_addc_u32 s1, s31, 0
	s_ashr_i32 s5, s10, 6
	s_ashr_i32 s11, s10, 8
	v_cndmask_b32_e32 v4, v1, v4, vcc
	s_and_b32 s4, s5, 3
	s_lshl_b32 s9, s5, 10
	s_lshl_b32 s13, s11, 6
	s_lshl_b32 s5, s96, 8
	v_lshlrev_b32_e32 v155, 2, v4
	v_xor_b32_e32 v4, 32, v1
	s_add_i32 s5, s5, s13
	v_cmp_lt_i32_e32 vcc, v4, v5
	v_add_u32_e32 v0, s5, v0
	v_ashrrev_i32_e32 v3, 31, v2
	v_cndmask_b32_e32 v1, v1, v4, vcc
	v_lshlrev_b32_e32 v157, 2, v1
	v_ashrrev_i32_e32 v1, 31, v0
	v_lshl_add_u64 v[4:5], v[2:3], 2, s[76:77]
	v_lshlrev_b64 v[6:7], 7, v[0:1]
	v_lshl_add_u64 v[10:11], v[4:5], 0, v[6:7]
	v_mov_b32_e32 v184, v0
	v_ashrrev_i32_e32 v185, 31, v184
	v_lshlrev_b64 v[184:185], 7, v[184:185]
	v_lshl_add_u64 v[184:185], v[4:5], 0, v[184:185]
	global_load_dwordx4 v[188:191], v[184:185], off offset:16
	global_load_dwordx4 v[192:195], v[184:185], off
	v_add_u32_e32 v184, 0x10, v0
	v_ashrrev_i32_e32 v185, 31, v184
	v_lshlrev_b64 v[184:185], 7, v[184:185]
	v_lshl_add_u64 v[184:185], v[4:5], 0, v[184:185]
	global_load_dwordx4 v[196:199], v[184:185], off offset:16
	global_load_dwordx4 v[200:203], v[184:185], off
	v_add_u32_e32 v184, 0x20, v0
	v_ashrrev_i32_e32 v185, 31, v184
	v_lshlrev_b64 v[184:185], 7, v[184:185]
	v_lshl_add_u64 v[184:185], v[4:5], 0, v[184:185]
	global_load_dwordx4 v[204:207], v[184:185], off offset:16
	global_load_dwordx4 v[208:211], v[184:185], off
	v_add_u32_e32 v184, 0x30, v0
	v_ashrrev_i32_e32 v185, 31, v184
	v_lshlrev_b64 v[184:185], 7, v[184:185]
	v_lshl_add_u64 v[184:185], v[4:5], 0, v[184:185]
	global_load_dwordx4 v[212:215], v[184:185], off offset:16
	global_load_dwordx4 v[216:219], v[184:185], off
	v_add_u32_e32 v184, 0x80, v0
	v_ashrrev_i32_e32 v185, 31, v184
	v_lshlrev_b64 v[184:185], 7, v[184:185]
	v_lshl_add_u64 v[184:185], v[4:5], 0, v[184:185]
	global_load_dwordx4 v[220:223], v[184:185], off offset:16
	global_load_dwordx4 v[224:227], v[184:185], off
	v_add_u32_e32 v184, 0x90, v0
	v_ashrrev_i32_e32 v185, 31, v184
	v_lshlrev_b64 v[184:185], 7, v[184:185]
	v_lshl_add_u64 v[184:185], v[4:5], 0, v[184:185]
	global_load_dwordx4 v[228:231], v[184:185], off offset:16
	global_load_dwordx4 v[232:235], v[184:185], off
	v_add_u32_e32 v184, 0xa0, v0
	v_ashrrev_i32_e32 v185, 31, v184
	v_lshlrev_b64 v[184:185], 7, v[184:185]
	v_lshl_add_u64 v[184:185], v[4:5], 0, v[184:185]
	global_load_dwordx4 v[236:239], v[184:185], off offset:16
	global_load_dwordx4 v[240:243], v[184:185], off
	v_add_u32_e32 v184, 0xb0, v0
	v_ashrrev_i32_e32 v185, 31, v184
	v_lshlrev_b64 v[184:185], 7, v[184:185]
	v_lshl_add_u64 v[184:185], v[4:5], 0, v[184:185]
	global_load_dwordx4 v[244:247], v[184:185], off offset:16
	global_load_dwordx4 v[248:251], v[184:185], off
	s_waitcnt vmcnt(0)
	v_mov_b32_e32 v6, v188
	v_mov_b32_e32 v7, v189
	v_mov_b32_e32 v8, v190
	v_mov_b32_e32 v9, v191
	s_nop 0
	v_mov_b32_e32 v10, v192
	v_mov_b32_e32 v11, v193
	v_mov_b32_e32 v12, v194
	v_mov_b32_e32 v13, v195
	s_waitcnt vmcnt(3)
	v_add_u32_e32 v56, 0x90, v0
	v_ashrrev_i32_e32 v57, 31, v56
	v_add_u32_e32 v58, 0xa0, v0
	v_ashrrev_i32_e32 v59, 31, v58
	s_waitcnt vmcnt(2)
	v_add_u32_e32 v60, 0xb0, v0
	v_ashrrev_i32_e32 v61, 31, v60
	s_lshl_b32 s66, s4, 5
	s_lshl_b32 s6, s94, 8
	s_or_b32 s6, s6, s66
	v_add_u32_e32 v2, s6, v2
	v_ashrrev_i32_e32 v3, 31, v2
	s_ashr_i32 s97, s96, 31
	s_lshl_b64 s[6:7], s[96:97], 19
	v_readlane_b32 s14, v255, 34
	v_readlane_b32 s34, v255, 36
	s_cmp_gt_i32 s96, 63
	v_readlane_b32 s15, v255, 35
	v_readlane_b32 s35, v255, 37
	s_cselect_b32 s8, s35, s15
	s_cselect_b32 s12, s34, s14
	s_ashr_i32 s95, s94, 31
	s_lshl_b64 s[14:15], s[94:95], 19
	s_add_u32 s40, s12, s14
	s_addc_u32 s41, s8, s15
	s_add_i32 s67, s9, 0
	s_add_i32 m0, s67, 0x10000
	v_mov_b32_e32 v136, 0
	v_mov_b32_e32 v131, v136
	v_mov_b32_e32 v135, v136
	v_mov_b32_e32 v129, v136
	v_mov_b32_e32 v133, v136
	s_mov_b32 s5, 0
	v_mov_b32_e32 v15, v6
	v_mov_b32_e32 v14, v10
	v_mov_b32_e32 v16, v12
	v_mov_b32_e32 v17, v8
	v_pk_add_f32 v[14:15], v[14:15], v[16:17]
	v_add_f32_e32 v6, v11, v13
	v_add_f32_e32 v8, v7, v9
	v_mov_b32_e32 v7, v14
	v_mov_b32_e32 v9, v15
	v_pk_add_f32 v[6:7], v[6:7], v[8:9]
	s_nop 0
	v_mov_b32_e32 v8, v6
	v_mov_b32_e32 v9, v7
	s_nop 1
	v_permlane16_swap_b32 v8, v6
	v_permlane16_swap_b32 v9, v7
	s_nop 0
	v_pk_add_f32 v[48:49], v[6:7], v[8:9]
	v_add_u32_e32 v6, 16, v0
	v_ashrrev_i32_e32 v7, 31, v6
	v_lshlrev_b64 v[8:9], 7, v[6:7]
	v_lshl_add_u64 v[12:13], v[4:5], 0, v[8:9]
	v_mov_b32_e32 v8, v196
	v_mov_b32_e32 v9, v197
	v_mov_b32_e32 v10, v198
	v_mov_b32_e32 v11, v199
	s_nop 0
	v_mov_b32_e32 v12, v200
	v_mov_b32_e32 v13, v201
	v_mov_b32_e32 v14, v202
	v_mov_b32_e32 v15, v203
	ds_bpermute_b32 v51, v157, v49
	ds_bpermute_b32 v50, v157, v48
	v_mov_b32_e32 v17, v8
	v_mov_b32_e32 v16, v12
	v_mov_b32_e32 v18, v14
	v_mov_b32_e32 v19, v10
	v_pk_add_f32 v[16:17], v[16:17], v[18:19]
	v_add_f32_e32 v8, v13, v15
	v_add_f32_e32 v10, v9, v11
	v_mov_b32_e32 v9, v16
	v_mov_b32_e32 v11, v17
	v_pk_add_f32 v[8:9], v[8:9], v[10:11]
	s_nop 0
	v_mov_b32_e32 v10, v8
	v_mov_b32_e32 v11, v9
	s_nop 1
	v_permlane16_swap_b32 v10, v8
	v_permlane16_swap_b32 v11, v9
	s_nop 0
	v_pk_add_f32 v[52:53], v[8:9], v[10:11]
	v_add_u32_e32 v8, 32, v0
	v_ashrrev_i32_e32 v9, 31, v8
	v_lshlrev_b64 v[10:11], 7, v[8:9]
	v_lshl_add_u64 v[14:15], v[4:5], 0, v[10:11]
	v_mov_b32_e32 v10, v204
	v_mov_b32_e32 v11, v205
	v_mov_b32_e32 v12, v206
	v_mov_b32_e32 v13, v207
	s_nop 0
	v_mov_b32_e32 v14, v208
	v_mov_b32_e32 v15, v209
	v_mov_b32_e32 v16, v210
	v_mov_b32_e32 v17, v211
	ds_bpermute_b32 v55, v157, v53
	ds_bpermute_b32 v54, v157, v52
	v_mov_b32_e32 v19, v10
	v_mov_b32_e32 v18, v14
	v_mov_b32_e32 v20, v16
	v_mov_b32_e32 v21, v12
	v_pk_add_f32 v[18:19], v[18:19], v[20:21]
	v_add_f32_e32 v10, v15, v17
	v_add_f32_e32 v12, v11, v13
	v_mov_b32_e32 v11, v18
	v_mov_b32_e32 v13, v19
	v_pk_add_f32 v[10:11], v[10:11], v[12:13]
	s_nop 0
	v_mov_b32_e32 v12, v10
	v_mov_b32_e32 v13, v11
	s_nop 1
	v_permlane16_swap_b32 v12, v10
	v_permlane16_swap_b32 v13, v11
	s_nop 0
	v_pk_add_f32 v[64:65], v[10:11], v[12:13]
	v_add_u32_e32 v10, 48, v0
	v_ashrrev_i32_e32 v11, 31, v10
	v_lshlrev_b64 v[12:13], 7, v[10:11]
	v_lshl_add_u64 v[16:17], v[4:5], 0, v[12:13]
	v_mov_b32_e32 v12, v212
	v_mov_b32_e32 v13, v213
	v_mov_b32_e32 v14, v214
	v_mov_b32_e32 v15, v215
	s_nop 0
	v_mov_b32_e32 v16, v216
	v_mov_b32_e32 v17, v217
	v_mov_b32_e32 v18, v218
	v_mov_b32_e32 v19, v219
	ds_bpermute_b32 v67, v157, v65
	ds_bpermute_b32 v66, v157, v64
	v_mov_b32_e32 v21, v12
	v_mov_b32_e32 v20, v16
	v_mov_b32_e32 v22, v18
	v_mov_b32_e32 v23, v14
	v_pk_add_f32 v[20:21], v[20:21], v[22:23]
	v_add_f32_e32 v12, v17, v19
	v_add_f32_e32 v14, v13, v15
	v_mov_b32_e32 v13, v20
	v_mov_b32_e32 v15, v21
	v_pk_add_f32 v[12:13], v[12:13], v[14:15]
	s_nop 0
	v_mov_b32_e32 v14, v12
	v_mov_b32_e32 v15, v13
	s_nop 1
	v_permlane16_swap_b32 v14, v12
	v_permlane16_swap_b32 v15, v13
	s_nop 0
	v_pk_add_f32 v[68:69], v[12:13], v[14:15]
	v_add_u32_e32 v12, 0x80, v0
	v_ashrrev_i32_e32 v13, 31, v12
	v_lshlrev_b64 v[14:15], 7, v[12:13]
	v_lshl_add_u64 v[18:19], v[4:5], 0, v[14:15]
	v_mov_b32_e32 v14, v220
	v_mov_b32_e32 v15, v221
	v_mov_b32_e32 v16, v222
	v_mov_b32_e32 v17, v223
	s_nop 0
	v_mov_b32_e32 v18, v224
	v_mov_b32_e32 v19, v225
	v_mov_b32_e32 v20, v226
	v_mov_b32_e32 v21, v227
	v_lshlrev_b64 v[0:1], 11, v[0:1]
	v_lshl_add_u64 v[0:1], s[44:45], 0, v[0:1]
	ds_bpermute_b32 v71, v157, v69
	ds_bpermute_b32 v70, v157, v68
	v_mov_b32_e32 v23, v14
	v_mov_b32_e32 v22, v18
	v_mov_b32_e32 v24, v20
	v_mov_b32_e32 v25, v16
	v_pk_add_f32 v[22:23], v[22:23], v[24:25]
	v_add_f32_e32 v14, v19, v21
	v_add_f32_e32 v16, v15, v17
	v_mov_b32_e32 v15, v22
	v_mov_b32_e32 v17, v23
	v_pk_add_f32 v[14:15], v[14:15], v[16:17]
	s_nop 0
	v_mov_b32_e32 v16, v14
	v_mov_b32_e32 v17, v15
	s_nop 1
	v_permlane16_swap_b32 v16, v14
	v_permlane16_swap_b32 v17, v15
	s_nop 0
	v_pk_add_f32 v[112:113], v[14:15], v[16:17]
	v_lshlrev_b64 v[14:15], 7, v[56:57]
	v_lshl_add_u64 v[18:19], v[4:5], 0, v[14:15]
	v_mov_b32_e32 v14, v228
	v_mov_b32_e32 v15, v229
	v_mov_b32_e32 v16, v230
	v_mov_b32_e32 v17, v231
	s_nop 0
	v_mov_b32_e32 v18, v232
	v_mov_b32_e32 v19, v233
	v_mov_b32_e32 v20, v234
	v_mov_b32_e32 v21, v235
	ds_bpermute_b32 v115, v157, v113
	ds_bpermute_b32 v114, v157, v112
	v_mov_b32_e32 v23, v14
	v_mov_b32_e32 v22, v18
	v_mov_b32_e32 v24, v20
	v_mov_b32_e32 v25, v16
	v_pk_add_f32 v[22:23], v[22:23], v[24:25]
	v_add_f32_e32 v14, v19, v21
	v_add_f32_e32 v16, v15, v17
	v_mov_b32_e32 v15, v22
	v_mov_b32_e32 v17, v23
	v_pk_add_f32 v[14:15], v[14:15], v[16:17]
	s_nop 0
	v_mov_b32_e32 v16, v14
	v_mov_b32_e32 v17, v15
	s_nop 1
	v_permlane16_swap_b32 v16, v14
	v_permlane16_swap_b32 v17, v15
	s_nop 0
	v_pk_add_f32 v[116:117], v[14:15], v[16:17]
	v_lshlrev_b64 v[14:15], 7, v[58:59]
	v_lshl_add_u64 v[18:19], v[4:5], 0, v[14:15]
	v_mov_b32_e32 v14, v236
	v_mov_b32_e32 v15, v237
	v_mov_b32_e32 v16, v238
	v_mov_b32_e32 v17, v239
	s_nop 0
	v_mov_b32_e32 v18, v240
	v_mov_b32_e32 v19, v241
	v_mov_b32_e32 v20, v242
	v_mov_b32_e32 v21, v243
	ds_bpermute_b32 v119, v157, v117
	ds_bpermute_b32 v118, v157, v116
	v_mov_b32_e32 v23, v14
	v_mov_b32_e32 v22, v18
	v_mov_b32_e32 v24, v20
	v_mov_b32_e32 v25, v16
	v_pk_add_f32 v[22:23], v[22:23], v[24:25]
	v_add_f32_e32 v14, v19, v21
	v_add_f32_e32 v16, v15, v17
	v_mov_b32_e32 v15, v22
	v_mov_b32_e32 v17, v23
	v_pk_add_f32 v[14:15], v[14:15], v[16:17]
	s_nop 0
	v_mov_b32_e32 v16, v14
	v_mov_b32_e32 v17, v15
	s_nop 1
	v_permlane16_swap_b32 v16, v14
	v_permlane16_swap_b32 v17, v15
	s_nop 0
	v_pk_add_f32 v[120:121], v[14:15], v[16:17]
	v_lshlrev_b64 v[14:15], 7, v[60:61]
	v_lshl_add_u64 v[4:5], v[4:5], 0, v[14:15]
	v_mov_b32_e32 v14, v244
	v_mov_b32_e32 v15, v245
	v_mov_b32_e32 v16, v246
	v_mov_b32_e32 v17, v247
	v_mov_b32_e32 v18, v248
	v_mov_b32_e32 v19, v249
	v_mov_b32_e32 v20, v250
	v_mov_b32_e32 v21, v251
	ds_bpermute_b32 v123, v157, v121
	ds_bpermute_b32 v122, v157, v120
	v_mov_b32_e32 v5, v14
	v_mov_b32_e32 v4, v18
	v_mov_b32_e32 v22, v20
	v_mov_b32_e32 v23, v16
	v_pk_add_f32 v[4:5], v[4:5], v[22:23]
	v_add_f32_e32 v14, v19, v21
	v_add_f32_e32 v16, v15, v17
	v_mov_b32_e32 v15, v4
	v_mov_b32_e32 v17, v5
	v_pk_add_f32 v[4:5], v[14:15], v[16:17]
	s_nop 0
	v_mov_b32_e32 v14, v4
	v_mov_b32_e32 v15, v5
	s_nop 1
	v_permlane16_swap_b32 v14, v4
	v_permlane16_swap_b32 v15, v5
	s_nop 0
	v_pk_add_f32 v[124:125], v[4:5], v[14:15]
	v_lshlrev_b64 v[4:5], 2, v[2:3]
	v_lshlrev_b64 v[2:3], 1, v[2:3]
	v_lshl_add_u64 v[74:75], v[0:1], 0, v[2:3]
	v_lshlrev_b64 v[0:1], 11, v[6:7]
	v_lshl_add_u64 v[0:1], s[44:45], 0, v[0:1]
	v_lshl_add_u64 v[76:77], v[0:1], 0, v[2:3]
	v_lshlrev_b64 v[0:1], 11, v[8:9]
	v_lshl_add_u64 v[0:1], s[44:45], 0, v[0:1]
	v_lshl_add_u64 v[78:79], v[0:1], 0, v[2:3]
	v_lshlrev_b64 v[0:1], 11, v[10:11]
	v_lshl_add_u64 v[0:1], s[44:45], 0, v[0:1]
	v_lshl_add_u64 v[80:81], v[0:1], 0, v[2:3]
	v_lshlrev_b64 v[0:1], 11, v[12:13]
	v_lshl_add_u64 v[0:1], s[44:45], 0, v[0:1]
	v_lshl_add_u64 v[138:139], v[0:1], 0, v[2:3]
	v_lshlrev_b64 v[0:1], 11, v[56:57]
	v_lshl_add_u64 v[0:1], s[44:45], 0, v[0:1]
	v_lshl_add_u64 v[56:57], v[0:1], 0, v[2:3]
	v_lshlrev_b64 v[0:1], 11, v[58:59]
	v_lshl_add_u64 v[0:1], s[44:45], 0, v[0:1]
	v_lshl_add_u64 v[58:59], v[0:1], 0, v[2:3]
	v_lshlrev_b64 v[0:1], 11, v[60:61]
	v_lshl_add_u64 v[0:1], s[44:45], 0, v[0:1]
	v_lshl_add_u64 v[62:63], s[70:71], 0, v[4:5]
	v_lshl_add_u64 v[72:73], s[0:1], 0, v[4:5]
	v_lshl_add_u64 v[140:141], v[0:1], 0, v[2:3]
	global_load_dwordx4 v[36:39], v[62:63], off offset:16
	global_load_dwordx4 v[44:47], v[62:63], off
	global_load_dwordx4 v[32:35], v[72:73], off offset:16
	global_load_dwordx4 v[40:43], v[72:73], off
	global_load_dwordx4 v[28:31], v[74:75], off
	global_load_dwordx4 v[24:27], v[76:77], off
	global_load_dwordx4 v[20:23], v[78:79], off
	global_load_dwordx4 v[16:19], v[80:81], off
	global_load_dwordx4 v[12:15], v[138:139], off
	global_load_dwordx4 v[8:11], v[56:57], off
	global_load_dwordx4 v[4:7], v[58:59], off
	global_load_dwordx4 v[0:3], v[140:141], off
	global_load_dwordx4 v[100:103], v[62:63], off offset:528
	global_load_dwordx4 v[108:111], v[62:63], off offset:512
	global_load_dwordx4 v[96:99], v[72:73], off offset:528
	global_load_dwordx4 v[104:107], v[72:73], off offset:512
	global_load_dwordx4 v[92:95], v[74:75], off offset:256
	global_load_dwordx4 v[88:91], v[76:77], off offset:256
	global_load_dwordx4 v[84:87], v[78:79], off offset:256
	s_nop 0
	global_load_dwordx4 v[80:83], v[80:81], off offset:256
	s_nop 0
	global_load_dwordx4 v[76:79], v[138:139], off offset:256
	global_load_dwordx4 v[72:75], v[56:57], off offset:256
	global_load_dwordx4 v[60:63], v[58:59], off offset:256
	s_nop 0
	global_load_dwordx4 v[56:59], v[140:141], off offset:256
	ds_bpermute_b32 v127, v157, v125
	global_load_lds_dwordx4 v130, s[40:41]
	s_add_i32 m0, s67, 0x12000
	s_add_u32 s14, s40, 0x40000
	global_load_lds_dwordx4 v134, s[40:41]
	s_addc_u32 s15, s41, 0
	s_add_i32 m0, s67, 0x14000
	ds_bpermute_b32 v126, v157, v124
	global_load_lds_dwordx4 v130, s[14:15]
	s_add_i32 m0, s67, 0x16000
	s_add_u32 s74, s42, s6
	s_addc_u32 s75, s43, s7
	s_add_i32 s68, s67, 0x2000
	global_load_lds_dwordx4 v134, s[14:15]
	s_mov_b32 m0, s67
	s_add_u32 s6, s74, 0x40000
	global_load_lds_dwordx4 v128, s[74:75]
	s_mov_b32 m0, s68
	s_addc_u32 s7, s75, 0
	s_add_i32 s69, s67, 0x4000
	global_load_lds_dwordx4 v132, s[74:75]
	s_mov_b32 m0, s69
	s_add_i32 s90, s67, 0x6000
	global_load_lds_dwordx4 v128, s[6:7]
	s_mov_b32 m0, s90
	s_cmp_eq_u32 s11, 1
	global_load_lds_dwordx4 v132, s[6:7]
	v_lshl_add_u64 v[138:139], s[40:41], 0, v[130:131]
	v_lshl_add_u64 v[140:141], s[40:41], 0, v[134:135]
	v_lshl_add_u64 v[142:143], s[74:75], 0, v[128:129]
	v_lshl_add_u64 v[144:145], s[74:75], 0, v[132:133]
	s_cselect_b64 s[6:7], -1, 0
	s_cmp_lg_u32 s11, 1
	s_cbranch_scc1 .LBB0_2364
	s_barrier

.LBB0_2393:
	s_or_b64 exec, exec, s[46:47]
	s_andn2_b64 vcc, exec, s[10:11]
	s_mov_b64 s[10:11], -1
	s_cbranch_vccnz .LBB0_2366
	v_mov_b32_e32 v0, v153
	v_mov_b32_e32 v1, v151
	s_lshl_b32 s10, s60, 8
	s_add_i32 s10, s10, s13
	v_add_u32_e32 v0, s10, v0
	s_waitcnt lgkmcnt(0)
	v_lshlrev_b32_e32 v2, 3, v1
	v_ashrrev_i32_e32 v3, 31, v2
	v_ashrrev_i32_e32 v1, 31, v0
	v_lshl_add_u64 v[6:7], v[2:3], 2, s[76:77]
	v_lshlrev_b64 v[4:5], 7, v[0:1]
	v_lshl_add_u64 v[4:5], v[6:7], 0, v[4:5]
	v_mov_b32_e32 v100, v0
	v_ashrrev_i32_e32 v101, 31, v100
	v_lshlrev_b64 v[100:101], 7, v[100:101]
	v_lshl_add_u64 v[100:101], v[6:7], 0, v[100:101]
	global_load_dwordx4 v[104:107], v[100:101], off offset:16
	global_load_dwordx4 v[108:111], v[100:101], off
	v_add_u32_e32 v100, 0x10, v0
	v_ashrrev_i32_e32 v101, 31, v100
	v_lshlrev_b64 v[100:101], 7, v[100:101]
	v_lshl_add_u64 v[100:101], v[6:7], 0, v[100:101]
	global_load_dwordx4 v[124:127], v[100:101], off offset:16
	global_load_dwordx4 v[180:183], v[100:101], off
	v_add_u32_e32 v100, 0x20, v0
	v_ashrrev_i32_e32 v101, 31, v100
	v_lshlrev_b64 v[100:101], 7, v[100:101]
	v_lshl_add_u64 v[100:101], v[6:7], 0, v[100:101]
	global_load_dwordx4 v[184:187], v[100:101], off offset:16
	global_load_dwordx4 v[188:191], v[100:101], off
	v_add_u32_e32 v100, 0x30, v0
	v_ashrrev_i32_e32 v101, 31, v100
	v_lshlrev_b64 v[100:101], 7, v[100:101]
	v_lshl_add_u64 v[100:101], v[6:7], 0, v[100:101]
	global_load_dwordx4 v[192:195], v[100:101], off offset:16
	global_load_dwordx4 v[196:199], v[100:101], off
	v_add_u32_e32 v100, 0x80, v0
	v_ashrrev_i32_e32 v101, 31, v100
	v_lshlrev_b64 v[100:101], 7, v[100:101]
	v_lshl_add_u64 v[100:101], v[6:7], 0, v[100:101]
	global_load_dwordx4 v[200:203], v[100:101], off offset:16
	global_load_dwordx4 v[204:207], v[100:101], off
	v_add_u32_e32 v100, 0x90, v0
	v_ashrrev_i32_e32 v101, 31, v100
	v_lshlrev_b64 v[100:101], 7, v[100:101]
	v_lshl_add_u64 v[100:101], v[6:7], 0, v[100:101]
	global_load_dwordx4 v[208:211], v[100:101], off offset:16
	global_load_dwordx4 v[212:215], v[100:101], off
	v_add_u32_e32 v100, 0xa0, v0
	v_ashrrev_i32_e32 v101, 31, v100
	v_lshlrev_b64 v[100:101], 7, v[100:101]
	v_lshl_add_u64 v[100:101], v[6:7], 0, v[100:101]
	global_load_dwordx4 v[216:219], v[100:101], off offset:16
	global_load_dwordx4 v[220:223], v[100:101], off
	v_add_u32_e32 v100, 0xb0, v0
	v_ashrrev_i32_e32 v101, 31, v100
	v_lshlrev_b64 v[100:101], 7, v[100:101]
	v_lshl_add_u64 v[100:101], v[6:7], 0, v[100:101]
	global_load_dwordx4 v[224:227], v[100:101], off offset:16
	global_load_dwordx4 v[228:231], v[100:101], off
	s_waitcnt vmcnt(0)
	v_mov_b32_e32 v8, v104
	v_mov_b32_e32 v9, v105
	v_mov_b32_e32 v10, v106
	v_mov_b32_e32 v11, v107
	v_mov_b32_e32 v12, v108
	v_mov_b32_e32 v13, v109
	v_mov_b32_e32 v14, v110
	v_mov_b32_e32 v15, v111
	v_add_u32_e32 v56, 0x90, v0
	v_ashrrev_i32_e32 v57, 31, v56
	v_add_u32_e32 v58, 0xa0, v0
	v_ashrrev_i32_e32 v59, 31, v58
	v_add_u32_e32 v60, 0xb0, v0
	v_ashrrev_i32_e32 v61, 31, v60
	s_lshl_b32 s10, s36, 8
	s_or_b32 s10, s10, s66
	v_add_u32_e32 v2, s10, v2
	v_ashrrev_i32_e32 v3, 31, v2
	v_readlane_b32 s10, v255, 48
	v_readlane_b32 s11, v255, 49
	s_andn2_b64 vcc, exec, s[6:7]
	v_mov_b32_e32 v5, v8
	v_mov_b32_e32 v4, v12
	v_mov_b32_e32 v16, v14
	v_mov_b32_e32 v17, v10
	v_pk_add_f32 v[4:5], v[4:5], v[16:17]
	v_add_f32_e32 v8, v13, v15
	v_add_f32_e32 v10, v9, v11
	v_mov_b32_e32 v9, v4
	v_mov_b32_e32 v11, v5
	v_pk_add_f32 v[4:5], v[8:9], v[10:11]
	s_nop 0
	v_mov_b32_e32 v8, v4
	v_mov_b32_e32 v9, v5
	s_nop 1
	v_permlane16_swap_b32 v8, v4
	v_permlane16_swap_b32 v9, v5
	s_nop 0
	v_pk_add_f32 v[48:49], v[4:5], v[8:9]
	v_add_u32_e32 v4, 16, v0
	v_ashrrev_i32_e32 v5, 31, v4
	v_lshlrev_b64 v[8:9], 7, v[4:5]
	v_lshl_add_u64 v[12:13], v[6:7], 0, v[8:9]
	v_mov_b32_e32 v8, v124
	v_mov_b32_e32 v9, v125
	v_mov_b32_e32 v10, v126
	v_mov_b32_e32 v11, v127
	s_nop 0
	v_mov_b32_e32 v12, v180
	v_mov_b32_e32 v13, v181
	v_mov_b32_e32 v14, v182
	v_mov_b32_e32 v15, v183
	ds_bpermute_b32 v51, v157, v49
	ds_bpermute_b32 v50, v157, v48
	v_mov_b32_e32 v17, v8
	v_mov_b32_e32 v16, v12
	v_mov_b32_e32 v18, v14
	v_mov_b32_e32 v19, v10
	v_pk_add_f32 v[16:17], v[16:17], v[18:19]
	v_add_f32_e32 v8, v13, v15
	v_add_f32_e32 v10, v9, v11
	v_mov_b32_e32 v9, v16
	v_mov_b32_e32 v11, v17
	v_pk_add_f32 v[8:9], v[8:9], v[10:11]
	s_nop 0
	v_mov_b32_e32 v10, v8
	v_mov_b32_e32 v11, v9
	s_nop 1
	v_permlane16_swap_b32 v10, v8
	v_permlane16_swap_b32 v11, v9
	s_nop 0
	v_pk_add_f32 v[52:53], v[8:9], v[10:11]
	v_add_u32_e32 v8, 32, v0
	v_ashrrev_i32_e32 v9, 31, v8
	v_lshlrev_b64 v[10:11], 7, v[8:9]
	v_lshl_add_u64 v[14:15], v[6:7], 0, v[10:11]
	v_mov_b32_e32 v10, v184
	v_mov_b32_e32 v11, v185
	v_mov_b32_e32 v12, v186
	v_mov_b32_e32 v13, v187
	s_nop 0
	v_mov_b32_e32 v14, v188
	v_mov_b32_e32 v15, v189
	v_mov_b32_e32 v16, v190
	v_mov_b32_e32 v17, v191
	ds_bpermute_b32 v55, v157, v53
	ds_bpermute_b32 v54, v157, v52
	v_mov_b32_e32 v19, v10
	v_mov_b32_e32 v18, v14
	v_mov_b32_e32 v20, v16
	v_mov_b32_e32 v21, v12
	v_pk_add_f32 v[18:19], v[18:19], v[20:21]
	v_add_f32_e32 v10, v15, v17
	v_add_f32_e32 v12, v11, v13
	v_mov_b32_e32 v11, v18
	v_mov_b32_e32 v13, v19
	v_pk_add_f32 v[10:11], v[10:11], v[12:13]
	s_nop 0
	v_mov_b32_e32 v12, v10
	v_mov_b32_e32 v13, v11
	s_nop 1
	v_permlane16_swap_b32 v12, v10
	v_permlane16_swap_b32 v13, v11
	s_nop 0
	v_pk_add_f32 v[64:65], v[10:11], v[12:13]
	v_add_u32_e32 v10, 48, v0
	v_ashrrev_i32_e32 v11, 31, v10
	v_lshlrev_b64 v[12:13], 7, v[10:11]
	v_lshl_add_u64 v[16:17], v[6:7], 0, v[12:13]
	v_mov_b32_e32 v12, v192
	v_mov_b32_e32 v13, v193
	v_mov_b32_e32 v14, v194
	v_mov_b32_e32 v15, v195
	s_nop 0
	v_mov_b32_e32 v16, v196
	v_mov_b32_e32 v17, v197
	v_mov_b32_e32 v18, v198
	v_mov_b32_e32 v19, v199
	ds_bpermute_b32 v67, v157, v65
	ds_bpermute_b32 v66, v157, v64
	v_mov_b32_e32 v21, v12
	v_mov_b32_e32 v20, v16
	v_mov_b32_e32 v22, v18
	v_mov_b32_e32 v23, v14
	v_pk_add_f32 v[20:21], v[20:21], v[22:23]
	v_add_f32_e32 v12, v17, v19
	v_add_f32_e32 v14, v13, v15
	v_mov_b32_e32 v13, v20
	v_mov_b32_e32 v15, v21
	v_pk_add_f32 v[12:13], v[12:13], v[14:15]
	s_nop 0
	v_mov_b32_e32 v14, v12
	v_mov_b32_e32 v15, v13
	s_nop 1
	v_permlane16_swap_b32 v14, v12
	v_permlane16_swap_b32 v15, v13
	s_nop 0
	v_pk_add_f32 v[68:69], v[12:13], v[14:15]
	v_add_u32_e32 v12, 0x80, v0
	v_ashrrev_i32_e32 v13, 31, v12
	v_lshlrev_b64 v[14:15], 7, v[12:13]
	v_lshl_add_u64 v[18:19], v[6:7], 0, v[14:15]
	v_mov_b32_e32 v14, v200
	v_mov_b32_e32 v15, v201
	v_mov_b32_e32 v16, v202
	v_mov_b32_e32 v17, v203
	s_nop 0
	v_mov_b32_e32 v18, v204
	v_mov_b32_e32 v19, v205
	v_mov_b32_e32 v20, v206
	v_mov_b32_e32 v21, v207
	v_lshlrev_b64 v[0:1], 11, v[0:1]
	v_lshl_add_u64 v[0:1], s[44:45], 0, v[0:1]
	ds_bpermute_b32 v71, v157, v69
	ds_bpermute_b32 v70, v157, v68
	v_mov_b32_e32 v23, v14
	v_mov_b32_e32 v22, v18
	v_mov_b32_e32 v24, v20
	v_mov_b32_e32 v25, v16
	v_pk_add_f32 v[22:23], v[22:23], v[24:25]
	v_add_f32_e32 v14, v19, v21
	v_add_f32_e32 v16, v15, v17
	v_mov_b32_e32 v15, v22
	v_mov_b32_e32 v17, v23
	v_pk_add_f32 v[14:15], v[14:15], v[16:17]
	s_nop 0
	v_mov_b32_e32 v16, v14
	v_mov_b32_e32 v17, v15
	s_nop 1
	v_permlane16_swap_b32 v16, v14
	v_permlane16_swap_b32 v17, v15
	s_nop 0
	v_pk_add_f32 v[112:113], v[14:15], v[16:17]
	v_lshlrev_b64 v[14:15], 7, v[56:57]
	v_lshl_add_u64 v[18:19], v[6:7], 0, v[14:15]
	v_mov_b32_e32 v14, v208
	v_mov_b32_e32 v15, v209
	v_mov_b32_e32 v16, v210
	v_mov_b32_e32 v17, v211
	s_nop 0
	v_mov_b32_e32 v18, v212
	v_mov_b32_e32 v19, v213
	v_mov_b32_e32 v20, v214
	v_mov_b32_e32 v21, v215
	ds_bpermute_b32 v115, v157, v113
	ds_bpermute_b32 v114, v157, v112
	v_mov_b32_e32 v23, v14
	v_mov_b32_e32 v22, v18
	v_mov_b32_e32 v24, v20
	v_mov_b32_e32 v25, v16
	v_pk_add_f32 v[22:23], v[22:23], v[24:25]
	v_add_f32_e32 v14, v19, v21
	v_add_f32_e32 v16, v15, v17
	v_mov_b32_e32 v15, v22
	v_mov_b32_e32 v17, v23
	v_pk_add_f32 v[14:15], v[14:15], v[16:17]
	s_nop 0
	v_mov_b32_e32 v16, v14
	v_mov_b32_e32 v17, v15
	s_nop 1
	v_permlane16_swap_b32 v16, v14
	v_permlane16_swap_b32 v17, v15
	s_nop 0
	v_pk_add_f32 v[116:117], v[14:15], v[16:17]
	v_lshlrev_b64 v[14:15], 7, v[58:59]
	v_lshl_add_u64 v[18:19], v[6:7], 0, v[14:15]
	v_mov_b32_e32 v14, v216
	v_mov_b32_e32 v15, v217
	v_mov_b32_e32 v16, v218
	v_mov_b32_e32 v17, v219
	s_nop 0
	v_mov_b32_e32 v18, v220
	v_mov_b32_e32 v19, v221
	v_mov_b32_e32 v20, v222
	v_mov_b32_e32 v21, v223
	ds_bpermute_b32 v119, v157, v117
	ds_bpermute_b32 v118, v157, v116
	v_mov_b32_e32 v23, v14
	v_mov_b32_e32 v22, v18
	v_mov_b32_e32 v24, v20
	v_mov_b32_e32 v25, v16
	v_pk_add_f32 v[22:23], v[22:23], v[24:25]
	v_add_f32_e32 v14, v19, v21
	v_add_f32_e32 v16, v15, v17
	v_mov_b32_e32 v15, v22
	v_mov_b32_e32 v17, v23
	v_pk_add_f32 v[14:15], v[14:15], v[16:17]
	s_nop 0
	v_mov_b32_e32 v16, v14
	v_mov_b32_e32 v17, v15
	s_nop 1
	v_permlane16_swap_b32 v16, v14
	v_permlane16_swap_b32 v17, v15
	s_nop 0
	v_pk_add_f32 v[120:121], v[14:15], v[16:17]
	v_lshlrev_b64 v[14:15], 7, v[60:61]
	v_lshl_add_u64 v[6:7], v[6:7], 0, v[14:15]
	v_mov_b32_e32 v14, v224
	v_mov_b32_e32 v15, v225
	v_mov_b32_e32 v16, v226
	v_mov_b32_e32 v17, v227
	v_mov_b32_e32 v18, v228
	v_mov_b32_e32 v19, v229
	v_mov_b32_e32 v20, v230
	v_mov_b32_e32 v21, v231
	ds_bpermute_b32 v123, v157, v121
	ds_bpermute_b32 v122, v157, v120
	v_mov_b32_e32 v7, v14
	v_mov_b32_e32 v6, v18
	v_mov_b32_e32 v22, v20
	v_mov_b32_e32 v23, v16
	v_pk_add_f32 v[6:7], v[6:7], v[22:23]
	v_add_f32_e32 v14, v19, v21
	v_add_f32_e32 v16, v15, v17
	v_mov_b32_e32 v15, v6
	v_mov_b32_e32 v17, v7
	v_pk_add_f32 v[6:7], v[14:15], v[16:17]
	s_nop 0
	v_mov_b32_e32 v14, v6
	v_mov_b32_e32 v15, v7
	s_nop 1
	v_permlane16_swap_b32 v14, v6
	v_permlane16_swap_b32 v15, v7
	s_nop 0
	v_pk_add_f32 v[124:125], v[6:7], v[14:15]
	v_lshlrev_b64 v[6:7], 2, v[2:3]
	v_lshlrev_b64 v[2:3], 1, v[2:3]
	v_lshl_add_u64 v[74:75], v[0:1], 0, v[2:3]
	v_lshlrev_b64 v[0:1], 11, v[4:5]
	v_lshl_add_u64 v[0:1], s[44:45], 0, v[0:1]
	v_lshl_add_u64 v[76:77], v[0:1], 0, v[2:3]
	v_lshlrev_b64 v[0:1], 11, v[8:9]
	v_lshl_add_u64 v[0:1], s[44:45], 0, v[0:1]
	v_lshl_add_u64 v[78:79], v[0:1], 0, v[2:3]
	v_lshlrev_b64 v[0:1], 11, v[10:11]
	v_lshl_add_u64 v[0:1], s[44:45], 0, v[0:1]
	v_lshl_add_u64 v[80:81], v[0:1], 0, v[2:3]
	v_lshlrev_b64 v[0:1], 11, v[12:13]
	v_lshl_add_u64 v[0:1], s[44:45], 0, v[0:1]
	v_lshl_add_u64 v[146:147], v[0:1], 0, v[2:3]
	v_lshlrev_b64 v[0:1], 11, v[56:57]
	v_lshl_add_u64 v[0:1], s[44:45], 0, v[0:1]
	v_lshl_add_u64 v[56:57], v[0:1], 0, v[2:3]
	v_lshlrev_b64 v[0:1], 11, v[58:59]
	v_lshl_add_u64 v[0:1], s[44:45], 0, v[0:1]
	v_lshl_add_u64 v[58:59], v[0:1], 0, v[2:3]
	v_lshlrev_b64 v[0:1], 11, v[60:61]
	v_lshl_add_u64 v[0:1], s[44:45], 0, v[0:1]
	v_lshl_add_u64 v[62:63], s[10:11], 0, v[6:7]
	v_lshl_add_u64 v[72:73], s[0:1], 0, v[6:7]
	v_lshl_add_u64 v[148:149], v[0:1], 0, v[2:3]
	global_load_dwordx4 v[36:39], v[62:63], off offset:16
	global_load_dwordx4 v[44:47], v[62:63], off
	global_load_dwordx4 v[32:35], v[72:73], off offset:16
	global_load_dwordx4 v[40:43], v[72:73], off
	global_load_dwordx4 v[28:31], v[74:75], off
	global_load_dwordx4 v[24:27], v[76:77], off
	global_load_dwordx4 v[20:23], v[78:79], off
	global_load_dwordx4 v[16:19], v[80:81], off
	global_load_dwordx4 v[12:15], v[146:147], off
	global_load_dwordx4 v[8:11], v[56:57], off
	global_load_dwordx4 v[4:7], v[58:59], off
	global_load_dwordx4 v[0:3], v[148:149], off
	global_load_dwordx4 v[104:107], v[62:63], off offset:528
	global_load_dwordx4 v[108:111], v[62:63], off offset:512
	global_load_dwordx4 v[96:99], v[72:73], off offset:528
	global_load_dwordx4 v[100:103], v[72:73], off offset:512
	global_load_dwordx4 v[92:95], v[74:75], off offset:256
	global_load_dwordx4 v[88:91], v[76:77], off offset:256
	global_load_dwordx4 v[84:87], v[78:79], off offset:256
	s_nop 0
	global_load_dwordx4 v[80:83], v[80:81], off offset:256
	s_nop 0
	global_load_dwordx4 v[76:79], v[146:147], off offset:256
	global_load_dwordx4 v[72:75], v[56:57], off offset:256
	global_load_dwordx4 v[60:63], v[58:59], off offset:256
	s_nop 0
	global_load_dwordx4 v[56:59], v[148:149], off offset:256
	ds_bpermute_b32 v127, v157, v125
	ds_bpermute_b32 v126, v157, v124
	s_cbranch_vccnz .LBB0_2365
	s_barrier
	s_branch .LBB0_2365

.LBB0_2536:
	v_readlane_b32 s0, v255, 32
	v_readlane_b32 s1, v255, 33
	s_and_b64 vcc, exec, s[0:1]
	s_cbranch_vccnz .LBB0_2576
	v_ashrrev_i32_e32 v2, 31, v0
	v_lshrrev_b32_e32 v2, 26, v2
	v_add_u32_e32 v2, v0, v2
	v_ashrrev_i32_e32 v137, 6, v2
	v_bfe_i32 v2, v0, 27, 1
	v_lshlrev_b32_e32 v1, 4, v0
	v_lshrrev_b32_e32 v2, 22, v2
	v_add_u32_e32 v2, v1, v2
	v_and_b32_e32 v2, 0xfffffc00, v2
	v_sub_u32_e32 v2, v1, v2
	v_lshrrev_b32_e32 v3, 4, v2
	v_bitop3_b32 v2, v3, v2, 32 bitop3:0x6c
	v_ashrrev_i32_e32 v4, 31, v2
	v_lshrrev_b32_e32 v4, 26, v4
	v_lshlrev_b32_e32 v3, 3, v137
	v_add_u32_e32 v4, v2, v4
	v_and_b32_e32 v3, -16, v3
	v_ashrrev_i32_e32 v149, 6, v4
	v_and_b32_e32 v4, 0xc0, v4
	v_add_u32_e32 v3, v149, v3
	v_lshlrev_b32_e32 v5, 5, v137
	v_sub_u32_e32 v2, v2, v4
	v_mov_b32_e32 v4, 1
	v_and_b32_e32 v147, 32, v5
	v_ashrrev_i16_sdwa v2, v4, sext(v2) dst_sel:DWORD dst_unused:UNUSED_PAD src0_sel:DWORD src1_sel:BYTE_0
	v_lshlrev_b32_e32 v5, 1, v3
	v_lshrrev_b32_e32 v6, 2, v3
	v_and_b32_e32 v7, 3, v149
	s_mov_b32 s6, 0xffffe0
	v_bfe_i32 v161, v2, 0, 16
	v_and_b32_e32 v5, 24, v5
	v_and_b32_e32 v6, 4, v6
	v_and_or_b32 v7, v3, s6, v7
	s_movk_i32 s11, 0xb00
	v_add_u32_e32 v2, v147, v161
	v_or3_b32 v5, v7, v6, v5
	v_mul_lo_u32 v3, v3, s11
	v_add_lshl_u32 v128, v2, v3, 1
	v_mul_u32_u24_e32 v3, 0xb00, v5
	v_add_u32_e32 v1, 0x2000, v1
	v_add_lshl_u32 v130, v3, v2, 1
	v_ashrrev_i32_e32 v2, 31, v1
	v_lshrrev_b32_e32 v2, 22, v2
	v_add_u32_e32 v2, v1, v2
	v_ashrrev_i32_e32 v163, 10, v2
	v_mul_i32_i24_e32 v2, 0x400, v163
	v_sub_u32_e32 v1, v1, v2
	v_lshrrev_b32_e32 v2, 4, v1
	v_bitop3_b32 v1, v2, v1, 32 bitop3:0x6c
	v_ashrrev_i32_e32 v3, 31, v1
	v_lshrrev_b32_e32 v3, 26, v3
	v_lshlrev_b32_e32 v2, 3, v163
	v_add_u32_e32 v3, v1, v3
	v_and_b32_e32 v2, -16, v2
	v_ashrrev_i32_e32 v165, 6, v3
	v_and_b32_e32 v3, 0xc0, v3
	v_add_u32_e32 v2, v165, v2
	v_lshlrev_b32_e32 v5, 5, v163
	v_sub_u32_e32 v1, v1, v3
	v_and_b32_e32 v167, 32, v5
	v_ashrrev_i16_sdwa v1, v4, sext(v1) dst_sel:DWORD dst_unused:UNUSED_PAD src0_sel:DWORD src1_sel:BYTE_0
	v_lshlrev_b32_e32 v3, 1, v2
	v_lshrrev_b32_e32 v4, 2, v2
	v_and_b32_e32 v5, 3, v165
	v_bfe_i32 v169, v1, 0, 16
	v_and_b32_e32 v3, 24, v3
	v_and_b32_e32 v4, 4, v4
	v_and_or_b32 v5, v2, s6, v5
	v_add_u32_e32 v1, v167, v169
	v_or3_b32 v3, v5, v4, v3
	v_mul_lo_u32 v2, v2, s11
	v_bfe_u32 v151, v0, 4, 2
	v_add_lshl_u32 v132, v1, v2, 1
	v_mul_u32_u24_e32 v2, 0xb00, v3
	v_and_b32_e32 v153, 15, v0
	v_add_lshl_u32 v134, v2, v1, 1
	v_mov_b32_e32 v0, v153
	v_mov_b32_e32 v1, v151
	s_add_u32 s0, s20, 0x2000
	v_lshlrev_b32_e32 v2, 3, v1
	v_mbcnt_lo_u32_b32 v1, -1, 0
	v_mbcnt_hi_u32_b32 v1, -1, v1
	v_and_b32_e32 v5, 64, v1
	v_xor_b32_e32 v4, 16, v1
	v_add_u32_e32 v5, 64, v5
	v_cmp_lt_i32_e32 vcc, v4, v5
	s_addc_u32 s1, s21, 0
	s_ashr_i32 s5, s10, 6
	s_ashr_i32 s12, s10, 8
	v_cndmask_b32_e32 v4, v1, v4, vcc
	s_and_b32 s4, s5, 3
	s_lshl_b32 s9, s5, 10
	s_lshl_b32 s15, s12, 6
	s_lshl_b32 s5, s80, 8
	v_lshlrev_b32_e32 v155, 2, v4
	v_xor_b32_e32 v4, 32, v1
	s_add_i32 s5, s5, s15
	v_cmp_lt_i32_e32 vcc, v4, v5
	v_add_u32_e32 v0, s5, v0
	v_ashrrev_i32_e32 v3, 31, v2
	v_cndmask_b32_e32 v1, v1, v4, vcc
	v_lshlrev_b32_e32 v157, 2, v1
	v_ashrrev_i32_e32 v1, 31, v0
	v_lshl_add_u64 v[4:5], v[2:3], 2, s[62:63]
	v_lshlrev_b64 v[6:7], 7, v[0:1]
	v_lshl_add_u64 v[10:11], v[4:5], 0, v[6:7]
	v_mov_b32_e32 v184, v0
	v_ashrrev_i32_e32 v185, 31, v184
	v_lshlrev_b64 v[184:185], 7, v[184:185]
	v_lshl_add_u64 v[184:185], v[4:5], 0, v[184:185]
	global_load_dwordx4 v[188:191], v[184:185], off offset:16
	global_load_dwordx4 v[192:195], v[184:185], off
	v_add_u32_e32 v184, 0x10, v0
	v_ashrrev_i32_e32 v185, 31, v184
	v_lshlrev_b64 v[184:185], 7, v[184:185]
	v_lshl_add_u64 v[184:185], v[4:5], 0, v[184:185]
	global_load_dwordx4 v[196:199], v[184:185], off offset:16
	global_load_dwordx4 v[200:203], v[184:185], off
	v_add_u32_e32 v184, 0x20, v0
	v_ashrrev_i32_e32 v185, 31, v184
	v_lshlrev_b64 v[184:185], 7, v[184:185]
	v_lshl_add_u64 v[184:185], v[4:5], 0, v[184:185]
	global_load_dwordx4 v[204:207], v[184:185], off offset:16
	global_load_dwordx4 v[208:211], v[184:185], off
	v_add_u32_e32 v184, 0x30, v0
	v_ashrrev_i32_e32 v185, 31, v184
	v_lshlrev_b64 v[184:185], 7, v[184:185]
	v_lshl_add_u64 v[184:185], v[4:5], 0, v[184:185]
	global_load_dwordx4 v[212:215], v[184:185], off offset:16
	global_load_dwordx4 v[216:219], v[184:185], off
	v_add_u32_e32 v184, 0x80, v0
	v_ashrrev_i32_e32 v185, 31, v184
	v_lshlrev_b64 v[184:185], 7, v[184:185]
	v_lshl_add_u64 v[184:185], v[4:5], 0, v[184:185]
	global_load_dwordx4 v[220:223], v[184:185], off offset:16
	global_load_dwordx4 v[224:227], v[184:185], off
	v_add_u32_e32 v184, 0x90, v0
	v_ashrrev_i32_e32 v185, 31, v184
	v_lshlrev_b64 v[184:185], 7, v[184:185]
	v_lshl_add_u64 v[184:185], v[4:5], 0, v[184:185]
	global_load_dwordx4 v[228:231], v[184:185], off offset:16
	global_load_dwordx4 v[232:235], v[184:185], off
	v_add_u32_e32 v184, 0xa0, v0
	v_ashrrev_i32_e32 v185, 31, v184
	v_lshlrev_b64 v[184:185], 7, v[184:185]
	v_lshl_add_u64 v[184:185], v[4:5], 0, v[184:185]
	global_load_dwordx4 v[236:239], v[184:185], off offset:16
	global_load_dwordx4 v[240:243], v[184:185], off
	v_add_u32_e32 v184, 0xb0, v0
	v_ashrrev_i32_e32 v185, 31, v184
	v_lshlrev_b64 v[184:185], 7, v[184:185]
	v_lshl_add_u64 v[184:185], v[4:5], 0, v[184:185]
	global_load_dwordx4 v[244:247], v[184:185], off offset:16
	global_load_dwordx4 v[248:251], v[184:185], off
	s_waitcnt vmcnt(0)
	v_mov_b32_e32 v6, v188
	v_mov_b32_e32 v7, v189
	v_mov_b32_e32 v8, v190
	v_mov_b32_e32 v9, v191
	s_nop 0
	v_mov_b32_e32 v10, v192
	v_mov_b32_e32 v11, v193
	v_mov_b32_e32 v12, v194
	v_mov_b32_e32 v13, v195
	v_add_u32_e32 v56, 0x90, v0
	v_ashrrev_i32_e32 v57, 31, v56
	v_add_u32_e32 v58, 0xa0, v0
	v_ashrrev_i32_e32 v59, 31, v58
	v_add_u32_e32 v60, 0xb0, v0
	v_ashrrev_i32_e32 v61, 31, v60
	s_lshl_b32 s66, s4, 5
	s_lshl_b32 s6, s79, 8
	s_or_b32 s6, s6, s66
	v_add_u32_e32 v2, s6, v2
	v_ashrrev_i32_e32 v3, 31, v2
	s_cmp_gt_i32 s80, 63
	v_readlane_b32 s34, v255, 44
	v_readlane_b32 s36, v255, 46
	v_readlane_b32 s35, v255, 45
	v_readlane_b32 s37, v255, 47
	s_cselect_b32 s7, s36, s34
	s_mul_i32 s34, s79, 0x160000
	s_cselect_b32 s6, s37, s35
	s_mul_hi_i32 s14, s79, 0x160000
	s_add_u32 s74, s7, s34
	s_addc_u32 s75, s6, s14
	s_add_i32 s67, s9, 0
	s_add_i32 m0, s67, 0x10000
	s_mul_i32 s13, s80, 0x160000
	s_mul_hi_i32 s8, s80, 0x160000
	v_mov_b32_e32 v136, 0
	v_mov_b32_e32 v131, v136
	v_mov_b32_e32 v135, v136
	v_mov_b32_e32 v129, v136
	v_mov_b32_e32 v133, v136
	s_mov_b32 s5, 0
	v_mov_b32_e32 v15, v6
	v_mov_b32_e32 v14, v10
	v_mov_b32_e32 v16, v12
	v_mov_b32_e32 v17, v8
	v_pk_add_f32 v[14:15], v[14:15], v[16:17]
	v_add_f32_e32 v6, v11, v13
	v_add_f32_e32 v8, v7, v9
	v_mov_b32_e32 v7, v14
	v_mov_b32_e32 v9, v15
	v_pk_add_f32 v[6:7], v[6:7], v[8:9]
	s_nop 0
	v_mov_b32_e32 v8, v6
	v_mov_b32_e32 v9, v7
	s_nop 1
	v_permlane16_swap_b32 v8, v6
	v_permlane16_swap_b32 v9, v7
	s_nop 0
	v_pk_add_f32 v[48:49], v[6:7], v[8:9]
	v_add_u32_e32 v6, 16, v0
	v_ashrrev_i32_e32 v7, 31, v6
	v_lshlrev_b64 v[8:9], 7, v[6:7]
	v_lshl_add_u64 v[12:13], v[4:5], 0, v[8:9]
	v_mov_b32_e32 v8, v196
	v_mov_b32_e32 v9, v197
	v_mov_b32_e32 v10, v198
	v_mov_b32_e32 v11, v199
	s_nop 0
	v_mov_b32_e32 v12, v200
	v_mov_b32_e32 v13, v201
	v_mov_b32_e32 v14, v202
	v_mov_b32_e32 v15, v203
	ds_bpermute_b32 v51, v157, v49
	ds_bpermute_b32 v50, v157, v48
	v_mov_b32_e32 v17, v8
	v_mov_b32_e32 v16, v12
	v_mov_b32_e32 v18, v14
	v_mov_b32_e32 v19, v10
	v_pk_add_f32 v[16:17], v[16:17], v[18:19]
	v_add_f32_e32 v8, v13, v15
	v_add_f32_e32 v10, v9, v11
	v_mov_b32_e32 v9, v16
	v_mov_b32_e32 v11, v17
	v_pk_add_f32 v[8:9], v[8:9], v[10:11]
	s_nop 0
	v_mov_b32_e32 v10, v8
	v_mov_b32_e32 v11, v9
	s_nop 1
	v_permlane16_swap_b32 v10, v8
	v_permlane16_swap_b32 v11, v9
	s_nop 0
	v_pk_add_f32 v[52:53], v[8:9], v[10:11]
	v_add_u32_e32 v8, 32, v0
	v_ashrrev_i32_e32 v9, 31, v8
	v_lshlrev_b64 v[10:11], 7, v[8:9]
	v_lshl_add_u64 v[14:15], v[4:5], 0, v[10:11]
	v_mov_b32_e32 v10, v204
	v_mov_b32_e32 v11, v205
	v_mov_b32_e32 v12, v206
	v_mov_b32_e32 v13, v207
	s_nop 0
	v_mov_b32_e32 v14, v208
	v_mov_b32_e32 v15, v209
	v_mov_b32_e32 v16, v210
	v_mov_b32_e32 v17, v211
	ds_bpermute_b32 v55, v157, v53
	ds_bpermute_b32 v54, v157, v52
	v_mov_b32_e32 v19, v10
	v_mov_b32_e32 v18, v14
	v_mov_b32_e32 v20, v16
	v_mov_b32_e32 v21, v12
	v_pk_add_f32 v[18:19], v[18:19], v[20:21]
	v_add_f32_e32 v10, v15, v17
	v_add_f32_e32 v12, v11, v13
	v_mov_b32_e32 v11, v18
	v_mov_b32_e32 v13, v19
	v_pk_add_f32 v[10:11], v[10:11], v[12:13]
	s_nop 0
	v_mov_b32_e32 v12, v10
	v_mov_b32_e32 v13, v11
	s_nop 1
	v_permlane16_swap_b32 v12, v10
	v_permlane16_swap_b32 v13, v11
	s_nop 0
	v_pk_add_f32 v[64:65], v[10:11], v[12:13]
	v_add_u32_e32 v10, 48, v0
	v_ashrrev_i32_e32 v11, 31, v10
	v_lshlrev_b64 v[12:13], 7, v[10:11]
	v_lshl_add_u64 v[16:17], v[4:5], 0, v[12:13]
	v_mov_b32_e32 v12, v212
	v_mov_b32_e32 v13, v213
	v_mov_b32_e32 v14, v214
	v_mov_b32_e32 v15, v215
	s_nop 0
	v_mov_b32_e32 v16, v216
	v_mov_b32_e32 v17, v217
	v_mov_b32_e32 v18, v218
	v_mov_b32_e32 v19, v219
	ds_bpermute_b32 v67, v157, v65
	ds_bpermute_b32 v66, v157, v64
	v_mov_b32_e32 v21, v12
	v_mov_b32_e32 v20, v16
	v_mov_b32_e32 v22, v18
	v_mov_b32_e32 v23, v14
	v_pk_add_f32 v[20:21], v[20:21], v[22:23]
	v_add_f32_e32 v12, v17, v19
	v_add_f32_e32 v14, v13, v15
	v_mov_b32_e32 v13, v20
	v_mov_b32_e32 v15, v21
	v_pk_add_f32 v[12:13], v[12:13], v[14:15]
	s_nop 0
	v_mov_b32_e32 v14, v12
	v_mov_b32_e32 v15, v13
	s_nop 1
	v_permlane16_swap_b32 v14, v12
	v_permlane16_swap_b32 v15, v13
	s_nop 0
	v_pk_add_f32 v[68:69], v[12:13], v[14:15]
	v_add_u32_e32 v12, 0x80, v0
	v_ashrrev_i32_e32 v13, 31, v12
	v_lshlrev_b64 v[14:15], 7, v[12:13]
	v_lshl_add_u64 v[18:19], v[4:5], 0, v[14:15]
	v_mov_b32_e32 v14, v220
	v_mov_b32_e32 v15, v221
	v_mov_b32_e32 v16, v222
	v_mov_b32_e32 v17, v223
	s_nop 0
	v_mov_b32_e32 v18, v224
	v_mov_b32_e32 v19, v225
	v_mov_b32_e32 v20, v226
	v_mov_b32_e32 v21, v227
	v_lshlrev_b64 v[0:1], 11, v[0:1]
	v_lshl_add_u64 v[0:1], s[44:45], 0, v[0:1]
	ds_bpermute_b32 v71, v157, v69
	ds_bpermute_b32 v70, v157, v68
	v_mov_b32_e32 v23, v14
	v_mov_b32_e32 v22, v18
	v_mov_b32_e32 v24, v20
	v_mov_b32_e32 v25, v16
	v_pk_add_f32 v[22:23], v[22:23], v[24:25]
	v_add_f32_e32 v14, v19, v21
	v_add_f32_e32 v16, v15, v17
	v_mov_b32_e32 v15, v22
	v_mov_b32_e32 v17, v23
	v_pk_add_f32 v[14:15], v[14:15], v[16:17]
	s_nop 0
	v_mov_b32_e32 v16, v14
	v_mov_b32_e32 v17, v15
	s_nop 1
	v_permlane16_swap_b32 v16, v14
	v_permlane16_swap_b32 v17, v15
	s_nop 0
	v_pk_add_f32 v[112:113], v[14:15], v[16:17]
	v_lshlrev_b64 v[14:15], 7, v[56:57]
	v_lshl_add_u64 v[18:19], v[4:5], 0, v[14:15]
	v_mov_b32_e32 v14, v228
	v_mov_b32_e32 v15, v229
	v_mov_b32_e32 v16, v230
	v_mov_b32_e32 v17, v231
	s_nop 0
	v_mov_b32_e32 v18, v232
	v_mov_b32_e32 v19, v233
	v_mov_b32_e32 v20, v234
	v_mov_b32_e32 v21, v235
	ds_bpermute_b32 v115, v157, v113
	ds_bpermute_b32 v114, v157, v112
	v_mov_b32_e32 v23, v14
	v_mov_b32_e32 v22, v18
	v_mov_b32_e32 v24, v20
	v_mov_b32_e32 v25, v16
	v_pk_add_f32 v[22:23], v[22:23], v[24:25]
	v_add_f32_e32 v14, v19, v21
	v_add_f32_e32 v16, v15, v17
	v_mov_b32_e32 v15, v22
	v_mov_b32_e32 v17, v23
	v_pk_add_f32 v[14:15], v[14:15], v[16:17]
	s_nop 0
	v_mov_b32_e32 v16, v14
	v_mov_b32_e32 v17, v15
	s_nop 1
	v_permlane16_swap_b32 v16, v14
	v_permlane16_swap_b32 v17, v15
	s_nop 0
	v_pk_add_f32 v[116:117], v[14:15], v[16:17]
	v_lshlrev_b64 v[14:15], 7, v[58:59]
	v_lshl_add_u64 v[18:19], v[4:5], 0, v[14:15]
	v_mov_b32_e32 v14, v236
	v_mov_b32_e32 v15, v237
	v_mov_b32_e32 v16, v238
	v_mov_b32_e32 v17, v239
	s_nop 0
	v_mov_b32_e32 v18, v240
	v_mov_b32_e32 v19, v241
	v_mov_b32_e32 v20, v242
	v_mov_b32_e32 v21, v243
	ds_bpermute_b32 v119, v157, v117
	ds_bpermute_b32 v118, v157, v116
	v_mov_b32_e32 v23, v14
	v_mov_b32_e32 v22, v18
	v_mov_b32_e32 v24, v20
	v_mov_b32_e32 v25, v16
	v_pk_add_f32 v[22:23], v[22:23], v[24:25]
	v_add_f32_e32 v14, v19, v21
	v_add_f32_e32 v16, v15, v17
	v_mov_b32_e32 v15, v22
	v_mov_b32_e32 v17, v23
	v_pk_add_f32 v[14:15], v[14:15], v[16:17]
	s_nop 0
	v_mov_b32_e32 v16, v14
	v_mov_b32_e32 v17, v15
	s_nop 1
	v_permlane16_swap_b32 v16, v14
	v_permlane16_swap_b32 v17, v15
	s_nop 0
	v_pk_add_f32 v[120:121], v[14:15], v[16:17]
	v_lshlrev_b64 v[14:15], 7, v[60:61]
	v_lshl_add_u64 v[4:5], v[4:5], 0, v[14:15]
	v_mov_b32_e32 v14, v244
	v_mov_b32_e32 v15, v245
	v_mov_b32_e32 v16, v246
	v_mov_b32_e32 v17, v247
	v_mov_b32_e32 v18, v248
	v_mov_b32_e32 v19, v249
	v_mov_b32_e32 v20, v250
	v_mov_b32_e32 v21, v251
	ds_bpermute_b32 v123, v157, v121
	ds_bpermute_b32 v122, v157, v120
	v_mov_b32_e32 v5, v14
	v_mov_b32_e32 v4, v18
	v_mov_b32_e32 v22, v20
	v_mov_b32_e32 v23, v16
	v_pk_add_f32 v[4:5], v[4:5], v[22:23]
	v_add_f32_e32 v14, v19, v21
	v_add_f32_e32 v16, v15, v17
	v_mov_b32_e32 v15, v4
	v_mov_b32_e32 v17, v5
	v_pk_add_f32 v[4:5], v[14:15], v[16:17]
	s_nop 0
	v_mov_b32_e32 v14, v4
	v_mov_b32_e32 v15, v5
	s_nop 1
	v_permlane16_swap_b32 v14, v4
	v_permlane16_swap_b32 v15, v5
	s_nop 0
	v_pk_add_f32 v[124:125], v[4:5], v[14:15]
	v_lshlrev_b64 v[4:5], 2, v[2:3]
	v_lshlrev_b64 v[2:3], 1, v[2:3]
	v_lshl_add_u64 v[74:75], v[0:1], 0, v[2:3]
	v_lshlrev_b64 v[0:1], 11, v[6:7]
	v_lshl_add_u64 v[0:1], s[44:45], 0, v[0:1]
	v_lshl_add_u64 v[76:77], v[0:1], 0, v[2:3]
	v_lshlrev_b64 v[0:1], 11, v[8:9]
	v_lshl_add_u64 v[0:1], s[44:45], 0, v[0:1]
	v_lshl_add_u64 v[78:79], v[0:1], 0, v[2:3]
	v_lshlrev_b64 v[0:1], 11, v[10:11]
	v_lshl_add_u64 v[0:1], s[44:45], 0, v[0:1]
	v_lshl_add_u64 v[80:81], v[0:1], 0, v[2:3]
	v_lshlrev_b64 v[0:1], 11, v[12:13]
	v_lshl_add_u64 v[0:1], s[44:45], 0, v[0:1]
	v_lshl_add_u64 v[138:139], v[0:1], 0, v[2:3]
	v_lshlrev_b64 v[0:1], 11, v[56:57]
	v_lshl_add_u64 v[0:1], s[44:45], 0, v[0:1]
	v_lshl_add_u64 v[56:57], v[0:1], 0, v[2:3]
	v_lshlrev_b64 v[0:1], 11, v[58:59]
	v_lshl_add_u64 v[0:1], s[44:45], 0, v[0:1]
	v_lshl_add_u64 v[58:59], v[0:1], 0, v[2:3]
	v_lshlrev_b64 v[0:1], 11, v[60:61]
	v_lshl_add_u64 v[0:1], s[44:45], 0, v[0:1]
	v_lshl_add_u64 v[62:63], s[72:73], 0, v[4:5]
	v_lshl_add_u64 v[72:73], s[0:1], 0, v[4:5]
	v_lshl_add_u64 v[140:141], v[0:1], 0, v[2:3]
	global_load_dwordx4 v[36:39], v[62:63], off offset:16
	global_load_dwordx4 v[44:47], v[62:63], off
	global_load_dwordx4 v[32:35], v[72:73], off offset:16
	global_load_dwordx4 v[40:43], v[72:73], off
	global_load_dwordx4 v[28:31], v[74:75], off
	global_load_dwordx4 v[24:27], v[76:77], off
	global_load_dwordx4 v[20:23], v[78:79], off
	global_load_dwordx4 v[16:19], v[80:81], off
	global_load_dwordx4 v[12:15], v[138:139], off
	global_load_dwordx4 v[8:11], v[56:57], off
	global_load_dwordx4 v[4:7], v[58:59], off
	global_load_dwordx4 v[0:3], v[140:141], off
	global_load_dwordx4 v[100:103], v[62:63], off offset:528
	global_load_dwordx4 v[108:111], v[62:63], off offset:512
	global_load_dwordx4 v[96:99], v[72:73], off offset:528
	global_load_dwordx4 v[104:107], v[72:73], off offset:512
	global_load_dwordx4 v[92:95], v[74:75], off offset:256
	global_load_dwordx4 v[88:91], v[76:77], off offset:256
	global_load_dwordx4 v[84:87], v[78:79], off offset:256
	s_nop 0
	global_load_dwordx4 v[80:83], v[80:81], off offset:256
	s_nop 0
	global_load_dwordx4 v[76:79], v[138:139], off offset:256
	global_load_dwordx4 v[72:75], v[56:57], off offset:256
	global_load_dwordx4 v[60:63], v[58:59], off offset:256
	s_nop 0
	global_load_dwordx4 v[56:59], v[140:141], off offset:256
	ds_bpermute_b32 v127, v157, v125
	global_load_lds_dwordx4 v130, s[74:75]
	s_add_i32 m0, s67, 0x12000
	s_add_u32 s6, s74, 0xb0000
	global_load_lds_dwordx4 v134, s[74:75]
	s_addc_u32 s7, s75, 0
	s_add_i32 m0, s67, 0x14000
	ds_bpermute_b32 v126, v157, v124
	global_load_lds_dwordx4 v130, s[6:7]
	s_add_i32 m0, s67, 0x16000
	s_add_u32 s40, s42, s13
	s_addc_u32 s41, s43, s8
	s_add_i32 s68, s67, 0x2000
	global_load_lds_dwordx4 v134, s[6:7]
	s_mov_b32 m0, s67
	s_add_u32 s6, s40, 0xb0000
	global_load_lds_dwordx4 v128, s[40:41]
	s_mov_b32 m0, s68
	s_addc_u32 s7, s41, 0
	s_add_i32 s69, s67, 0x4000
	global_load_lds_dwordx4 v132, s[40:41]
	s_mov_b32 m0, s69
	s_add_i32 s88, s67, 0x6000
	global_load_lds_dwordx4 v128, s[6:7]
	s_mov_b32 m0, s88
	s_cmp_eq_u32 s12, 1
	global_load_lds_dwordx4 v132, s[6:7]
	v_lshl_add_u64 v[138:139], s[74:75], 0, v[130:131]
	v_lshl_add_u64 v[140:141], s[74:75], 0, v[134:135]
	v_lshl_add_u64 v[142:143], s[40:41], 0, v[128:129]
	v_lshl_add_u64 v[144:145], s[40:41], 0, v[132:133]
	s_cselect_b64 s[6:7], -1, 0
	s_cmp_lg_u32 s12, 1
	s_cbranch_scc1 .LBB0_2539
	s_barrier

.LBB0_2572:
	s_or_b64 exec, exec, s[46:47]
	s_and_b64 vcc, exec, s[10:11]
	s_mov_b64 s[10:11], -1
	s_cbranch_vccnz .LBB0_2541
	v_mov_b32_e32 v0, v153
	v_mov_b32_e32 v1, v151
	s_lshl_b32 s10, s78, 8
	s_add_i32 s10, s10, s15
	v_add_u32_e32 v0, s10, v0
	s_waitcnt lgkmcnt(0)
	v_lshlrev_b32_e32 v2, 3, v1
	v_ashrrev_i32_e32 v3, 31, v2
	v_ashrrev_i32_e32 v1, 31, v0
	v_lshl_add_u64 v[6:7], v[2:3], 2, s[62:63]
	v_lshlrev_b64 v[4:5], 7, v[0:1]
	v_lshl_add_u64 v[4:5], v[6:7], 0, v[4:5]
	v_mov_b32_e32 v100, v0
	v_ashrrev_i32_e32 v101, 31, v100
	v_lshlrev_b64 v[100:101], 7, v[100:101]
	v_lshl_add_u64 v[100:101], v[6:7], 0, v[100:101]
	global_load_dwordx4 v[104:107], v[100:101], off offset:16
	global_load_dwordx4 v[108:111], v[100:101], off
	v_add_u32_e32 v100, 0x10, v0
	v_ashrrev_i32_e32 v101, 31, v100
	v_lshlrev_b64 v[100:101], 7, v[100:101]
	v_lshl_add_u64 v[100:101], v[6:7], 0, v[100:101]
	global_load_dwordx4 v[124:127], v[100:101], off offset:16
	global_load_dwordx4 v[180:183], v[100:101], off
	v_add_u32_e32 v100, 0x20, v0
	v_ashrrev_i32_e32 v101, 31, v100
	v_lshlrev_b64 v[100:101], 7, v[100:101]
	v_lshl_add_u64 v[100:101], v[6:7], 0, v[100:101]
	global_load_dwordx4 v[184:187], v[100:101], off offset:16
	global_load_dwordx4 v[188:191], v[100:101], off
	v_add_u32_e32 v100, 0x30, v0
	v_ashrrev_i32_e32 v101, 31, v100
	v_lshlrev_b64 v[100:101], 7, v[100:101]
	v_lshl_add_u64 v[100:101], v[6:7], 0, v[100:101]
	global_load_dwordx4 v[192:195], v[100:101], off offset:16
	global_load_dwordx4 v[196:199], v[100:101], off
	v_add_u32_e32 v100, 0x80, v0
	v_ashrrev_i32_e32 v101, 31, v100
	v_lshlrev_b64 v[100:101], 7, v[100:101]
	v_lshl_add_u64 v[100:101], v[6:7], 0, v[100:101]
	global_load_dwordx4 v[200:203], v[100:101], off offset:16
	global_load_dwordx4 v[204:207], v[100:101], off
	v_add_u32_e32 v100, 0x90, v0
	v_ashrrev_i32_e32 v101, 31, v100
	v_lshlrev_b64 v[100:101], 7, v[100:101]
	v_lshl_add_u64 v[100:101], v[6:7], 0, v[100:101]
	global_load_dwordx4 v[208:211], v[100:101], off offset:16
	global_load_dwordx4 v[212:215], v[100:101], off
	v_add_u32_e32 v100, 0xa0, v0
	v_ashrrev_i32_e32 v101, 31, v100
	v_lshlrev_b64 v[100:101], 7, v[100:101]
	v_lshl_add_u64 v[100:101], v[6:7], 0, v[100:101]
	global_load_dwordx4 v[216:219], v[100:101], off offset:16
	global_load_dwordx4 v[220:223], v[100:101], off
	v_add_u32_e32 v100, 0xb0, v0
	v_ashrrev_i32_e32 v101, 31, v100
	v_lshlrev_b64 v[100:101], 7, v[100:101]
	v_lshl_add_u64 v[100:101], v[6:7], 0, v[100:101]
	global_load_dwordx4 v[224:227], v[100:101], off offset:16
	global_load_dwordx4 v[228:231], v[100:101], off
	s_waitcnt vmcnt(0)
	v_mov_b32_e32 v8, v104
	v_mov_b32_e32 v9, v105
	v_mov_b32_e32 v10, v106
	v_mov_b32_e32 v11, v107
	v_mov_b32_e32 v12, v108
	v_mov_b32_e32 v13, v109
	v_mov_b32_e32 v14, v110
	v_mov_b32_e32 v15, v111
	v_add_u32_e32 v56, 0x90, v0
	v_ashrrev_i32_e32 v57, 31, v56
	v_add_u32_e32 v58, 0xa0, v0
	v_ashrrev_i32_e32 v59, 31, v58
	v_add_u32_e32 v60, 0xb0, v0
	v_ashrrev_i32_e32 v61, 31, v60
	s_lshl_b32 s10, s73, 8
	s_or_b32 s10, s10, s66
	v_add_u32_e32 v2, s10, v2
	v_ashrrev_i32_e32 v3, 31, v2
	v_readlane_b32 s10, v255, 50
	v_readlane_b32 s11, v255, 51
	s_andn2_b64 vcc, exec, s[6:7]
	v_mov_b32_e32 v5, v8
	v_mov_b32_e32 v4, v12
	v_mov_b32_e32 v16, v14
	v_mov_b32_e32 v17, v10
	v_pk_add_f32 v[4:5], v[4:5], v[16:17]
	v_add_f32_e32 v8, v13, v15
	v_add_f32_e32 v10, v9, v11
	v_mov_b32_e32 v9, v4
	v_mov_b32_e32 v11, v5
	v_pk_add_f32 v[4:5], v[8:9], v[10:11]
	s_nop 0
	v_mov_b32_e32 v8, v4
	v_mov_b32_e32 v9, v5
	s_nop 1
	v_permlane16_swap_b32 v8, v4
	v_permlane16_swap_b32 v9, v5
	s_nop 0
	v_pk_add_f32 v[48:49], v[4:5], v[8:9]
	v_add_u32_e32 v4, 16, v0
	v_ashrrev_i32_e32 v5, 31, v4
	v_lshlrev_b64 v[8:9], 7, v[4:5]
	v_lshl_add_u64 v[12:13], v[6:7], 0, v[8:9]
	v_mov_b32_e32 v8, v124
	v_mov_b32_e32 v9, v125
	v_mov_b32_e32 v10, v126
	v_mov_b32_e32 v11, v127
	s_nop 0
	v_mov_b32_e32 v12, v180
	v_mov_b32_e32 v13, v181
	v_mov_b32_e32 v14, v182
	v_mov_b32_e32 v15, v183
	ds_bpermute_b32 v51, v157, v49
	ds_bpermute_b32 v50, v157, v48
	v_mov_b32_e32 v17, v8
	v_mov_b32_e32 v16, v12
	v_mov_b32_e32 v18, v14
	v_mov_b32_e32 v19, v10
	v_pk_add_f32 v[16:17], v[16:17], v[18:19]
	v_add_f32_e32 v8, v13, v15
	v_add_f32_e32 v10, v9, v11
	v_mov_b32_e32 v9, v16
	v_mov_b32_e32 v11, v17
	v_pk_add_f32 v[8:9], v[8:9], v[10:11]
	s_nop 0
	v_mov_b32_e32 v10, v8
	v_mov_b32_e32 v11, v9
	s_nop 1
	v_permlane16_swap_b32 v10, v8
	v_permlane16_swap_b32 v11, v9
	s_nop 0
	v_pk_add_f32 v[52:53], v[8:9], v[10:11]
	v_add_u32_e32 v8, 32, v0
	v_ashrrev_i32_e32 v9, 31, v8
	v_lshlrev_b64 v[10:11], 7, v[8:9]
	v_lshl_add_u64 v[14:15], v[6:7], 0, v[10:11]
	v_mov_b32_e32 v10, v184
	v_mov_b32_e32 v11, v185
	v_mov_b32_e32 v12, v186
	v_mov_b32_e32 v13, v187
	s_nop 0
	v_mov_b32_e32 v14, v188
	v_mov_b32_e32 v15, v189
	v_mov_b32_e32 v16, v190
	v_mov_b32_e32 v17, v191
	ds_bpermute_b32 v55, v157, v53
	ds_bpermute_b32 v54, v157, v52
	v_mov_b32_e32 v19, v10
	v_mov_b32_e32 v18, v14
	v_mov_b32_e32 v20, v16
	v_mov_b32_e32 v21, v12
	v_pk_add_f32 v[18:19], v[18:19], v[20:21]
	v_add_f32_e32 v10, v15, v17
	v_add_f32_e32 v12, v11, v13
	v_mov_b32_e32 v11, v18
	v_mov_b32_e32 v13, v19
	v_pk_add_f32 v[10:11], v[10:11], v[12:13]
	s_nop 0
	v_mov_b32_e32 v12, v10
	v_mov_b32_e32 v13, v11
	s_nop 1
	v_permlane16_swap_b32 v12, v10
	v_permlane16_swap_b32 v13, v11
	s_nop 0
	v_pk_add_f32 v[64:65], v[10:11], v[12:13]
	v_add_u32_e32 v10, 48, v0
	v_ashrrev_i32_e32 v11, 31, v10
	v_lshlrev_b64 v[12:13], 7, v[10:11]
	v_lshl_add_u64 v[16:17], v[6:7], 0, v[12:13]
	v_mov_b32_e32 v12, v192
	v_mov_b32_e32 v13, v193
	v_mov_b32_e32 v14, v194
	v_mov_b32_e32 v15, v195
	s_nop 0
	v_mov_b32_e32 v16, v196
	v_mov_b32_e32 v17, v197
	v_mov_b32_e32 v18, v198
	v_mov_b32_e32 v19, v199
	ds_bpermute_b32 v67, v157, v65
	ds_bpermute_b32 v66, v157, v64
	v_mov_b32_e32 v21, v12
	v_mov_b32_e32 v20, v16
	v_mov_b32_e32 v22, v18
	v_mov_b32_e32 v23, v14
	v_pk_add_f32 v[20:21], v[20:21], v[22:23]
	v_add_f32_e32 v12, v17, v19
	v_add_f32_e32 v14, v13, v15
	v_mov_b32_e32 v13, v20
	v_mov_b32_e32 v15, v21
	v_pk_add_f32 v[12:13], v[12:13], v[14:15]
	s_nop 0
	v_mov_b32_e32 v14, v12
	v_mov_b32_e32 v15, v13
	s_nop 1
	v_permlane16_swap_b32 v14, v12
	v_permlane16_swap_b32 v15, v13
	s_nop 0
	v_pk_add_f32 v[68:69], v[12:13], v[14:15]
	v_add_u32_e32 v12, 0x80, v0
	v_ashrrev_i32_e32 v13, 31, v12
	v_lshlrev_b64 v[14:15], 7, v[12:13]
	v_lshl_add_u64 v[18:19], v[6:7], 0, v[14:15]
	v_mov_b32_e32 v14, v200
	v_mov_b32_e32 v15, v201
	v_mov_b32_e32 v16, v202
	v_mov_b32_e32 v17, v203
	s_nop 0
	v_mov_b32_e32 v18, v204
	v_mov_b32_e32 v19, v205
	v_mov_b32_e32 v20, v206
	v_mov_b32_e32 v21, v207
	v_lshlrev_b64 v[0:1], 11, v[0:1]
	v_lshl_add_u64 v[0:1], s[44:45], 0, v[0:1]
	ds_bpermute_b32 v71, v157, v69
	ds_bpermute_b32 v70, v157, v68
	v_mov_b32_e32 v23, v14
	v_mov_b32_e32 v22, v18
	v_mov_b32_e32 v24, v20
	v_mov_b32_e32 v25, v16
	v_pk_add_f32 v[22:23], v[22:23], v[24:25]
	v_add_f32_e32 v14, v19, v21
	v_add_f32_e32 v16, v15, v17
	v_mov_b32_e32 v15, v22
	v_mov_b32_e32 v17, v23
	v_pk_add_f32 v[14:15], v[14:15], v[16:17]
	s_nop 0
	v_mov_b32_e32 v16, v14
	v_mov_b32_e32 v17, v15
	s_nop 1
	v_permlane16_swap_b32 v16, v14
	v_permlane16_swap_b32 v17, v15
	s_nop 0
	v_pk_add_f32 v[112:113], v[14:15], v[16:17]
	v_lshlrev_b64 v[14:15], 7, v[56:57]
	v_lshl_add_u64 v[18:19], v[6:7], 0, v[14:15]
	v_mov_b32_e32 v14, v208
	v_mov_b32_e32 v15, v209
	v_mov_b32_e32 v16, v210
	v_mov_b32_e32 v17, v211
	s_nop 0
	v_mov_b32_e32 v18, v212
	v_mov_b32_e32 v19, v213
	v_mov_b32_e32 v20, v214
	v_mov_b32_e32 v21, v215
	ds_bpermute_b32 v115, v157, v113
	ds_bpermute_b32 v114, v157, v112
	v_mov_b32_e32 v23, v14
	v_mov_b32_e32 v22, v18
	v_mov_b32_e32 v24, v20
	v_mov_b32_e32 v25, v16
	v_pk_add_f32 v[22:23], v[22:23], v[24:25]
	v_add_f32_e32 v14, v19, v21
	v_add_f32_e32 v16, v15, v17
	v_mov_b32_e32 v15, v22
	v_mov_b32_e32 v17, v23
	v_pk_add_f32 v[14:15], v[14:15], v[16:17]
	s_nop 0
	v_mov_b32_e32 v16, v14
	v_mov_b32_e32 v17, v15
	s_nop 1
	v_permlane16_swap_b32 v16, v14
	v_permlane16_swap_b32 v17, v15
	s_nop 0
	v_pk_add_f32 v[116:117], v[14:15], v[16:17]
	v_lshlrev_b64 v[14:15], 7, v[58:59]
	v_lshl_add_u64 v[18:19], v[6:7], 0, v[14:15]
	v_mov_b32_e32 v14, v216
	v_mov_b32_e32 v15, v217
	v_mov_b32_e32 v16, v218
	v_mov_b32_e32 v17, v219
	s_nop 0
	v_mov_b32_e32 v18, v220
	v_mov_b32_e32 v19, v221
	v_mov_b32_e32 v20, v222
	v_mov_b32_e32 v21, v223
	ds_bpermute_b32 v119, v157, v117
	ds_bpermute_b32 v118, v157, v116
	v_mov_b32_e32 v23, v14
	v_mov_b32_e32 v22, v18
	v_mov_b32_e32 v24, v20
	v_mov_b32_e32 v25, v16
	v_pk_add_f32 v[22:23], v[22:23], v[24:25]
	v_add_f32_e32 v14, v19, v21
	v_add_f32_e32 v16, v15, v17
	v_mov_b32_e32 v15, v22
	v_mov_b32_e32 v17, v23
	v_pk_add_f32 v[14:15], v[14:15], v[16:17]
	s_nop 0
	v_mov_b32_e32 v16, v14
	v_mov_b32_e32 v17, v15
	s_nop 1
	v_permlane16_swap_b32 v16, v14
	v_permlane16_swap_b32 v17, v15
	s_nop 0
	v_pk_add_f32 v[120:121], v[14:15], v[16:17]
	v_lshlrev_b64 v[14:15], 7, v[60:61]
	v_lshl_add_u64 v[6:7], v[6:7], 0, v[14:15]
	v_mov_b32_e32 v14, v224
	v_mov_b32_e32 v15, v225
	v_mov_b32_e32 v16, v226
	v_mov_b32_e32 v17, v227
	v_mov_b32_e32 v18, v228
	v_mov_b32_e32 v19, v229
	v_mov_b32_e32 v20, v230
	v_mov_b32_e32 v21, v231
	ds_bpermute_b32 v123, v157, v121
	ds_bpermute_b32 v122, v157, v120
	v_mov_b32_e32 v7, v14
	v_mov_b32_e32 v6, v18
	v_mov_b32_e32 v22, v20
	v_mov_b32_e32 v23, v16
	v_pk_add_f32 v[6:7], v[6:7], v[22:23]
	v_add_f32_e32 v14, v19, v21
	v_add_f32_e32 v16, v15, v17
	v_mov_b32_e32 v15, v6
	v_mov_b32_e32 v17, v7
	v_pk_add_f32 v[6:7], v[14:15], v[16:17]
	s_nop 0
	v_mov_b32_e32 v14, v6
	v_mov_b32_e32 v15, v7
	s_nop 1
	v_permlane16_swap_b32 v14, v6
	v_permlane16_swap_b32 v15, v7
	s_nop 0
	v_pk_add_f32 v[124:125], v[6:7], v[14:15]
	v_lshlrev_b64 v[6:7], 2, v[2:3]
	v_lshlrev_b64 v[2:3], 1, v[2:3]
	v_lshl_add_u64 v[74:75], v[0:1], 0, v[2:3]
	v_lshlrev_b64 v[0:1], 11, v[4:5]
	v_lshl_add_u64 v[0:1], s[44:45], 0, v[0:1]
	v_lshl_add_u64 v[76:77], v[0:1], 0, v[2:3]
	v_lshlrev_b64 v[0:1], 11, v[8:9]
	v_lshl_add_u64 v[0:1], s[44:45], 0, v[0:1]
	v_lshl_add_u64 v[78:79], v[0:1], 0, v[2:3]
	v_lshlrev_b64 v[0:1], 11, v[10:11]
	v_lshl_add_u64 v[0:1], s[44:45], 0, v[0:1]
	v_lshl_add_u64 v[80:81], v[0:1], 0, v[2:3]
	v_lshlrev_b64 v[0:1], 11, v[12:13]
	v_lshl_add_u64 v[0:1], s[44:45], 0, v[0:1]
	v_lshl_add_u64 v[146:147], v[0:1], 0, v[2:3]
	v_lshlrev_b64 v[0:1], 11, v[56:57]
	v_lshl_add_u64 v[0:1], s[44:45], 0, v[0:1]
	v_lshl_add_u64 v[56:57], v[0:1], 0, v[2:3]
	v_lshlrev_b64 v[0:1], 11, v[58:59]
	v_lshl_add_u64 v[0:1], s[44:45], 0, v[0:1]
	v_lshl_add_u64 v[58:59], v[0:1], 0, v[2:3]
	v_lshlrev_b64 v[0:1], 11, v[60:61]
	v_lshl_add_u64 v[0:1], s[44:45], 0, v[0:1]
	v_lshl_add_u64 v[62:63], s[10:11], 0, v[6:7]
	v_lshl_add_u64 v[72:73], s[0:1], 0, v[6:7]
	v_lshl_add_u64 v[148:149], v[0:1], 0, v[2:3]
	global_load_dwordx4 v[36:39], v[62:63], off offset:16
	global_load_dwordx4 v[44:47], v[62:63], off
	global_load_dwordx4 v[32:35], v[72:73], off offset:16
	global_load_dwordx4 v[40:43], v[72:73], off
	global_load_dwordx4 v[28:31], v[74:75], off
	global_load_dwordx4 v[24:27], v[76:77], off
	global_load_dwordx4 v[20:23], v[78:79], off
	global_load_dwordx4 v[16:19], v[80:81], off
	global_load_dwordx4 v[12:15], v[146:147], off
	global_load_dwordx4 v[8:11], v[56:57], off
	global_load_dwordx4 v[4:7], v[58:59], off
	global_load_dwordx4 v[0:3], v[148:149], off
	global_load_dwordx4 v[104:107], v[62:63], off offset:528
	global_load_dwordx4 v[108:111], v[62:63], off offset:512
	global_load_dwordx4 v[96:99], v[72:73], off offset:528
	global_load_dwordx4 v[100:103], v[72:73], off offset:512
	global_load_dwordx4 v[92:95], v[74:75], off offset:256
	global_load_dwordx4 v[88:91], v[76:77], off offset:256
	global_load_dwordx4 v[84:87], v[78:79], off offset:256
	s_nop 0
	global_load_dwordx4 v[80:83], v[80:81], off offset:256
	s_nop 0
	global_load_dwordx4 v[76:79], v[146:147], off offset:256
	global_load_dwordx4 v[72:75], v[56:57], off offset:256
	global_load_dwordx4 v[60:63], v[58:59], off offset:256
	s_nop 0
	global_load_dwordx4 v[56:59], v[148:149], off offset:256
	ds_bpermute_b32 v127, v157, v125
	ds_bpermute_b32 v126, v157, v124
	s_cbranch_vccnz .LBB0_2540
	s_barrier
	s_branch .LBB0_2540
